# speedup vs baseline: 1.0050x; 1.0044x over previous
.Lbk64_350:
	s_waitcnt vmcnt(4)
	ds_read_b128 v[192:195], v227
	ds_read_b128 v[196:199], v228
	ds_read_b128 v[200:203], v227 offset:2048
	ds_read_b128 v[204:207], v228 offset:2048
	ds_read_b128 v[208:211], v227 offset:4096
	ds_read_b128 v[212:215], v228 offset:4096
	ds_read_b128 v[216:219], v227 offset:6144
	ds_read_b128 v[220:223], v228 offset:6144
	s_waitcnt vmcnt(0)
	s_barrier
	s_add_u32 s18, s18, 0x80
	s_addc_u32 s19, s19, 0
	s_add_u32 s16, s16, 0x80
	s_addc_u32 s17, s17, 0
	s_waitcnt lgkmcnt(0)
	ds_read_b128 v[154:157], v229 offset:0
	ds_read_b128 v[158:161], v230 offset:0
	ds_read_b128 v[162:165], v229 offset:2048
	ds_read_b128 v[166:169], v230 offset:2048
	s_waitcnt lgkmcnt(2)
	v_mfma_f32_16x16x32_bf16 v[126:129], v[192:195], v[154:157], v[126:129]
	v_mfma_f32_16x16x32_bf16 v[114:117], v[200:203], v[154:157], v[114:117]
	v_mfma_f32_16x16x32_bf16 v[86:89], v[208:211], v[154:157], v[86:89]
	v_mfma_f32_16x16x32_bf16 v[54:57], v[216:219], v[154:157], v[54:57]
	v_readfirstlane_b32 s32, v145
	s_lshl_b32 m0, s32, 3
	v_mov_b32_e32 v226, v224
	global_load_lds_dwordx4 v226, s[18:19]
	v_mfma_f32_16x16x32_bf16 v[126:129], v[196:199], v[158:161], v[126:129]
	v_mfma_f32_16x16x32_bf16 v[114:117], v[204:207], v[158:161], v[114:117]
	v_mfma_f32_16x16x32_bf16 v[86:89], v[212:215], v[158:161], v[86:89]
	v_mfma_f32_16x16x32_bf16 v[54:57], v[220:223], v[158:161], v[54:57]
	s_add_u32 m0, m0, 0x400
	v_add_u32_e32 v226, 0xac00, v224
	global_load_lds_dwordx4 v226, s[18:19]
	ds_read_b128 v[154:157], v229 offset:4096
	ds_read_b128 v[158:161], v230 offset:4096
	s_waitcnt lgkmcnt(2)
	v_mfma_f32_16x16x32_bf16 v[122:125], v[192:195], v[162:165], v[122:125]
	v_mfma_f32_16x16x32_bf16 v[102:105], v[200:203], v[162:165], v[102:105]
	v_mfma_f32_16x16x32_bf16 v[70:73], v[208:211], v[162:165], v[70:73]
	v_mfma_f32_16x16x32_bf16 v[38:41], v[216:219], v[162:165], v[38:41]
	s_add_u32 m0, m0, 0x400
	v_add_u32_e32 v226, 0x15800, v224
	global_load_lds_dwordx4 v226, s[18:19]
	v_mfma_f32_16x16x32_bf16 v[122:125], v[196:199], v[166:169], v[122:125]
	v_mfma_f32_16x16x32_bf16 v[102:105], v[204:207], v[166:169], v[102:105]
	v_mfma_f32_16x16x32_bf16 v[70:73], v[212:215], v[166:169], v[70:73]
	v_mfma_f32_16x16x32_bf16 v[38:41], v[220:223], v[166:169], v[38:41]
	s_add_u32 m0, m0, 0x400
	v_add_u32_e32 v226, 0x20400, v224
	global_load_lds_dwordx4 v226, s[18:19]
	ds_read_b128 v[162:165], v229 offset:6144
	ds_read_b128 v[166:169], v230 offset:6144
	s_waitcnt lgkmcnt(2)
	v_mfma_f32_16x16x32_bf16 v[118:121], v[192:195], v[154:157], v[118:121]
	v_mfma_f32_16x16x32_bf16 v[90:93], v[200:203], v[154:157], v[90:93]
	v_mfma_f32_16x16x32_bf16 v[58:61], v[208:211], v[154:157], v[58:61]
	v_mfma_f32_16x16x32_bf16 v[26:29], v[216:219], v[154:157], v[26:29]
	s_add_u32 m0, m0, 0x400
	v_add_u32_e32 v226, 0x2b000, v224
	global_load_lds_dwordx4 v226, s[18:19]
	v_mfma_f32_16x16x32_bf16 v[118:121], v[196:199], v[158:161], v[118:121]
	v_mfma_f32_16x16x32_bf16 v[90:93], v[204:207], v[158:161], v[90:93]
	v_mfma_f32_16x16x32_bf16 v[58:61], v[212:215], v[158:161], v[58:61]
	v_mfma_f32_16x16x32_bf16 v[26:29], v[220:223], v[158:161], v[26:29]
	s_add_u32 m0, m0, 0x400
	v_add_u32_e32 v226, 0x35c00, v224
	global_load_lds_dwordx4 v226, s[18:19]
	ds_read_b128 v[154:157], v229 offset:8192
	ds_read_b128 v[158:161], v230 offset:8192
	s_waitcnt lgkmcnt(2)
	v_mfma_f32_16x16x32_bf16 v[110:113], v[192:195], v[162:165], v[110:113]
	v_mfma_f32_16x16x32_bf16 v[78:81], v[200:203], v[162:165], v[78:81]
	v_mfma_f32_16x16x32_bf16 v[46:49], v[208:211], v[162:165], v[46:49]
	v_mfma_f32_16x16x32_bf16 v[18:21], v[216:219], v[162:165], v[18:21]
	s_add_u32 m0, m0, 0x400
	v_add_u32_e32 v226, 0x40800, v224
	global_load_lds_dwordx4 v226, s[18:19]
	v_mfma_f32_16x16x32_bf16 v[110:113], v[196:199], v[166:169], v[110:113]
	v_mfma_f32_16x16x32_bf16 v[78:81], v[204:207], v[166:169], v[78:81]
	v_mfma_f32_16x16x32_bf16 v[46:49], v[212:215], v[166:169], v[46:49]
	v_mfma_f32_16x16x32_bf16 v[18:21], v[220:223], v[166:169], v[18:21]
	s_add_u32 m0, m0, 0x400
	v_add_u32_e32 v226, 0x4b400, v224
	global_load_lds_dwordx4 v226, s[18:19]
	ds_read_b128 v[162:165], v229 offset:10240
	ds_read_b128 v[166:169], v230 offset:10240
	s_waitcnt lgkmcnt(2)
	v_mfma_f32_16x16x32_bf16 v[106:109], v[192:195], v[154:157], v[106:109]
	v_mfma_f32_16x16x32_bf16 v[74:77], v[200:203], v[154:157], v[74:77]
	v_mfma_f32_16x16x32_bf16 v[42:45], v[208:211], v[154:157], v[42:45]
	v_mfma_f32_16x16x32_bf16 v[14:17], v[216:219], v[154:157], v[14:17]
	s_add_u32 m0, s25, 44
	s_and_b32 m0, m0, 1
	s_lshl_b32 m0, m0, 14
	s_add_u32 m0, m0, 0x8000
	v_readfirstlane_b32 s32, v145
	s_lshl_b32 s32, s32, 2
	s_add_u32 m0, m0, s32
	v_mov_b32_e32 v226, v225
	global_load_lds_dwordx4 v226, s[16:17]
	v_mfma_f32_16x16x32_bf16 v[106:109], v[196:199], v[158:161], v[106:109]
	v_mfma_f32_16x16x32_bf16 v[74:77], v[204:207], v[158:161], v[74:77]
	v_mfma_f32_16x16x32_bf16 v[42:45], v[212:215], v[158:161], v[42:45]
	v_mfma_f32_16x16x32_bf16 v[14:17], v[220:223], v[158:161], v[14:17]
	s_add_u32 m0, m0, 0x400
	v_add_u32_e32 v226, 0xac00, v225
	global_load_lds_dwordx4 v226, s[16:17]
	ds_read_b128 v[154:157], v229 offset:12288
	ds_read_b128 v[158:161], v230 offset:12288
	s_waitcnt lgkmcnt(2)
	v_mfma_f32_16x16x32_bf16 v[98:101], v[192:195], v[162:165], v[98:101]
	v_mfma_f32_16x16x32_bf16 v[66:69], v[200:203], v[162:165], v[66:69]
	v_mfma_f32_16x16x32_bf16 v[34:37], v[208:211], v[162:165], v[34:37]
	v_mfma_f32_16x16x32_bf16 v[10:13], v[216:219], v[162:165], v[10:13]
	s_add_u32 m0, m0, 0x400
	v_add_u32_e32 v226, 0x15800, v225
	global_load_lds_dwordx4 v226, s[16:17]
	v_mfma_f32_16x16x32_bf16 v[98:101], v[196:199], v[166:169], v[98:101]
	v_mfma_f32_16x16x32_bf16 v[66:69], v[204:207], v[166:169], v[66:69]
	v_mfma_f32_16x16x32_bf16 v[34:37], v[212:215], v[166:169], v[34:37]
	v_mfma_f32_16x16x32_bf16 v[10:13], v[220:223], v[166:169], v[10:13]
	s_add_u32 m0, m0, 0x400
	v_add_u32_e32 v226, 0x20400, v225
	global_load_lds_dwordx4 v226, s[16:17]
	ds_read_b128 v[162:165], v229 offset:14336
	ds_read_b128 v[166:169], v230 offset:14336
	s_waitcnt lgkmcnt(2)
	v_mfma_f32_16x16x32_bf16 v[94:97], v[192:195], v[154:157], v[94:97]
	v_mfma_f32_16x16x32_bf16 v[62:65], v[200:203], v[154:157], v[62:65]
	v_mfma_f32_16x16x32_bf16 v[30:33], v[208:211], v[154:157], v[30:33]
	v_mfma_f32_16x16x32_bf16 v[6:9], v[216:219], v[154:157], v[6:9]
	v_mfma_f32_16x16x32_bf16 v[94:97], v[196:199], v[158:161], v[94:97]
	v_mfma_f32_16x16x32_bf16 v[62:65], v[204:207], v[158:161], v[62:65]
	v_mfma_f32_16x16x32_bf16 v[30:33], v[212:215], v[158:161], v[30:33]
	v_mfma_f32_16x16x32_bf16 v[6:9], v[220:223], v[158:161], v[6:9]
	s_waitcnt lgkmcnt(0)
	v_mfma_f32_16x16x32_bf16 v[82:85], v[192:195], v[162:165], v[82:85]
	v_mfma_f32_16x16x32_bf16 v[50:53], v[200:203], v[162:165], v[50:53]
	v_mfma_f32_16x16x32_bf16 v[22:25], v[208:211], v[162:165], v[22:25]
	v_mfma_f32_16x16x32_bf16 v[2:5], v[216:219], v[162:165], v[2:5]
	v_mfma_f32_16x16x32_bf16 v[82:85], v[196:199], v[166:169], v[82:85]
	v_mfma_f32_16x16x32_bf16 v[50:53], v[204:207], v[166:169], v[50:53]
	v_mfma_f32_16x16x32_bf16 v[22:25], v[212:215], v[166:169], v[22:25]
	v_mfma_f32_16x16x32_bf16 v[2:5], v[220:223], v[166:169], v[2:5]
	v_xor_b32_e32 v229, 0x4000, v229
	v_xor_b32_e32 v230, 0x4000, v230
	s_add_i32 s25, s25, 1
	s_cmp_lg_u32 s25, 42
	s_cbranch_scc1 .Lbk64_350
	s_waitcnt vmcnt(4)
	ds_read_b128 v[192:195], v227
	ds_read_b128 v[196:199], v228
	ds_read_b128 v[200:203], v227 offset:2048
	ds_read_b128 v[204:207], v228 offset:2048
	ds_read_b128 v[208:211], v227 offset:4096
	ds_read_b128 v[212:215], v228 offset:4096
	ds_read_b128 v[216:219], v227 offset:6144
	ds_read_b128 v[220:223], v228 offset:6144
	s_waitcnt vmcnt(0)
	s_barrier
	s_waitcnt lgkmcnt(0)
	ds_read_b128 v[154:157], v229 offset:0
	ds_read_b128 v[158:161], v230 offset:0
	ds_read_b128 v[162:165], v229 offset:2048
	ds_read_b128 v[166:169], v230 offset:2048
	s_waitcnt lgkmcnt(2)
	v_mfma_f32_16x16x32_bf16 v[126:129], v[192:195], v[154:157], v[126:129]
	v_mfma_f32_16x16x32_bf16 v[114:117], v[200:203], v[154:157], v[114:117]
	v_mfma_f32_16x16x32_bf16 v[86:89], v[208:211], v[154:157], v[86:89]
	v_mfma_f32_16x16x32_bf16 v[54:57], v[216:219], v[154:157], v[54:57]
	v_mfma_f32_16x16x32_bf16 v[126:129], v[196:199], v[158:161], v[126:129]
	v_mfma_f32_16x16x32_bf16 v[114:117], v[204:207], v[158:161], v[114:117]
	v_mfma_f32_16x16x32_bf16 v[86:89], v[212:215], v[158:161], v[86:89]
	v_mfma_f32_16x16x32_bf16 v[54:57], v[220:223], v[158:161], v[54:57]
	ds_read_b128 v[154:157], v229 offset:4096
	ds_read_b128 v[158:161], v230 offset:4096
	s_waitcnt lgkmcnt(2)
	v_mfma_f32_16x16x32_bf16 v[122:125], v[192:195], v[162:165], v[122:125]
	v_mfma_f32_16x16x32_bf16 v[102:105], v[200:203], v[162:165], v[102:105]
	v_mfma_f32_16x16x32_bf16 v[70:73], v[208:211], v[162:165], v[70:73]
	v_mfma_f32_16x16x32_bf16 v[38:41], v[216:219], v[162:165], v[38:41]
	v_mfma_f32_16x16x32_bf16 v[122:125], v[196:199], v[166:169], v[122:125]
	v_mfma_f32_16x16x32_bf16 v[102:105], v[204:207], v[166:169], v[102:105]
	v_mfma_f32_16x16x32_bf16 v[70:73], v[212:215], v[166:169], v[70:73]
	v_mfma_f32_16x16x32_bf16 v[38:41], v[220:223], v[166:169], v[38:41]
	ds_read_b128 v[162:165], v229 offset:6144
	ds_read_b128 v[166:169], v230 offset:6144
	s_waitcnt lgkmcnt(2)
	v_mfma_f32_16x16x32_bf16 v[118:121], v[192:195], v[154:157], v[118:121]
	v_mfma_f32_16x16x32_bf16 v[90:93], v[200:203], v[154:157], v[90:93]
	v_mfma_f32_16x16x32_bf16 v[58:61], v[208:211], v[154:157], v[58:61]
	v_mfma_f32_16x16x32_bf16 v[26:29], v[216:219], v[154:157], v[26:29]
	v_mfma_f32_16x16x32_bf16 v[118:121], v[196:199], v[158:161], v[118:121]
	v_mfma_f32_16x16x32_bf16 v[90:93], v[204:207], v[158:161], v[90:93]
	v_mfma_f32_16x16x32_bf16 v[58:61], v[212:215], v[158:161], v[58:61]
	v_mfma_f32_16x16x32_bf16 v[26:29], v[220:223], v[158:161], v[26:29]
	ds_read_b128 v[154:157], v229 offset:8192
	ds_read_b128 v[158:161], v230 offset:8192
	s_waitcnt lgkmcnt(2)
	v_mfma_f32_16x16x32_bf16 v[110:113], v[192:195], v[162:165], v[110:113]
	v_mfma_f32_16x16x32_bf16 v[78:81], v[200:203], v[162:165], v[78:81]
	v_mfma_f32_16x16x32_bf16 v[46:49], v[208:211], v[162:165], v[46:49]
	v_mfma_f32_16x16x32_bf16 v[18:21], v[216:219], v[162:165], v[18:21]
	v_mfma_f32_16x16x32_bf16 v[110:113], v[196:199], v[166:169], v[110:113]
	v_mfma_f32_16x16x32_bf16 v[78:81], v[204:207], v[166:169], v[78:81]
	v_mfma_f32_16x16x32_bf16 v[46:49], v[212:215], v[166:169], v[46:49]
	v_mfma_f32_16x16x32_bf16 v[18:21], v[220:223], v[166:169], v[18:21]
	ds_read_b128 v[162:165], v229 offset:10240
	ds_read_b128 v[166:169], v230 offset:10240
	s_waitcnt lgkmcnt(2)
	v_mfma_f32_16x16x32_bf16 v[106:109], v[192:195], v[154:157], v[106:109]
	v_mfma_f32_16x16x32_bf16 v[74:77], v[200:203], v[154:157], v[74:77]
	v_mfma_f32_16x16x32_bf16 v[42:45], v[208:211], v[154:157], v[42:45]
	v_mfma_f32_16x16x32_bf16 v[14:17], v[216:219], v[154:157], v[14:17]
	v_mfma_f32_16x16x32_bf16 v[106:109], v[196:199], v[158:161], v[106:109]
	v_mfma_f32_16x16x32_bf16 v[74:77], v[204:207], v[158:161], v[74:77]
	v_mfma_f32_16x16x32_bf16 v[42:45], v[212:215], v[158:161], v[42:45]
	v_mfma_f32_16x16x32_bf16 v[14:17], v[220:223], v[158:161], v[14:17]
	ds_read_b128 v[154:157], v229 offset:12288
	ds_read_b128 v[158:161], v230 offset:12288
	s_waitcnt lgkmcnt(2)
	v_mfma_f32_16x16x32_bf16 v[98:101], v[192:195], v[162:165], v[98:101]
	v_mfma_f32_16x16x32_bf16 v[66:69], v[200:203], v[162:165], v[66:69]
	v_mfma_f32_16x16x32_bf16 v[34:37], v[208:211], v[162:165], v[34:37]
	v_mfma_f32_16x16x32_bf16 v[10:13], v[216:219], v[162:165], v[10:13]
	v_mfma_f32_16x16x32_bf16 v[98:101], v[196:199], v[166:169], v[98:101]
	v_mfma_f32_16x16x32_bf16 v[66:69], v[204:207], v[166:169], v[66:69]
	v_mfma_f32_16x16x32_bf16 v[34:37], v[212:215], v[166:169], v[34:37]
	v_mfma_f32_16x16x32_bf16 v[10:13], v[220:223], v[166:169], v[10:13]
	ds_read_b128 v[162:165], v229 offset:14336
	ds_read_b128 v[166:169], v230 offset:14336
	s_waitcnt lgkmcnt(2)
	v_mfma_f32_16x16x32_bf16 v[94:97], v[192:195], v[154:157], v[94:97]
	v_mfma_f32_16x16x32_bf16 v[62:65], v[200:203], v[154:157], v[62:65]
	v_mfma_f32_16x16x32_bf16 v[30:33], v[208:211], v[154:157], v[30:33]
	v_mfma_f32_16x16x32_bf16 v[6:9], v[216:219], v[154:157], v[6:9]
	v_mfma_f32_16x16x32_bf16 v[94:97], v[196:199], v[158:161], v[94:97]
	v_mfma_f32_16x16x32_bf16 v[62:65], v[204:207], v[158:161], v[62:65]
	v_mfma_f32_16x16x32_bf16 v[30:33], v[212:215], v[158:161], v[30:33]
	v_mfma_f32_16x16x32_bf16 v[6:9], v[220:223], v[158:161], v[6:9]
	s_waitcnt lgkmcnt(0)
	v_mfma_f32_16x16x32_bf16 v[82:85], v[192:195], v[162:165], v[82:85]
	v_mfma_f32_16x16x32_bf16 v[50:53], v[200:203], v[162:165], v[50:53]
	v_mfma_f32_16x16x32_bf16 v[22:25], v[208:211], v[162:165], v[22:25]
	v_mfma_f32_16x16x32_bf16 v[2:5], v[216:219], v[162:165], v[2:5]
	v_mfma_f32_16x16x32_bf16 v[82:85], v[196:199], v[166:169], v[82:85]
	v_mfma_f32_16x16x32_bf16 v[50:53], v[204:207], v[166:169], v[50:53]
	v_mfma_f32_16x16x32_bf16 v[22:25], v[212:215], v[166:169], v[22:25]
	v_mfma_f32_16x16x32_bf16 v[2:5], v[220:223], v[166:169], v[2:5]
	s_nop 7
	s_nop 7
	s_waitcnt vmcnt(6)
	v_add_u32_e32 v145, v149, v147
	s_waitcnt vmcnt(0)
	s_waitcnt lgkmcnt(0)
	s_lshl_b32 s16, s5, 7
	s_ashr_i32 s17, s16, 31
	s_lshl_b64 s[16:17], s[16:17], 1
	v_and_b32_e32 v1, 0xfffffc0, v1
	v_lshl_or_b32 v1, v143, 2, v1
	v_mul_lo_u32 v1, v1, s33
	v_lshl_or_b32 v1, v142, 2, v1
	s_lshl_b32 s18, s5, 1
	s_ashr_i32 s19, s18, 31
	s_lshl_b64 s[18:19], s[18:19], 2
	s_add_i32 s24, s24, 1
	v_mov_b64_e32 v[158:159], v[62:63]
	v_mov_b64_e32 v[160:161], v[64:65]
	v_mov_b64_e32 v[162:163], v[30:31]
	v_mov_b64_e32 v[164:165], v[32:33]
	v_mov_b64_e32 v[130:131], v[22:23]
	v_mov_b64_e32 v[132:133], v[24:25]
	s_waitcnt lgkmcnt(0)
	v_mov_b64_e32 v[224:225], v[38:39]
	v_mov_b64_e32 v[226:227], v[40:41]
	v_mov_b64_e32 v[38:39], v[34:35]
	v_mov_b64_e32 v[40:41], v[36:37]
	v_mov_b64_e32 v[34:35], v[2:3]
	v_mov_b64_e32 v[36:37], v[4:5]
	s_nop 2
	v_mov_b32_e32 v2, v170
	v_mov_b64_e32 v[208:209], v[114:115]
	v_mov_b64_e32 v[210:211], v[116:117]
	v_add_u32_e32 v2, s4, v2
	v_ashrrev_i32_e32 v3, 31, v2
	v_lshlrev_b64 v[2:3], 11, v[2:3]
	v_lshl_add_u64 v[2:3], s[8:9], 0, v[2:3]
	v_lshl_add_u64 v[2:3], v[2:3], 0, s[16:17]
	v_mov_b64_e32 v[212:213], v[54:55]
	v_mov_b64_e32 v[214:215], v[56:57]
	v_mov_b64_e32 v[216:217], v[122:123]
	v_mov_b64_e32 v[218:219], v[124:125]
	v_mov_b64_e32 v[220:221], v[102:103]
	v_mov_b64_e32 v[222:223], v[104:105]
	v_mov_b64_e32 v[228:229], v[118:119]
	v_mov_b64_e32 v[230:231], v[120:121]
	v_mov_b64_e32 v[232:233], v[58:59]
	v_mov_b64_e32 v[234:235], v[60:61]
	v_mov_b64_e32 v[236:237], v[26:27]
	v_mov_b64_e32 v[238:239], v[28:29]
	v_mov_b64_e32 v[240:241], v[110:111]
	v_mov_b64_e32 v[242:243], v[112:113]
	v_mov_b64_e32 v[244:245], v[78:79]
	v_mov_b64_e32 v[246:247], v[80:81]
	v_mov_b64_e32 v[248:249], v[46:47]
	v_mov_b64_e32 v[250:251], v[48:49]
	v_mov_b64_e32 v[62:63], v[106:107]
	v_mov_b64_e32 v[64:65], v[108:109]
	v_mov_b64_e32 v[46:47], v[74:75]
	v_mov_b64_e32 v[48:49], v[76:77]
	v_mov_b64_e32 v[74:75], v[98:99]
	v_mov_b64_e32 v[76:77], v[100:101]
	v_mov_b64_e32 v[54:55], v[66:67]
	v_mov_b64_e32 v[56:57], v[68:69]
	v_mov_b64_e32 v[58:59], v[158:159]
	v_mov_b64_e32 v[60:61], v[160:161]
	v_mov_b64_e32 v[66:67], v[50:51]
	v_mov_b64_e32 v[68:69], v[52:53]
	flat_load_dwordx4 v[138:141], v[2:3]
	flat_load_dwordx4 v[122:125], v[2:3] offset:16
	flat_load_dwordx4 v[118:121], v[2:3] offset:32
	flat_load_dwordx4 v[114:117], v[2:3] offset:48
	flat_load_dwordx4 v[110:113], v[2:3] offset:64
	flat_load_dwordx4 v[106:109], v[2:3] offset:80
	flat_load_dwordx4 v[102:105], v[2:3] offset:96
	flat_load_dwordx4 v[98:101], v[2:3] offset:112
	s_waitcnt vmcnt(0) lgkmcnt(0)
	s_barrier
	s_nop 7
	ds_write2_b32 v1, v126, v216 offset1:16
	ds_write2_b32 v1, v127, v217 offset0:68 offset1:84
	ds_write2_b32 v1, v128, v218 offset0:136 offset1:152
	ds_write2_b32 v1, v129, v219 offset0:204 offset1:220
	ds_write2_b32 v1, v228, v240 offset0:32 offset1:48
	ds_write2_b32 v1, v229, v241 offset0:100 offset1:116
	ds_write2_b32 v1, v230, v242 offset0:168 offset1:184
	ds_write2_b32 v1, v231, v243 offset0:236 offset1:252
	v_mov_b64_e32 v[180:181], v[18:19]
	v_mov_b64_e32 v[182:183], v[20:21]
	v_mov_b64_e32 v[78:79], v[94:95]
	v_mov_b64_e32 v[80:81], v[96:97]
	v_add_u32_e32 v135, 0x3000, v1
	v_add_u32_e32 v134, 0x3400, v1
	v_mov_b32_e32 v136, v170
	v_mov_b64_e32 v[50:51], v[130:131]
	v_mov_b64_e32 v[52:53], v[132:133]
	v_lshlrev_b32_e32 v137, 16, v138
	s_nop 1
	v_add_u32_e32 v130, 0x1000, v1
	v_add_u32_e32 v131, 0x1400, v1
	v_add_u32_e32 v132, 0x2000, v1
	v_add_u32_e32 v133, 0x2400, v1
	ds_write2_b32 v130, v208, v220 offset0:64 offset1:80
	ds_write2_b32 v130, v209, v221 offset0:132 offset1:148
	ds_write2_b32 v130, v210, v222 offset0:200 offset1:216
	ds_write2_b32 v131, v211, v223 offset0:12 offset1:28
	ds_write2_b32 v130, v90, v244 offset0:96 offset1:112
	ds_write2_b32 v130, v91, v245 offset0:164 offset1:180
	ds_write2_b32 v130, v92, v246 offset0:232 offset1:248
	ds_write2_b32 v131, v93, v247 offset0:44 offset1:60
	ds_write2_b32 v132, v86, v70 offset0:128 offset1:144
	ds_write2_b32 v132, v87, v71 offset0:196 offset1:212
	ds_write2_b32 v133, v88, v72 offset0:8 offset1:24
	ds_write2_b32 v133, v89, v73 offset0:76 offset1:92
	ds_write2_b32 v132, v232, v248 offset0:160 offset1:176
	ds_write2_b32 v132, v233, v249 offset0:228 offset1:244
	ds_write2_b32 v133, v234, v250 offset0:40 offset1:56
	ds_write2_b32 v133, v235, v251 offset0:108 offset1:124
	ds_write2_b32 v135, v212, v224 offset0:192 offset1:208
	ds_write2_b32 v134, v213, v225 offset0:4 offset1:20
	ds_write2_b32 v134, v214, v226 offset0:72 offset1:88
	ds_write2_b32 v134, v215, v227 offset0:140 offset1:156
	ds_write2_b32 v135, v236, v180 offset0:224 offset1:240
	ds_write2_b32 v134, v237, v181 offset0:36 offset1:52
	ds_write2_b32 v134, v238, v182 offset0:104 offset1:120
	ds_write2_b32 v134, v239, v183 offset0:172 offset1:188
	s_waitcnt lgkmcnt(0)
	s_barrier
	v_mov_b64_e32 v[30:31], v[42:43]
	v_mov_b64_e32 v[32:33], v[44:45]
	v_add_u32_e32 v126, s4, v136
	v_ashrrev_i32_e32 v127, 31, v126
	v_lshlrev_b64 v[2:3], 11, v[126:127]
	v_lshl_add_u64 v[2:3], s[8:9], 0, v[2:3]
	v_lshl_add_u64 v[128:129], v[2:3], 0, s[16:17]
	v_mul_lo_u32 v136, v136, s33
	v_mov_b64_e32 v[18:19], v[14:15]
	v_mov_b64_e32 v[20:21], v[16:17]
	v_and_b32_e32 v138, 0xffff0000, v138
	v_mov_b64_e32 v[22:23], v[10:11]
	v_mov_b64_e32 v[24:25], v[12:13]
	v_mov_b64_e32 v[42:43], v[162:163]
	v_mov_b64_e32 v[44:45], v[164:165]
	v_mov_b64_e32 v[26:27], v[6:7]
	v_mov_b64_e32 v[28:29], v[8:9]
	flat_load_dwordx4 v[94:97], v[128:129] offset:128
	flat_load_dwordx4 v[90:93], v[128:129] offset:144
	flat_load_dwordx4 v[86:89], v[128:129] offset:160
	flat_load_dwordx4 v[70:73], v[128:129] offset:176
	flat_load_dwordx4 v[14:17], v[128:129] offset:192
	flat_load_dwordx4 v[10:13], v[128:129] offset:208
	flat_load_dwordx4 v[6:9], v[128:129] offset:224
	flat_load_dwordx4 v[2:5], v[128:129] offset:240
	ds_read_b128 v[142:145], v136
	ds_read_b128 v[154:157], v136 offset:16
	s_waitcnt lgkmcnt(0)
	v_add_f32_e32 v137, v142, v137
	v_add_f32_e32 v138, v143, v138
	v_cvt_pk_bf16_f32 v138, v137, v138
	v_lshlrev_b32_e32 v137, 16, v139
	v_and_b32_e32 v139, 0xffff0000, v139
	v_add_f32_e32 v137, v144, v137
	v_add_f32_e32 v139, v145, v139
	v_cvt_pk_bf16_f32 v139, v137, v139
	v_lshlrev_b32_e32 v137, 16, v140
	v_and_b32_e32 v140, 0xffff0000, v140
	v_add_f32_e32 v137, v154, v137
	v_add_f32_e32 v140, v155, v140
	v_cvt_pk_bf16_f32 v140, v137, v140
	v_lshlrev_b32_e32 v137, 16, v141
	v_and_b32_e32 v141, 0xffff0000, v141
	v_add_f32_e32 v137, v156, v137
	v_add_f32_e32 v141, v157, v141
	v_and_b32_e32 v142, 0xffff0000, v138
	v_cvt_pk_bf16_f32 v141, v137, v141
	v_lshlrev_b32_e32 v137, 16, v138
	v_mul_f32_e32 v153, v142, v142
	v_lshlrev_b32_e32 v143, 16, v139
	v_fmac_f32_e32 v153, v137, v137
	v_and_b32_e32 v144, 0xffff0000, v139
	v_fmac_f32_e32 v153, v143, v143
	v_lshlrev_b32_e32 v145, 16, v140
	v_fmac_f32_e32 v153, v144, v144
	flat_store_dwordx4 v[128:129], v[138:141]
	v_and_b32_e32 v147, 0xffff0000, v140
	v_lshlrev_b32_e32 v149, 16, v141
	v_and_b32_e32 v151, 0xffff0000, v141
	v_fmac_f32_e32 v153, v145, v145
	ds_read_b128 v[138:141], v136 offset:32
	ds_read_b128 v[142:145], v136 offset:48
	v_lshlrev_b32_e32 v137, 16, v122
	v_and_b32_e32 v122, 0xffff0000, v122
	v_fmac_f32_e32 v153, v147, v147
	s_waitcnt lgkmcnt(0)
	v_add_f32_e32 v137, v138, v137
	v_add_f32_e32 v122, v139, v122
	v_cvt_pk_bf16_f32 v122, v137, v122
	v_lshlrev_b32_e32 v137, 16, v123
	v_and_b32_e32 v123, 0xffff0000, v123
	v_add_f32_e32 v137, v140, v137
	v_add_f32_e32 v123, v141, v123
	v_cvt_pk_bf16_f32 v123, v137, v123
	v_lshlrev_b32_e32 v137, 16, v124
	v_and_b32_e32 v124, 0xffff0000, v124
	v_add_f32_e32 v137, v142, v137
	v_add_f32_e32 v124, v143, v124
	v_cvt_pk_bf16_f32 v124, v137, v124
	v_lshlrev_b32_e32 v137, 16, v125
	v_and_b32_e32 v125, 0xffff0000, v125
	v_add_f32_e32 v137, v144, v137
	v_add_f32_e32 v125, v145, v125
	v_and_b32_e32 v138, 0xffff0000, v122
	v_cvt_pk_bf16_f32 v125, v137, v125
	v_lshlrev_b32_e32 v137, 16, v122
	v_mul_f32_e32 v138, v138, v138
	v_lshlrev_b32_e32 v139, 16, v123
	v_fmac_f32_e32 v138, v137, v137
	v_and_b32_e32 v140, 0xffff0000, v123
	v_fmac_f32_e32 v138, v139, v139
	v_lshlrev_b32_e32 v141, 16, v124
	v_fmac_f32_e32 v138, v140, v140
	v_and_b32_e32 v142, 0xffff0000, v124
	v_fmac_f32_e32 v138, v141, v141
	v_lshlrev_b32_e32 v143, 16, v125
	v_fmac_f32_e32 v138, v142, v142
	v_fmac_f32_e32 v153, v149, v149
	v_and_b32_e32 v144, 0xffff0000, v125
	v_fmac_f32_e32 v138, v143, v143
	v_fmac_f32_e32 v153, v151, v151
	v_fmac_f32_e32 v138, v144, v144
	flat_store_dwordx4 v[128:129], v[122:125] offset:16
	v_add_f32_e32 v137, v153, v138
	ds_read_b128 v[122:125], v136 offset:64
	ds_read_b128 v[138:141], v136 offset:80
	v_lshlrev_b32_e32 v142, 16, v118
	v_and_b32_e32 v118, 0xffff0000, v118
	s_waitcnt lgkmcnt(0)
	v_add_f32_e32 v122, v122, v142
	v_add_f32_e32 v118, v123, v118
	v_cvt_pk_bf16_f32 v118, v122, v118
	v_lshlrev_b32_e32 v122, 16, v119
	v_and_b32_e32 v119, 0xffff0000, v119
	v_add_f32_e32 v122, v124, v122
	v_add_f32_e32 v119, v125, v119
	v_cvt_pk_bf16_f32 v119, v122, v119
	v_lshlrev_b32_e32 v122, 16, v120
	v_and_b32_e32 v120, 0xffff0000, v120
	v_add_f32_e32 v122, v138, v122
	v_add_f32_e32 v120, v139, v120
	v_cvt_pk_bf16_f32 v120, v122, v120
	v_lshlrev_b32_e32 v122, 16, v121
	v_and_b32_e32 v121, 0xffff0000, v121
	v_add_f32_e32 v122, v140, v122
	v_add_f32_e32 v121, v141, v121
	v_and_b32_e32 v123, 0xffff0000, v118
	v_cvt_pk_bf16_f32 v121, v122, v121
	v_lshlrev_b32_e32 v122, 16, v118
	v_mul_f32_e32 v123, v123, v123
	v_lshlrev_b32_e32 v124, 16, v119
	v_fmac_f32_e32 v123, v122, v122
	v_and_b32_e32 v125, 0xffff0000, v119
	v_fmac_f32_e32 v123, v124, v124
	v_lshlrev_b32_e32 v138, 16, v120
	v_fmac_f32_e32 v123, v125, v125
	v_and_b32_e32 v139, 0xffff0000, v120
	v_fmac_f32_e32 v123, v138, v138
	v_lshlrev_b32_e32 v140, 16, v121
	v_fmac_f32_e32 v123, v139, v139
	v_and_b32_e32 v141, 0xffff0000, v121
	v_fmac_f32_e32 v123, v140, v140
	v_fmac_f32_e32 v123, v141, v141
	flat_store_dwordx4 v[128:129], v[118:121] offset:32
	v_add_f32_e32 v137, v137, v123
	ds_read_b128 v[118:121], v136 offset:96
	ds_read_b128 v[122:125], v136 offset:112
	v_lshlrev_b32_e32 v138, 16, v114
	v_and_b32_e32 v114, 0xffff0000, v114
	s_waitcnt lgkmcnt(0)
	v_add_f32_e32 v118, v118, v138
	v_add_f32_e32 v114, v119, v114
	v_cvt_pk_bf16_f32 v114, v118, v114
	v_lshlrev_b32_e32 v118, 16, v115
	v_and_b32_e32 v115, 0xffff0000, v115
	v_add_f32_e32 v118, v120, v118
	v_add_f32_e32 v115, v121, v115
	v_cvt_pk_bf16_f32 v115, v118, v115
	v_lshlrev_b32_e32 v118, 16, v116
	v_and_b32_e32 v116, 0xffff0000, v116
	v_add_f32_e32 v118, v122, v118
	v_add_f32_e32 v116, v123, v116
	v_cvt_pk_bf16_f32 v116, v118, v116
	v_lshlrev_b32_e32 v118, 16, v117
	v_and_b32_e32 v117, 0xffff0000, v117
	v_add_f32_e32 v118, v124, v118
	v_add_f32_e32 v117, v125, v117
	v_and_b32_e32 v119, 0xffff0000, v114
	v_cvt_pk_bf16_f32 v117, v118, v117
	v_lshlrev_b32_e32 v118, 16, v114
	v_mul_f32_e32 v119, v119, v119
	v_lshlrev_b32_e32 v120, 16, v115
	v_fmac_f32_e32 v119, v118, v118
	v_and_b32_e32 v121, 0xffff0000, v115
	v_fmac_f32_e32 v119, v120, v120
	v_lshlrev_b32_e32 v122, 16, v116
	v_fmac_f32_e32 v119, v121, v121
	v_and_b32_e32 v123, 0xffff0000, v116
	v_fmac_f32_e32 v119, v122, v122
	v_lshlrev_b32_e32 v124, 16, v117
	v_fmac_f32_e32 v119, v123, v123
	v_and_b32_e32 v125, 0xffff0000, v117
	v_fmac_f32_e32 v119, v124, v124
	v_fmac_f32_e32 v119, v125, v125
	flat_store_dwordx4 v[128:129], v[114:117] offset:48
	v_add_f32_e32 v122, v137, v119
	ds_read_b128 v[114:117], v136 offset:128
	ds_read_b128 v[118:121], v136 offset:144
	v_lshlrev_b32_e32 v123, 16, v110
	v_and_b32_e32 v110, 0xffff0000, v110
	s_waitcnt lgkmcnt(0)
	v_add_f32_e32 v114, v114, v123
	v_add_f32_e32 v110, v115, v110
	v_cvt_pk_bf16_f32 v110, v114, v110
	v_lshlrev_b32_e32 v114, 16, v111
	v_and_b32_e32 v111, 0xffff0000, v111
	v_add_f32_e32 v114, v116, v114
	v_add_f32_e32 v111, v117, v111
	v_cvt_pk_bf16_f32 v111, v114, v111
	v_lshlrev_b32_e32 v114, 16, v112
	v_and_b32_e32 v112, 0xffff0000, v112
	v_add_f32_e32 v114, v118, v114
	v_add_f32_e32 v112, v119, v112
	v_cvt_pk_bf16_f32 v112, v114, v112
	v_lshlrev_b32_e32 v114, 16, v113
	v_and_b32_e32 v113, 0xffff0000, v113
	v_add_f32_e32 v114, v120, v114
	v_add_f32_e32 v113, v121, v113
	v_and_b32_e32 v115, 0xffff0000, v110
	v_cvt_pk_bf16_f32 v113, v114, v113
	v_lshlrev_b32_e32 v114, 16, v110
	v_mul_f32_e32 v115, v115, v115
	v_lshlrev_b32_e32 v116, 16, v111
	v_fmac_f32_e32 v115, v114, v114
	v_and_b32_e32 v117, 0xffff0000, v111
	v_fmac_f32_e32 v115, v116, v116
	v_lshlrev_b32_e32 v118, 16, v112
	v_fmac_f32_e32 v115, v117, v117
	v_and_b32_e32 v119, 0xffff0000, v112
	v_fmac_f32_e32 v115, v118, v118
	v_lshlrev_b32_e32 v120, 16, v113
	v_fmac_f32_e32 v115, v119, v119
	v_and_b32_e32 v121, 0xffff0000, v113
	v_fmac_f32_e32 v115, v120, v120
	v_fmac_f32_e32 v115, v121, v121
	flat_store_dwordx4 v[128:129], v[110:113] offset:64
	v_add_f32_e32 v118, v122, v115
	ds_read_b128 v[110:113], v136 offset:160
	ds_read_b128 v[114:117], v136 offset:176
	v_lshlrev_b32_e32 v119, 16, v106
	v_and_b32_e32 v106, 0xffff0000, v106
	s_waitcnt lgkmcnt(0)
	v_add_f32_e32 v110, v110, v119
	v_add_f32_e32 v106, v111, v106
	v_cvt_pk_bf16_f32 v106, v110, v106
	v_lshlrev_b32_e32 v110, 16, v107
	v_and_b32_e32 v107, 0xffff0000, v107
	v_add_f32_e32 v110, v112, v110
	v_add_f32_e32 v107, v113, v107
	v_cvt_pk_bf16_f32 v107, v110, v107
	v_lshlrev_b32_e32 v110, 16, v108
	v_and_b32_e32 v108, 0xffff0000, v108
	v_add_f32_e32 v110, v114, v110
	v_add_f32_e32 v108, v115, v108
	v_cvt_pk_bf16_f32 v108, v110, v108
	v_lshlrev_b32_e32 v110, 16, v109
	v_and_b32_e32 v109, 0xffff0000, v109
	v_add_f32_e32 v110, v116, v110
	v_add_f32_e32 v109, v117, v109
	v_and_b32_e32 v111, 0xffff0000, v106
	v_cvt_pk_bf16_f32 v109, v110, v109
	v_lshlrev_b32_e32 v110, 16, v106
	v_mul_f32_e32 v111, v111, v111
	v_lshlrev_b32_e32 v112, 16, v107
	v_fmac_f32_e32 v111, v110, v110
	v_and_b32_e32 v113, 0xffff0000, v107
	v_fmac_f32_e32 v111, v112, v112
	v_lshlrev_b32_e32 v114, 16, v108
	v_fmac_f32_e32 v111, v113, v113
	v_and_b32_e32 v115, 0xffff0000, v108
	v_fmac_f32_e32 v111, v114, v114
	v_lshlrev_b32_e32 v116, 16, v109
	v_fmac_f32_e32 v111, v115, v115
	v_and_b32_e32 v117, 0xffff0000, v109
	v_fmac_f32_e32 v111, v116, v116
	v_fmac_f32_e32 v111, v117, v117
	flat_store_dwordx4 v[128:129], v[106:109] offset:80
	v_add_f32_e32 v114, v118, v111
	ds_read_b128 v[106:109], v136 offset:192
	ds_read_b128 v[110:113], v136 offset:208
	v_lshlrev_b32_e32 v115, 16, v102
	v_and_b32_e32 v102, 0xffff0000, v102
	s_waitcnt lgkmcnt(0)
	v_add_f32_e32 v106, v106, v115
	v_add_f32_e32 v102, v107, v102
	v_cvt_pk_bf16_f32 v102, v106, v102
	v_lshlrev_b32_e32 v106, 16, v103
	v_and_b32_e32 v103, 0xffff0000, v103
	v_add_f32_e32 v106, v108, v106
	v_add_f32_e32 v103, v109, v103
	v_cvt_pk_bf16_f32 v103, v106, v103
	v_lshlrev_b32_e32 v106, 16, v104
	v_and_b32_e32 v104, 0xffff0000, v104
	v_add_f32_e32 v106, v110, v106
	v_add_f32_e32 v104, v111, v104
	v_cvt_pk_bf16_f32 v104, v106, v104
	v_lshlrev_b32_e32 v106, 16, v105
	v_and_b32_e32 v105, 0xffff0000, v105
	v_add_f32_e32 v106, v112, v106
	v_add_f32_e32 v105, v113, v105
	v_and_b32_e32 v107, 0xffff0000, v102
	v_cvt_pk_bf16_f32 v105, v106, v105
	v_lshlrev_b32_e32 v106, 16, v102
	v_mul_f32_e32 v107, v107, v107
	v_lshlrev_b32_e32 v108, 16, v103
	v_fmac_f32_e32 v107, v106, v106
	v_and_b32_e32 v109, 0xffff0000, v103
	v_fmac_f32_e32 v107, v108, v108
	v_lshlrev_b32_e32 v110, 16, v104
	v_fmac_f32_e32 v107, v109, v109
	v_and_b32_e32 v111, 0xffff0000, v104
	v_fmac_f32_e32 v107, v110, v110
	v_lshlrev_b32_e32 v112, 16, v105
	v_fmac_f32_e32 v107, v111, v111
	v_and_b32_e32 v113, 0xffff0000, v105
	v_fmac_f32_e32 v107, v112, v112
	v_fmac_f32_e32 v107, v113, v113
	flat_store_dwordx4 v[128:129], v[102:105] offset:96
	v_add_f32_e32 v110, v114, v107
	ds_read_b128 v[102:105], v136 offset:224
	ds_read_b128 v[106:109], v136 offset:240
	v_lshlrev_b32_e32 v111, 16, v98
	v_and_b32_e32 v98, 0xffff0000, v98
	s_waitcnt lgkmcnt(0)
	v_add_f32_e32 v102, v102, v111
	v_add_f32_e32 v98, v103, v98
	v_cvt_pk_bf16_f32 v98, v102, v98
	v_lshlrev_b32_e32 v102, 16, v99
	v_and_b32_e32 v99, 0xffff0000, v99
	v_add_f32_e32 v102, v104, v102
	v_add_f32_e32 v99, v105, v99
	v_cvt_pk_bf16_f32 v99, v102, v99
	v_lshlrev_b32_e32 v102, 16, v100
	v_and_b32_e32 v100, 0xffff0000, v100
	v_add_f32_e32 v102, v106, v102
	v_add_f32_e32 v100, v107, v100
	v_cvt_pk_bf16_f32 v100, v102, v100
	v_lshlrev_b32_e32 v102, 16, v101
	v_and_b32_e32 v101, 0xffff0000, v101
	v_add_f32_e32 v102, v108, v102
	v_add_f32_e32 v101, v109, v101
	v_and_b32_e32 v103, 0xffff0000, v98
	v_cvt_pk_bf16_f32 v101, v102, v101
	v_lshlrev_b32_e32 v102, 16, v98
	v_mul_f32_e32 v103, v103, v103
	v_lshlrev_b32_e32 v104, 16, v99
	v_fmac_f32_e32 v103, v102, v102
	v_and_b32_e32 v105, 0xffff0000, v99
	v_fmac_f32_e32 v103, v104, v104
	v_lshlrev_b32_e32 v106, 16, v100
	v_fmac_f32_e32 v103, v105, v105
	v_and_b32_e32 v107, 0xffff0000, v100
	v_fmac_f32_e32 v103, v106, v106
	v_lshlrev_b32_e32 v108, 16, v101
	v_fmac_f32_e32 v103, v107, v107
	v_and_b32_e32 v109, 0xffff0000, v101
	v_fmac_f32_e32 v103, v108, v108
	flat_store_dwordx4 v[128:129], v[98:101] offset:112
	v_fmac_f32_e32 v103, v109, v109
	v_add_f32_e32 v102, v110, v103
	v_lshlrev_b64 v[98:99], 6, v[126:127]
	v_lshl_add_u64 v[98:99], s[6:7], 0, v[98:99]
	v_lshl_add_u64 v[98:99], v[98:99], 0, s[18:19]
	flat_store_dword v[98:99], v102
	s_waitcnt lgkmcnt(0)
	s_barrier
	ds_write2_b32 v1, v62, v74 offset1:16
	ds_write2_b32 v1, v63, v75 offset0:68 offset1:84
	ds_write2_b32 v1, v64, v76 offset0:136 offset1:152
	ds_write2_b32 v1, v65, v77 offset0:204 offset1:220
	ds_write2_b32 v1, v78, v82 offset0:32 offset1:48
	ds_write2_b32 v1, v79, v83 offset0:100 offset1:116
	ds_write2_b32 v1, v80, v84 offset0:168 offset1:184
	ds_write2_b32 v1, v81, v85 offset0:236 offset1:252
	ds_write2_b32 v130, v46, v54 offset0:64 offset1:80
	ds_write2_b32 v130, v47, v55 offset0:132 offset1:148
	ds_write2_b32 v130, v48, v56 offset0:200 offset1:216
	ds_write2_b32 v131, v49, v57 offset0:12 offset1:28
	ds_write2_b32 v130, v58, v66 offset0:96 offset1:112
	ds_write2_b32 v130, v59, v67 offset0:164 offset1:180
	ds_write2_b32 v130, v60, v68 offset0:232 offset1:248
	ds_write2_b32 v131, v61, v69 offset0:44 offset1:60
	ds_write2_b32 v132, v30, v38 offset0:128 offset1:144
	ds_write2_b32 v132, v31, v39 offset0:196 offset1:212
	ds_write2_b32 v133, v32, v40 offset0:8 offset1:24
	ds_write2_b32 v133, v33, v41 offset0:76 offset1:92
	ds_write2_b32 v132, v42, v50 offset0:160 offset1:176
	ds_write2_b32 v132, v43, v51 offset0:228 offset1:244
	ds_write2_b32 v133, v44, v52 offset0:40 offset1:56
	ds_write2_b32 v133, v45, v53 offset0:108 offset1:124
	ds_write2_b32 v135, v18, v22 offset0:192 offset1:208
	ds_write2_b32 v134, v19, v23 offset0:4 offset1:20
	ds_write2_b32 v134, v20, v24 offset0:72 offset1:88
	ds_write2_b32 v134, v21, v25 offset0:140 offset1:156
	ds_write2_b32 v135, v26, v34 offset0:224 offset1:240
	ds_write2_b32 v134, v27, v35 offset0:36 offset1:52
	ds_write2_b32 v134, v28, v36 offset0:104 offset1:120
	ds_write2_b32 v134, v29, v37 offset0:172 offset1:188
	v_mov_b32_e32 v1, v170
	s_waitcnt lgkmcnt(0)
	s_barrier
	s_waitcnt vmcnt(0)
	v_lshlrev_b32_e32 v28, 16, v94
	v_add_u32_e32 v18, s4, v1
	v_ashrrev_i32_e32 v19, 31, v18
	v_lshlrev_b64 v[20:21], 11, v[18:19]
	v_lshl_add_u64 v[20:21], s[38:39], 0, v[20:21]
	v_mul_lo_u32 v1, v1, s33
	v_lshl_add_u64 v[32:33], v[20:21], 0, s[16:17]
	ds_read_b128 v[20:23], v1
	ds_read_b128 v[24:27], v1 offset:16
	s_mov_b64 s[4:5], 0
	s_waitcnt lgkmcnt(1)
	v_add_f32_e32 v20, v20, v28
	v_and_b32_e32 v28, 0xffff0000, v94
	v_add_f32_e32 v21, v21, v28
	v_cvt_pk_bf16_f32 v28, v20, v21
	v_and_b32_e32 v21, 0xffff0000, v95
	v_lshlrev_b32_e32 v20, 16, v95
	v_add_f32_e32 v21, v23, v21
	v_add_f32_e32 v20, v22, v20
	v_cvt_pk_bf16_f32 v29, v20, v21
	v_and_b32_e32 v21, 0xffff0000, v96
	v_lshlrev_b32_e32 v20, 16, v96
	s_waitcnt lgkmcnt(0)
	v_add_f32_e32 v21, v25, v21
	v_add_f32_e32 v20, v24, v20
	v_cvt_pk_bf16_f32 v30, v20, v21
	v_and_b32_e32 v21, 0xffff0000, v97
	v_lshlrev_b32_e32 v20, 16, v97
	v_add_f32_e32 v21, v27, v21
	v_add_f32_e32 v20, v26, v20
	v_cvt_pk_bf16_f32 v31, v20, v21
	v_and_b32_e32 v21, 0xffff0000, v28
	v_lshlrev_b32_e32 v20, 16, v28
	v_mul_f32_e32 v34, v21, v21
	v_lshlrev_b32_e32 v22, 16, v29
	v_fmac_f32_e32 v34, v20, v20
	v_and_b32_e32 v23, 0xffff0000, v29
	v_fmac_f32_e32 v34, v22, v22
	v_lshlrev_b32_e32 v24, 16, v30
	v_fmac_f32_e32 v34, v23, v23
	v_and_b32_e32 v25, 0xffff0000, v30
	v_fmac_f32_e32 v34, v24, v24
	v_add_co_u32_e32 v20, vcc, s90, v32
	v_lshlrev_b32_e32 v26, 16, v31
	v_fmac_f32_e32 v34, v25, v25
	v_addc_co_u32_e32 v21, vcc, 0, v33, vcc
	v_and_b32_e32 v27, 0xffff0000, v31
	v_fmac_f32_e32 v34, v26, v26
	flat_store_dwordx4 v[20:21], v[28:31] offset:128
	v_fmac_f32_e32 v34, v27, v27
	ds_read_b128 v[22:25], v1 offset:32
	ds_read_b128 v[26:29], v1 offset:48
	v_lshlrev_b32_e32 v30, 16, v90
	s_waitcnt lgkmcnt(0)
	v_add_f32_e32 v22, v22, v30
	v_and_b32_e32 v30, 0xffff0000, v90
	v_add_f32_e32 v23, v23, v30
	v_cvt_pk_bf16_f32 v22, v22, v23
	v_lshlrev_b32_e32 v23, 16, v91
	v_add_f32_e32 v23, v24, v23
	v_and_b32_e32 v24, 0xffff0000, v91
	v_add_f32_e32 v24, v25, v24
	v_cvt_pk_bf16_f32 v23, v23, v24
	v_lshlrev_b32_e32 v24, 16, v92
	v_and_b32_e32 v25, 0xffff0000, v92
	v_add_f32_e32 v24, v26, v24
	v_add_f32_e32 v25, v27, v25
	v_cvt_pk_bf16_f32 v24, v24, v25
	v_lshlrev_b32_e32 v25, 16, v93
	v_and_b32_e32 v26, 0xffff0000, v93
	v_add_f32_e32 v25, v28, v25
	v_add_f32_e32 v26, v29, v26
	v_and_b32_e32 v27, 0xffff0000, v22
	v_cvt_pk_bf16_f32 v25, v25, v26
	v_lshlrev_b32_e32 v26, 16, v22
	v_mul_f32_e32 v27, v27, v27
	v_lshlrev_b32_e32 v28, 16, v23
	v_fmac_f32_e32 v27, v26, v26
	v_and_b32_e32 v29, 0xffff0000, v23
	v_fmac_f32_e32 v27, v28, v28
	v_lshlrev_b32_e32 v30, 16, v24
	v_fmac_f32_e32 v27, v29, v29
	v_and_b32_e32 v31, 0xffff0000, v24
	v_fmac_f32_e32 v27, v30, v30
	v_lshlrev_b32_e32 v32, 16, v25
	v_fmac_f32_e32 v27, v31, v31
	v_and_b32_e32 v33, 0xffff0000, v25
	v_fmac_f32_e32 v27, v32, v32
	v_fmac_f32_e32 v27, v33, v33
	flat_store_dwordx4 v[20:21], v[22:25] offset:144
	v_add_f32_e32 v30, v34, v27
	ds_read_b128 v[22:25], v1 offset:64
	ds_read_b128 v[26:29], v1 offset:80
	v_lshlrev_b32_e32 v31, 16, v86
	s_waitcnt lgkmcnt(0)
	v_add_f32_e32 v22, v22, v31
	v_and_b32_e32 v31, 0xffff0000, v86
	v_add_f32_e32 v23, v23, v31
	v_cvt_pk_bf16_f32 v22, v22, v23
	v_lshlrev_b32_e32 v23, 16, v87
	v_add_f32_e32 v23, v24, v23
	v_and_b32_e32 v24, 0xffff0000, v87
	v_add_f32_e32 v24, v25, v24
	v_cvt_pk_bf16_f32 v23, v23, v24
	v_lshlrev_b32_e32 v24, 16, v88
	v_and_b32_e32 v25, 0xffff0000, v88
	v_add_f32_e32 v24, v26, v24
	v_add_f32_e32 v25, v27, v25
	v_cvt_pk_bf16_f32 v24, v24, v25
	v_lshlrev_b32_e32 v25, 16, v89
	v_and_b32_e32 v26, 0xffff0000, v89
	v_add_f32_e32 v25, v28, v25
	v_add_f32_e32 v26, v29, v26
	v_and_b32_e32 v27, 0xffff0000, v22
	v_cvt_pk_bf16_f32 v25, v25, v26
	v_lshlrev_b32_e32 v26, 16, v22
	v_mul_f32_e32 v27, v27, v27
	v_lshlrev_b32_e32 v28, 16, v23
	v_fmac_f32_e32 v27, v26, v26
	v_and_b32_e32 v29, 0xffff0000, v23
	v_fmac_f32_e32 v27, v28, v28
	v_lshlrev_b32_e32 v31, 16, v24
	v_fmac_f32_e32 v27, v29, v29
	v_and_b32_e32 v32, 0xffff0000, v24
	v_fmac_f32_e32 v27, v31, v31
	v_lshlrev_b32_e32 v33, 16, v25
	v_fmac_f32_e32 v27, v32, v32
	v_and_b32_e32 v34, 0xffff0000, v25
	v_fmac_f32_e32 v27, v33, v33
	v_fmac_f32_e32 v27, v34, v34
	flat_store_dwordx4 v[20:21], v[22:25] offset:160
	v_add_f32_e32 v30, v30, v27
	ds_read_b128 v[22:25], v1 offset:96
	ds_read_b128 v[26:29], v1 offset:112
	v_lshlrev_b32_e32 v31, 16, v70
	s_waitcnt lgkmcnt(0)
	v_add_f32_e32 v22, v22, v31
	v_and_b32_e32 v31, 0xffff0000, v70
	v_add_f32_e32 v23, v23, v31
	v_cvt_pk_bf16_f32 v22, v22, v23
	v_lshlrev_b32_e32 v23, 16, v71
	v_add_f32_e32 v23, v24, v23
	v_and_b32_e32 v24, 0xffff0000, v71
	v_add_f32_e32 v24, v25, v24
	v_cvt_pk_bf16_f32 v23, v23, v24
	v_lshlrev_b32_e32 v24, 16, v72
	v_and_b32_e32 v25, 0xffff0000, v72
	v_add_f32_e32 v24, v26, v24
	v_add_f32_e32 v25, v27, v25
	v_cvt_pk_bf16_f32 v24, v24, v25
	v_lshlrev_b32_e32 v25, 16, v73
	v_and_b32_e32 v26, 0xffff0000, v73
	v_add_f32_e32 v25, v28, v25
	v_add_f32_e32 v26, v29, v26
	v_and_b32_e32 v27, 0xffff0000, v22
	v_cvt_pk_bf16_f32 v25, v25, v26
	v_lshlrev_b32_e32 v26, 16, v22
	v_mul_f32_e32 v27, v27, v27
	v_lshlrev_b32_e32 v28, 16, v23
	v_fmac_f32_e32 v27, v26, v26
	v_and_b32_e32 v29, 0xffff0000, v23
	v_fmac_f32_e32 v27, v28, v28
	v_lshlrev_b32_e32 v31, 16, v24
	v_fmac_f32_e32 v27, v29, v29
	v_and_b32_e32 v32, 0xffff0000, v24
	v_fmac_f32_e32 v27, v31, v31
	v_lshlrev_b32_e32 v33, 16, v25
	v_fmac_f32_e32 v27, v32, v32
	v_and_b32_e32 v34, 0xffff0000, v25
	v_fmac_f32_e32 v27, v33, v33
	v_fmac_f32_e32 v27, v34, v34
	flat_store_dwordx4 v[20:21], v[22:25] offset:176
	v_add_f32_e32 v30, v30, v27
	ds_read_b128 v[22:25], v1 offset:128
	ds_read_b128 v[26:29], v1 offset:144
	v_lshlrev_b32_e32 v31, 16, v14
	v_and_b32_e32 v14, 0xffff0000, v14
	s_waitcnt lgkmcnt(0)
	v_add_f32_e32 v22, v22, v31
	v_add_f32_e32 v14, v23, v14
	v_cvt_pk_bf16_f32 v14, v22, v14
	v_lshlrev_b32_e32 v22, 16, v15
	v_and_b32_e32 v15, 0xffff0000, v15
	v_add_f32_e32 v22, v24, v22
	v_add_f32_e32 v15, v25, v15
	v_cvt_pk_bf16_f32 v15, v22, v15
	v_lshlrev_b32_e32 v22, 16, v16
	v_and_b32_e32 v16, 0xffff0000, v16
	v_add_f32_e32 v22, v26, v22
	v_add_f32_e32 v16, v27, v16
	v_cvt_pk_bf16_f32 v16, v22, v16
	v_lshlrev_b32_e32 v22, 16, v17
	v_and_b32_e32 v17, 0xffff0000, v17
	v_add_f32_e32 v22, v28, v22
	v_add_f32_e32 v17, v29, v17
	v_and_b32_e32 v23, 0xffff0000, v14
	v_cvt_pk_bf16_f32 v17, v22, v17
	v_lshlrev_b32_e32 v22, 16, v14
	v_mul_f32_e32 v23, v23, v23
	v_lshlrev_b32_e32 v24, 16, v15
	v_fmac_f32_e32 v23, v22, v22
	v_and_b32_e32 v25, 0xffff0000, v15
	v_fmac_f32_e32 v23, v24, v24
	v_lshlrev_b32_e32 v26, 16, v16
	v_fmac_f32_e32 v23, v25, v25
	v_and_b32_e32 v27, 0xffff0000, v16
	v_fmac_f32_e32 v23, v26, v26
	v_lshlrev_b32_e32 v28, 16, v17
	v_fmac_f32_e32 v23, v27, v27
	v_and_b32_e32 v29, 0xffff0000, v17
	v_fmac_f32_e32 v23, v28, v28
	v_fmac_f32_e32 v23, v29, v29
	flat_store_dwordx4 v[20:21], v[14:17] offset:192
	v_add_f32_e32 v26, v30, v23
	ds_read_b128 v[14:17], v1 offset:160
	ds_read_b128 v[22:25], v1 offset:176
	v_lshlrev_b32_e32 v27, 16, v10
	v_and_b32_e32 v10, 0xffff0000, v10
	s_waitcnt lgkmcnt(0)
	v_add_f32_e32 v14, v14, v27
	v_add_f32_e32 v10, v15, v10
	v_cvt_pk_bf16_f32 v10, v14, v10
	v_lshlrev_b32_e32 v14, 16, v11
	v_and_b32_e32 v11, 0xffff0000, v11
	v_add_f32_e32 v14, v16, v14
	v_add_f32_e32 v11, v17, v11
	v_cvt_pk_bf16_f32 v11, v14, v11
	v_lshlrev_b32_e32 v14, 16, v12
	v_and_b32_e32 v12, 0xffff0000, v12
	v_add_f32_e32 v14, v22, v14
	v_add_f32_e32 v12, v23, v12
	v_cvt_pk_bf16_f32 v12, v14, v12
	v_lshlrev_b32_e32 v14, 16, v13
	v_and_b32_e32 v13, 0xffff0000, v13
	v_add_f32_e32 v14, v24, v14
	v_add_f32_e32 v13, v25, v13
	v_and_b32_e32 v15, 0xffff0000, v10
	v_cvt_pk_bf16_f32 v13, v14, v13
	v_lshlrev_b32_e32 v14, 16, v10
	v_mul_f32_e32 v15, v15, v15
	v_lshlrev_b32_e32 v16, 16, v11
	v_fmac_f32_e32 v15, v14, v14
	v_and_b32_e32 v17, 0xffff0000, v11
	v_fmac_f32_e32 v15, v16, v16
	v_lshlrev_b32_e32 v22, 16, v12
	v_fmac_f32_e32 v15, v17, v17
	v_and_b32_e32 v23, 0xffff0000, v12
	v_fmac_f32_e32 v15, v22, v22
	v_lshlrev_b32_e32 v24, 16, v13
	v_fmac_f32_e32 v15, v23, v23
	v_and_b32_e32 v25, 0xffff0000, v13
	v_fmac_f32_e32 v15, v24, v24
	v_fmac_f32_e32 v15, v25, v25
	flat_store_dwordx4 v[20:21], v[10:13] offset:208
	v_add_f32_e32 v22, v26, v15
	ds_read_b128 v[10:13], v1 offset:192
	ds_read_b128 v[14:17], v1 offset:208
	v_lshlrev_b32_e32 v23, 16, v6
	v_and_b32_e32 v6, 0xffff0000, v6
	s_waitcnt lgkmcnt(0)
	v_add_f32_e32 v10, v10, v23
	v_add_f32_e32 v6, v11, v6
	v_cvt_pk_bf16_f32 v6, v10, v6
	v_lshlrev_b32_e32 v10, 16, v7
	v_and_b32_e32 v7, 0xffff0000, v7
	v_add_f32_e32 v10, v12, v10
	v_add_f32_e32 v7, v13, v7
	v_cvt_pk_bf16_f32 v7, v10, v7
	v_lshlrev_b32_e32 v10, 16, v8
	v_and_b32_e32 v8, 0xffff0000, v8
	v_add_f32_e32 v10, v14, v10
	v_add_f32_e32 v8, v15, v8
	v_cvt_pk_bf16_f32 v8, v10, v8
	v_lshlrev_b32_e32 v10, 16, v9
	v_and_b32_e32 v9, 0xffff0000, v9
	v_add_f32_e32 v10, v16, v10
	v_add_f32_e32 v9, v17, v9
	v_and_b32_e32 v11, 0xffff0000, v6
	v_cvt_pk_bf16_f32 v9, v10, v9
	v_lshlrev_b32_e32 v10, 16, v6
	v_mul_f32_e32 v11, v11, v11
	v_lshlrev_b32_e32 v12, 16, v7
	v_fmac_f32_e32 v11, v10, v10
	v_and_b32_e32 v13, 0xffff0000, v7
	v_fmac_f32_e32 v11, v12, v12
	v_lshlrev_b32_e32 v14, 16, v8
	v_fmac_f32_e32 v11, v13, v13
	v_and_b32_e32 v15, 0xffff0000, v8
	v_fmac_f32_e32 v11, v14, v14
	v_lshlrev_b32_e32 v16, 16, v9
	v_fmac_f32_e32 v11, v15, v15
	v_and_b32_e32 v17, 0xffff0000, v9
	v_fmac_f32_e32 v11, v16, v16
	v_fmac_f32_e32 v11, v17, v17
	flat_store_dwordx4 v[20:21], v[6:9] offset:224
	v_add_f32_e32 v14, v22, v11
	ds_read_b128 v[6:9], v1 offset:224
	ds_read_b128 v[10:13], v1 offset:240
	v_lshlrev_b32_e32 v1, 16, v2
	v_and_b32_e32 v2, 0xffff0000, v2
	s_waitcnt lgkmcnt(0)
	v_add_f32_e32 v1, v6, v1
	v_add_f32_e32 v2, v7, v2
	v_cvt_pk_bf16_f32 v2, v1, v2
	v_lshlrev_b32_e32 v1, 16, v3
	v_and_b32_e32 v3, 0xffff0000, v3
	v_add_f32_e32 v1, v8, v1
	v_add_f32_e32 v3, v9, v3
	v_cvt_pk_bf16_f32 v3, v1, v3
	v_lshlrev_b32_e32 v1, 16, v4
	v_and_b32_e32 v4, 0xffff0000, v4
	v_add_f32_e32 v1, v10, v1
	v_add_f32_e32 v4, v11, v4
	v_cvt_pk_bf16_f32 v4, v1, v4
	v_lshlrev_b32_e32 v1, 16, v5
	v_and_b32_e32 v5, 0xffff0000, v5
	v_add_f32_e32 v1, v12, v1
	v_add_f32_e32 v5, v13, v5
	v_and_b32_e32 v6, 0xffff0000, v2
	v_cvt_pk_bf16_f32 v5, v1, v5
	v_lshlrev_b32_e32 v1, 16, v2
	v_mul_f32_e32 v6, v6, v6
	v_lshlrev_b32_e32 v7, 16, v3
	v_fmac_f32_e32 v6, v1, v1
	v_and_b32_e32 v8, 0xffff0000, v3
	v_fmac_f32_e32 v6, v7, v7
	v_lshlrev_b32_e32 v9, 16, v4
	v_fmac_f32_e32 v6, v8, v8
	v_and_b32_e32 v10, 0xffff0000, v4
	v_fmac_f32_e32 v6, v9, v9
	v_lshlrev_b32_e32 v11, 16, v5
	v_fmac_f32_e32 v6, v10, v10
	v_and_b32_e32 v12, 0xffff0000, v5
	v_fmac_f32_e32 v6, v11, v11
	flat_store_dwordx4 v[20:21], v[2:5] offset:240
	v_fmac_f32_e32 v6, v12, v12
	v_add_f32_e32 v1, v14, v6
	v_lshlrev_b64 v[2:3], 6, v[18:19]
	v_lshl_add_u64 v[2:3], s[6:7], 0, v[2:3]
	v_lshl_add_u64 v[2:3], v[2:3], 0, s[18:19]
	flat_store_dword v[2:3], v1 offset:4
	s_branch .LBB0_342

.Lbk64_418:
	s_waitcnt vmcnt(4)
	ds_read_b128 v[192:195], v227
	ds_read_b128 v[196:199], v228
	ds_read_b128 v[200:203], v227 offset:2048
	ds_read_b128 v[204:207], v228 offset:2048
	ds_read_b128 v[208:211], v227 offset:4096
	ds_read_b128 v[212:215], v228 offset:4096
	ds_read_b128 v[216:219], v227 offset:6144
	ds_read_b128 v[220:223], v228 offset:6144
	s_waitcnt vmcnt(0)
	s_barrier
	s_add_u32 s4, s4, 0x80
	s_addc_u32 s5, s5, 0
	s_add_u32 s22, s22, 0x80
	s_addc_u32 s23, s23, 0
	s_waitcnt lgkmcnt(0)
	ds_read_b128 v[154:157], v229 offset:0
	ds_read_b128 v[158:161], v230 offset:0
	ds_read_b128 v[162:165], v229 offset:2048
	ds_read_b128 v[166:169], v230 offset:2048
	s_waitcnt lgkmcnt(2)
	v_mfma_f32_16x16x32_bf16 v[126:129], v[192:195], v[154:157], v[126:129]
	v_mfma_f32_16x16x32_bf16 v[114:117], v[200:203], v[154:157], v[114:117]
	v_mfma_f32_16x16x32_bf16 v[94:97], v[208:211], v[154:157], v[94:97]
	v_mfma_f32_16x16x32_bf16 v[62:65], v[216:219], v[154:157], v[62:65]
	v_readfirstlane_b32 s32, v142
	s_lshl_b32 m0, s32, 3
	v_add_u32_e32 v226, 0, v224
	v_max_i32_e32 v226, 0, v226
	v_min_i32_e32 v226, 0xffff, v226
	v_lshl_add_u32 v226, v226, 11, v231
	global_load_lds_dwordx4 v226, s[4:5]
	v_mfma_f32_16x16x32_bf16 v[126:129], v[196:199], v[158:161], v[126:129]
	v_mfma_f32_16x16x32_bf16 v[114:117], v[204:207], v[158:161], v[114:117]
	v_mfma_f32_16x16x32_bf16 v[94:97], v[212:215], v[158:161], v[94:97]
	v_mfma_f32_16x16x32_bf16 v[62:65], v[220:223], v[158:161], v[62:65]
	s_add_u32 m0, m0, 0x400
	v_add_u32_e32 v226, 8, v224
	v_max_i32_e32 v226, 0, v226
	v_min_i32_e32 v226, 0xffff, v226
	v_lshl_add_u32 v226, v226, 11, v231
	global_load_lds_dwordx4 v226, s[4:5]
	ds_read_b128 v[154:157], v229 offset:4096
	ds_read_b128 v[158:161], v230 offset:4096
	s_waitcnt lgkmcnt(2)
	v_mfma_f32_16x16x32_bf16 v[122:125], v[192:195], v[162:165], v[122:125]
	v_mfma_f32_16x16x32_bf16 v[106:109], v[200:203], v[162:165], v[106:109]
	v_mfma_f32_16x16x32_bf16 v[78:81], v[208:211], v[162:165], v[78:81]
	v_mfma_f32_16x16x32_bf16 v[46:49], v[216:219], v[162:165], v[46:49]
	s_add_u32 m0, m0, 0x400
	v_add_u32_e32 v226, 16, v224
	v_max_i32_e32 v226, 0, v226
	v_min_i32_e32 v226, 0xffff, v226
	v_lshl_add_u32 v226, v226, 11, v231
	global_load_lds_dwordx4 v226, s[4:5]
	v_mfma_f32_16x16x32_bf16 v[122:125], v[196:199], v[166:169], v[122:125]
	v_mfma_f32_16x16x32_bf16 v[106:109], v[204:207], v[166:169], v[106:109]
	v_mfma_f32_16x16x32_bf16 v[78:81], v[212:215], v[166:169], v[78:81]
	v_mfma_f32_16x16x32_bf16 v[46:49], v[220:223], v[166:169], v[46:49]
	s_add_u32 m0, m0, 0x400
	v_add_u32_e32 v226, 24, v224
	v_max_i32_e32 v226, 0, v226
	v_min_i32_e32 v226, 0xffff, v226
	v_lshl_add_u32 v226, v226, 11, v231
	global_load_lds_dwordx4 v226, s[4:5]
	ds_read_b128 v[162:165], v229 offset:6144
	ds_read_b128 v[166:169], v230 offset:6144
	s_waitcnt lgkmcnt(2)
	v_mfma_f32_16x16x32_bf16 v[118:121], v[192:195], v[154:157], v[118:121]
	v_mfma_f32_16x16x32_bf16 v[98:101], v[200:203], v[154:157], v[98:101]
	v_mfma_f32_16x16x32_bf16 v[70:73], v[208:211], v[154:157], v[70:73]
	v_mfma_f32_16x16x32_bf16 v[38:41], v[216:219], v[154:157], v[38:41]
	s_add_u32 m0, m0, 0x400
	v_add_u32_e32 v226, 32, v224
	v_max_i32_e32 v226, 0, v226
	v_min_i32_e32 v226, 0xffff, v226
	v_lshl_add_u32 v226, v226, 11, v231
	global_load_lds_dwordx4 v226, s[4:5]
	v_mfma_f32_16x16x32_bf16 v[118:121], v[196:199], v[158:161], v[118:121]
	v_mfma_f32_16x16x32_bf16 v[98:101], v[204:207], v[158:161], v[98:101]
	v_mfma_f32_16x16x32_bf16 v[70:73], v[212:215], v[158:161], v[70:73]
	v_mfma_f32_16x16x32_bf16 v[38:41], v[220:223], v[158:161], v[38:41]
	s_add_u32 m0, m0, 0x400
	v_add_u32_e32 v226, 40, v224
	v_max_i32_e32 v226, 0, v226
	v_min_i32_e32 v226, 0xffff, v226
	v_lshl_add_u32 v226, v226, 11, v231
	global_load_lds_dwordx4 v226, s[4:5]
	ds_read_b128 v[154:157], v229 offset:8192
	ds_read_b128 v[158:161], v230 offset:8192
	s_waitcnt lgkmcnt(2)
	v_mfma_f32_16x16x32_bf16 v[110:113], v[192:195], v[162:165], v[110:113]
	v_mfma_f32_16x16x32_bf16 v[86:89], v[200:203], v[162:165], v[86:89]
	v_mfma_f32_16x16x32_bf16 v[54:57], v[208:211], v[162:165], v[54:57]
	v_mfma_f32_16x16x32_bf16 v[26:29], v[216:219], v[162:165], v[26:29]
	s_add_u32 m0, m0, 0x400
	v_add_u32_e32 v226, 48, v224
	v_max_i32_e32 v226, 0, v226
	v_min_i32_e32 v226, 0xffff, v226
	v_lshl_add_u32 v226, v226, 11, v231
	global_load_lds_dwordx4 v226, s[4:5]
	v_mfma_f32_16x16x32_bf16 v[110:113], v[196:199], v[166:169], v[110:113]
	v_mfma_f32_16x16x32_bf16 v[86:89], v[204:207], v[166:169], v[86:89]
	v_mfma_f32_16x16x32_bf16 v[54:57], v[212:215], v[166:169], v[54:57]
	v_mfma_f32_16x16x32_bf16 v[26:29], v[220:223], v[166:169], v[26:29]
	s_add_u32 m0, m0, 0x400
	v_add_u32_e32 v226, 56, v224
	v_max_i32_e32 v226, 0, v226
	v_min_i32_e32 v226, 0xffff, v226
	v_lshl_add_u32 v226, v226, 11, v231
	global_load_lds_dwordx4 v226, s[4:5]
	ds_read_b128 v[162:165], v229 offset:10240
	ds_read_b128 v[166:169], v230 offset:10240
	s_waitcnt lgkmcnt(2)
	v_mfma_f32_16x16x32_bf16 v[102:105], v[192:195], v[154:157], v[102:105]
	v_mfma_f32_16x16x32_bf16 v[74:77], v[200:203], v[154:157], v[74:77]
	v_mfma_f32_16x16x32_bf16 v[42:45], v[208:211], v[154:157], v[42:45]
	v_mfma_f32_16x16x32_bf16 v[18:21], v[216:219], v[154:157], v[18:21]
	s_add_u32 m0, s21, 17
	s_and_b32 m0, m0, 1
	s_lshl_b32 m0, m0, 14
	s_add_u32 m0, m0, 0x8000
	v_readfirstlane_b32 s32, v142
	s_lshl_b32 s32, s32, 2
	s_add_u32 m0, m0, s32
	v_mov_b32_e32 v226, v225
	global_load_lds_dwordx4 v226, s[22:23]
	v_mfma_f32_16x16x32_bf16 v[102:105], v[196:199], v[158:161], v[102:105]
	v_mfma_f32_16x16x32_bf16 v[74:77], v[204:207], v[158:161], v[74:77]
	v_mfma_f32_16x16x32_bf16 v[42:45], v[212:215], v[158:161], v[42:45]
	v_mfma_f32_16x16x32_bf16 v[18:21], v[220:223], v[158:161], v[18:21]
	s_add_u32 m0, m0, 0x400
	v_add_u32_e32 v226, 0x4000, v225
	global_load_lds_dwordx4 v226, s[22:23]
	ds_read_b128 v[154:157], v229 offset:12288
	ds_read_b128 v[158:161], v230 offset:12288
	s_waitcnt lgkmcnt(2)
	v_mfma_f32_16x16x32_bf16 v[90:93], v[192:195], v[162:165], v[90:93]
	v_mfma_f32_16x16x32_bf16 v[58:61], v[200:203], v[162:165], v[58:61]
	v_mfma_f32_16x16x32_bf16 v[30:33], v[208:211], v[162:165], v[30:33]
	v_mfma_f32_16x16x32_bf16 v[10:13], v[216:219], v[162:165], v[10:13]
	s_add_u32 m0, m0, 0x400
	v_add_u32_e32 v226, 0x8000, v225
	global_load_lds_dwordx4 v226, s[22:23]
	v_mfma_f32_16x16x32_bf16 v[90:93], v[196:199], v[166:169], v[90:93]
	v_mfma_f32_16x16x32_bf16 v[58:61], v[204:207], v[166:169], v[58:61]
	v_mfma_f32_16x16x32_bf16 v[30:33], v[212:215], v[166:169], v[30:33]
	v_mfma_f32_16x16x32_bf16 v[10:13], v[220:223], v[166:169], v[10:13]
	s_add_u32 m0, m0, 0x400
	v_add_u32_e32 v226, 0xc000, v225
	global_load_lds_dwordx4 v226, s[22:23]
	ds_read_b128 v[162:165], v229 offset:14336
	ds_read_b128 v[166:169], v230 offset:14336
	s_waitcnt lgkmcnt(2)
	v_mfma_f32_16x16x32_bf16 v[82:85], v[192:195], v[154:157], v[82:85]
	v_mfma_f32_16x16x32_bf16 v[50:53], v[200:203], v[154:157], v[50:53]
	v_mfma_f32_16x16x32_bf16 v[22:25], v[208:211], v[154:157], v[22:25]
	v_mfma_f32_16x16x32_bf16 v[6:9], v[216:219], v[154:157], v[6:9]
	v_mfma_f32_16x16x32_bf16 v[82:85], v[196:199], v[158:161], v[82:85]
	v_mfma_f32_16x16x32_bf16 v[50:53], v[204:207], v[158:161], v[50:53]
	v_mfma_f32_16x16x32_bf16 v[22:25], v[212:215], v[158:161], v[22:25]
	v_mfma_f32_16x16x32_bf16 v[6:9], v[220:223], v[158:161], v[6:9]
	s_waitcnt lgkmcnt(0)
	v_mfma_f32_16x16x32_bf16 v[66:69], v[192:195], v[162:165], v[66:69]
	v_mfma_f32_16x16x32_bf16 v[34:37], v[200:203], v[162:165], v[34:37]
	v_mfma_f32_16x16x32_bf16 v[14:17], v[208:211], v[162:165], v[14:17]
	v_mfma_f32_16x16x32_bf16 v[2:5], v[216:219], v[162:165], v[2:5]
	v_mfma_f32_16x16x32_bf16 v[66:69], v[196:199], v[166:169], v[66:69]
	v_mfma_f32_16x16x32_bf16 v[34:37], v[204:207], v[166:169], v[34:37]
	v_mfma_f32_16x16x32_bf16 v[14:17], v[212:215], v[166:169], v[14:17]
	v_mfma_f32_16x16x32_bf16 v[2:5], v[220:223], v[166:169], v[2:5]
	v_xor_b32_e32 v229, 0x4000, v229
	v_xor_b32_e32 v230, 0x4000, v230
	s_add_i32 s21, s21, 1
	s_cmp_lg_u32 s21, 15
	s_cbranch_scc1 .Lbk64_418
	s_waitcnt vmcnt(4)
	ds_read_b128 v[192:195], v227
	ds_read_b128 v[196:199], v228
	ds_read_b128 v[200:203], v227 offset:2048
	ds_read_b128 v[204:207], v228 offset:2048
	ds_read_b128 v[208:211], v227 offset:4096
	ds_read_b128 v[212:215], v228 offset:4096
	ds_read_b128 v[216:219], v227 offset:6144
	ds_read_b128 v[220:223], v228 offset:6144
	s_waitcnt vmcnt(0)
	s_barrier
	s_waitcnt lgkmcnt(0)
	ds_read_b128 v[154:157], v229 offset:0
	ds_read_b128 v[158:161], v230 offset:0
	ds_read_b128 v[162:165], v229 offset:2048
	ds_read_b128 v[166:169], v230 offset:2048
	s_waitcnt lgkmcnt(2)
	v_mfma_f32_16x16x32_bf16 v[126:129], v[192:195], v[154:157], v[126:129]
	v_mfma_f32_16x16x32_bf16 v[114:117], v[200:203], v[154:157], v[114:117]
	v_mfma_f32_16x16x32_bf16 v[94:97], v[208:211], v[154:157], v[94:97]
	v_mfma_f32_16x16x32_bf16 v[62:65], v[216:219], v[154:157], v[62:65]
	v_mfma_f32_16x16x32_bf16 v[126:129], v[196:199], v[158:161], v[126:129]
	v_mfma_f32_16x16x32_bf16 v[114:117], v[204:207], v[158:161], v[114:117]
	v_mfma_f32_16x16x32_bf16 v[94:97], v[212:215], v[158:161], v[94:97]
	v_mfma_f32_16x16x32_bf16 v[62:65], v[220:223], v[158:161], v[62:65]
	ds_read_b128 v[154:157], v229 offset:4096
	ds_read_b128 v[158:161], v230 offset:4096
	s_waitcnt lgkmcnt(2)
	v_mfma_f32_16x16x32_bf16 v[122:125], v[192:195], v[162:165], v[122:125]
	v_mfma_f32_16x16x32_bf16 v[106:109], v[200:203], v[162:165], v[106:109]
	v_mfma_f32_16x16x32_bf16 v[78:81], v[208:211], v[162:165], v[78:81]
	v_mfma_f32_16x16x32_bf16 v[46:49], v[216:219], v[162:165], v[46:49]
	v_mfma_f32_16x16x32_bf16 v[122:125], v[196:199], v[166:169], v[122:125]
	v_mfma_f32_16x16x32_bf16 v[106:109], v[204:207], v[166:169], v[106:109]
	v_mfma_f32_16x16x32_bf16 v[78:81], v[212:215], v[166:169], v[78:81]
	v_mfma_f32_16x16x32_bf16 v[46:49], v[220:223], v[166:169], v[46:49]
	ds_read_b128 v[162:165], v229 offset:6144
	ds_read_b128 v[166:169], v230 offset:6144
	s_waitcnt lgkmcnt(2)
	v_mfma_f32_16x16x32_bf16 v[118:121], v[192:195], v[154:157], v[118:121]
	v_mfma_f32_16x16x32_bf16 v[98:101], v[200:203], v[154:157], v[98:101]
	v_mfma_f32_16x16x32_bf16 v[70:73], v[208:211], v[154:157], v[70:73]
	v_mfma_f32_16x16x32_bf16 v[38:41], v[216:219], v[154:157], v[38:41]
	v_mfma_f32_16x16x32_bf16 v[118:121], v[196:199], v[158:161], v[118:121]
	v_mfma_f32_16x16x32_bf16 v[98:101], v[204:207], v[158:161], v[98:101]
	v_mfma_f32_16x16x32_bf16 v[70:73], v[212:215], v[158:161], v[70:73]
	v_mfma_f32_16x16x32_bf16 v[38:41], v[220:223], v[158:161], v[38:41]
	ds_read_b128 v[154:157], v229 offset:8192
	ds_read_b128 v[158:161], v230 offset:8192
	s_waitcnt lgkmcnt(2)
	v_mfma_f32_16x16x32_bf16 v[110:113], v[192:195], v[162:165], v[110:113]
	v_mfma_f32_16x16x32_bf16 v[86:89], v[200:203], v[162:165], v[86:89]
	v_mfma_f32_16x16x32_bf16 v[54:57], v[208:211], v[162:165], v[54:57]
	v_mfma_f32_16x16x32_bf16 v[26:29], v[216:219], v[162:165], v[26:29]
	v_mfma_f32_16x16x32_bf16 v[110:113], v[196:199], v[166:169], v[110:113]
	v_mfma_f32_16x16x32_bf16 v[86:89], v[204:207], v[166:169], v[86:89]
	v_mfma_f32_16x16x32_bf16 v[54:57], v[212:215], v[166:169], v[54:57]
	v_mfma_f32_16x16x32_bf16 v[26:29], v[220:223], v[166:169], v[26:29]
	ds_read_b128 v[162:165], v229 offset:10240
	ds_read_b128 v[166:169], v230 offset:10240
	s_waitcnt lgkmcnt(2)
	v_mfma_f32_16x16x32_bf16 v[102:105], v[192:195], v[154:157], v[102:105]
	v_mfma_f32_16x16x32_bf16 v[74:77], v[200:203], v[154:157], v[74:77]
	v_mfma_f32_16x16x32_bf16 v[42:45], v[208:211], v[154:157], v[42:45]
	v_mfma_f32_16x16x32_bf16 v[18:21], v[216:219], v[154:157], v[18:21]
	v_mfma_f32_16x16x32_bf16 v[102:105], v[196:199], v[158:161], v[102:105]
	v_mfma_f32_16x16x32_bf16 v[74:77], v[204:207], v[158:161], v[74:77]
	v_mfma_f32_16x16x32_bf16 v[42:45], v[212:215], v[158:161], v[42:45]
	v_mfma_f32_16x16x32_bf16 v[18:21], v[220:223], v[158:161], v[18:21]
	ds_read_b128 v[154:157], v229 offset:12288
	ds_read_b128 v[158:161], v230 offset:12288
	s_waitcnt lgkmcnt(2)
	v_mfma_f32_16x16x32_bf16 v[90:93], v[192:195], v[162:165], v[90:93]
	v_mfma_f32_16x16x32_bf16 v[58:61], v[200:203], v[162:165], v[58:61]
	v_mfma_f32_16x16x32_bf16 v[30:33], v[208:211], v[162:165], v[30:33]
	v_mfma_f32_16x16x32_bf16 v[10:13], v[216:219], v[162:165], v[10:13]
	v_mfma_f32_16x16x32_bf16 v[90:93], v[196:199], v[166:169], v[90:93]
	v_mfma_f32_16x16x32_bf16 v[58:61], v[204:207], v[166:169], v[58:61]
	v_mfma_f32_16x16x32_bf16 v[30:33], v[212:215], v[166:169], v[30:33]
	v_mfma_f32_16x16x32_bf16 v[10:13], v[220:223], v[166:169], v[10:13]
	ds_read_b128 v[162:165], v229 offset:14336
	ds_read_b128 v[166:169], v230 offset:14336
	s_waitcnt lgkmcnt(2)
	v_mfma_f32_16x16x32_bf16 v[82:85], v[192:195], v[154:157], v[82:85]
	v_mfma_f32_16x16x32_bf16 v[50:53], v[200:203], v[154:157], v[50:53]
	v_mfma_f32_16x16x32_bf16 v[22:25], v[208:211], v[154:157], v[22:25]
	v_mfma_f32_16x16x32_bf16 v[6:9], v[216:219], v[154:157], v[6:9]
	v_mfma_f32_16x16x32_bf16 v[82:85], v[196:199], v[158:161], v[82:85]
	v_mfma_f32_16x16x32_bf16 v[50:53], v[204:207], v[158:161], v[50:53]
	v_mfma_f32_16x16x32_bf16 v[22:25], v[212:215], v[158:161], v[22:25]
	v_mfma_f32_16x16x32_bf16 v[6:9], v[220:223], v[158:161], v[6:9]
	s_waitcnt lgkmcnt(0)
	v_mfma_f32_16x16x32_bf16 v[66:69], v[192:195], v[162:165], v[66:69]
	v_mfma_f32_16x16x32_bf16 v[34:37], v[200:203], v[162:165], v[34:37]
	v_mfma_f32_16x16x32_bf16 v[14:17], v[208:211], v[162:165], v[14:17]
	v_mfma_f32_16x16x32_bf16 v[2:5], v[216:219], v[162:165], v[2:5]
	v_mfma_f32_16x16x32_bf16 v[66:69], v[196:199], v[166:169], v[66:69]
	v_mfma_f32_16x16x32_bf16 v[34:37], v[204:207], v[166:169], v[34:37]
	v_mfma_f32_16x16x32_bf16 v[14:17], v[212:215], v[166:169], v[14:17]
	v_mfma_f32_16x16x32_bf16 v[2:5], v[220:223], v[166:169], v[2:5]
	s_nop 7
	s_nop 7
	s_waitcnt vmcnt(6)
	v_add_u32_e32 v142, v149, v147
	s_waitcnt lgkmcnt(0)
	v_and_b32_e32 v1, 0xfffffc0, v1
	v_lshl_or_b32 v1, v144, 2, v1
	v_mul_lo_u32 v1, v1, s33
	v_lshl_or_b32 v1, v143, 2, v1
	s_waitcnt lgkmcnt(0)
	s_waitcnt lgkmcnt(0)
	s_waitcnt lgkmcnt(0)
	s_waitcnt lgkmcnt(0)
	s_waitcnt lgkmcnt(0)
	v_mov_b64_e32 v[162:163], v[30:31]
	v_mov_b64_e32 v[164:165], v[32:33]
	v_mov_b64_e32 v[134:135], v[10:11]
	v_mov_b64_e32 v[136:137], v[12:13]
	s_nop 2
	s_waitcnt lgkmcnt(0)
	v_mov_b64_e32 v[180:181], v[6:7]
	v_mov_b64_e32 v[182:183], v[8:9]
	s_nop 2
	s_waitcnt vmcnt(0)
	v_mov_b64_e32 v[166:167], v[22:23]
	v_mov_b64_e32 v[168:169], v[24:25]
	s_waitcnt lgkmcnt(0)
	v_mov_b64_e32 v[130:131], v[34:35]
	v_mov_b64_e32 v[132:133], v[36:37]
	v_mov_b64_e32 v[138:139], v[14:15]
	v_mov_b64_e32 v[140:141], v[16:17]
	v_mov_b64_e32 v[158:159], v[2:3]
	v_mov_b64_e32 v[160:161], v[4:5]
	s_nop 1
	s_waitcnt lgkmcnt(0)
	v_mov_b64_e32 v[22:23], v[126:127]
	v_mov_b64_e32 v[24:25], v[128:129]
	s_nop 2
	v_mov_b64_e32 v[32:33], v[114:115]
	v_mov_b64_e32 v[34:35], v[116:117]
	s_nop 2
	s_waitcnt lgkmcnt(0)
	v_mov_b64_e32 v[2:3], v[122:123]
	v_mov_b64_e32 v[4:5], v[124:125]
	v_mov_b64_e32 v[122:123], v[46:47]
	v_mov_b64_e32 v[124:125], v[48:49]
	s_waitcnt lgkmcnt(0)
	v_mov_b64_e32 v[46:47], v[118:119]
	v_mov_b64_e32 v[48:49], v[120:121]
	v_mov_b64_e32 v[118:119], v[38:39]
	v_mov_b64_e32 v[120:121], v[40:41]
	v_mov_b64_e32 v[36:37], v[110:111]
	v_mov_b64_e32 v[38:39], v[112:113]
	s_nop 2
	s_waitcnt vmcnt(0) lgkmcnt(0)
	s_barrier
	ds_write2_b32 v1, v22, v2 offset1:16
	ds_write2_b32 v1, v23, v3 offset0:68 offset1:84
	ds_write2_b32 v1, v24, v4 offset0:136 offset1:152
	ds_write2_b32 v1, v25, v5 offset0:204 offset1:220
	ds_write2_b32 v1, v46, v36 offset0:32 offset1:48
	ds_write2_b32 v1, v47, v37 offset0:100 offset1:116
	ds_write2_b32 v1, v48, v38 offset0:168 offset1:184
	ds_write2_b32 v1, v49, v39 offset0:236 offset1:252
	v_mov_b64_e32 v[200:201], v[86:87]
	v_mov_b64_e32 v[202:203], v[88:89]
	s_nop 1
	v_add_u32_e32 v88, 0x1000, v1
	ds_write2_b32 v88, v32, v106 offset0:64 offset1:80
	ds_write2_b32 v88, v33, v107 offset0:132 offset1:148
	ds_write2_b32 v88, v34, v108 offset0:200 offset1:216
	v_add_u32_e32 v89, 0x1400, v1
	v_mov_b64_e32 v[212:213], v[26:27]
	v_mov_b64_e32 v[214:215], v[28:29]
	ds_write2_b32 v89, v35, v109 offset0:12 offset1:28
	ds_write2_b32 v88, v98, v200 offset0:96 offset1:112
	ds_write2_b32 v88, v99, v201 offset0:164 offset1:180
	ds_write2_b32 v88, v100, v202 offset0:232 offset1:248
	ds_write2_b32 v89, v101, v203 offset0:44 offset1:60
	v_mov_b64_e32 v[30:31], v[90:91]
	v_mov_b64_e32 v[32:33], v[92:93]
	s_nop 2
	v_add_u32_e32 v90, 0x2000, v1
	v_add_u32_e32 v91, 0x2400, v1
	ds_write2_b32 v90, v94, v78 offset0:128 offset1:144
	ds_write2_b32 v90, v95, v79 offset0:196 offset1:212
	ds_write2_b32 v91, v96, v80 offset0:8 offset1:24
	ds_write2_b32 v91, v97, v81 offset0:76 offset1:92
	ds_write2_b32 v90, v70, v54 offset0:160 offset1:176
	ds_write2_b32 v90, v71, v55 offset0:228 offset1:244
	ds_write2_b32 v91, v72, v56 offset0:40 offset1:56
	v_add_u32_e32 v92, 0x3000, v1
	v_add_u32_e32 v93, 0x3400, v1
	v_mov_b32_e32 v70, v170
	v_mov_b64_e32 v[6:7], v[42:43]
	v_mov_b64_e32 v[8:9], v[44:45]
	ds_write2_b32 v91, v73, v57 offset0:108 offset1:124
	ds_write2_b32 v92, v62, v122 offset0:192 offset1:208
	ds_write2_b32 v93, v63, v123 offset0:4 offset1:20
	ds_write2_b32 v93, v64, v124 offset0:72 offset1:88
	v_mov_b64_e32 v[42:43], v[50:51]
	v_mov_b64_e32 v[44:45], v[52:53]
	ds_write2_b32 v93, v65, v125 offset0:140 offset1:156
	ds_write2_b32 v92, v118, v212 offset0:224 offset1:240
	ds_write2_b32 v93, v119, v213 offset0:36 offset1:52
	ds_write2_b32 v93, v120, v214 offset0:104 offset1:120
	ds_write2_b32 v93, v121, v215 offset0:172 offset1:188
	s_waitcnt lgkmcnt(0)
	s_barrier
	v_mov_b64_e32 v[14:15], v[102:103]
	v_mov_b64_e32 v[16:17], v[104:105]
	v_ashrrev_i32_e32 v50, 7, v70
	v_mov_b64_e32 v[10:11], v[74:75]
	v_mov_b64_e32 v[12:13], v[76:77]
	v_mov_b64_e32 v[2:3], v[18:19]
	v_mov_b64_e32 v[4:5], v[20:21]
	v_mov_b64_e32 v[26:27], v[58:59]
	v_mov_b64_e32 v[28:29], v[60:61]
	v_mov_b64_e32 v[22:23], v[162:163]
	v_mov_b64_e32 v[24:25], v[164:165]
	v_mov_b64_e32 v[18:19], v[134:135]
	v_mov_b64_e32 v[20:21], v[136:137]
	v_mov_b64_e32 v[46:47], v[82:83]
	v_mov_b64_e32 v[48:49], v[84:85]
	v_mov_b64_e32 v[38:39], v[166:167]
	v_mov_b64_e32 v[40:41], v[168:169]
	v_mov_b64_e32 v[34:35], v[180:181]
	v_mov_b64_e32 v[36:37], v[182:183]
	v_mov_b64_e32 v[62:63], v[66:67]
	v_mov_b64_e32 v[64:65], v[68:69]
	v_mov_b64_e32 v[58:59], v[130:131]
	v_mov_b64_e32 v[60:61], v[132:133]
	s_nop 1
	v_add_u32_e32 v66, s46, v50
	v_cmp_lt_i32_e32 vcc, s91, v66
	v_mov_b64_e32 v[54:55], v[138:139]
	v_mov_b64_e32 v[56:57], v[140:141]
	v_mov_b64_e32 v[50:51], v[158:159]
	v_mov_b64_e32 v[52:53], v[160:161]
	s_and_saveexec_b64 s[4:5], vcc
	s_xor_b64 s[22:23], exec, s[4:5]
	v_add_u32_e32 v66, 0xfffffef0, v66
	v_mul_hi_u32 v67, v66, s96
	v_lshrrev_b32_e32 v67, 3, v67
	v_add_u32_e32 v68, 16, v67
	v_lshl_add_u32 v67, v67, 5, v67
	v_sub_u32_e32 v71, v66, v67
	s_or_saveexec_b64 s[22:23], s[22:23]
	v_mov_b32_e32 v72, 0x1000
	s_xor_b64 exec, exec, s[22:23]
	v_mul_hi_i32 v67, v66, s97
	v_lshrrev_b32_e32 v68, 31, v67
	v_ashrrev_i32_e32 v67, 3, v67
	v_add_u32_e32 v68, v67, v68
	v_lshl_add_u32 v67, v68, 4, v68
	v_sub_u32_e32 v71, v66, v67
	v_mov_b32_e32 v72, 0x800
	s_or_b64 exec, exec, s[22:23]
	v_cmp_lt_i32_e32 vcc, 15, v68
	s_and_saveexec_b64 s[4:5], vcc
	s_xor_b64 s[4:5], exec, s[4:5]
	v_add_u32_e32 v66, -16, v68
	v_mov_b32_e32 v67, v0
	v_lshlrev_b64 v[66:67], 12, v[66:67]
	v_lshl_add_u64 v[66:67], v[66:67], 0, s[42:43]
	s_andn2_saveexec_b64 s[22:23], s[4:5]
	v_ashrrev_i32_e32 v69, 31, v68
	v_lshlrev_b64 v[66:67], 11, v[68:69]
	s_or_b64 exec, exec, s[22:23]
	v_and_b32_e32 v69, 0x7f, v70
	v_cmp_gt_i32_e32 vcc, s79, v69
	s_and_saveexec_b64 s[22:23], vcc
	s_cbranch_execz .LBB0_436
	v_cmp_ne_u32_e32 vcc, 0, v69
	s_and_b64 exec, exec, vcc
	s_cbranch_execz .LBB0_436
	v_mul_lo_u32 v71, v71, s54
	v_add3_u32 v68, v69, v71, -1
	v_cmp_lt_i32_e32 vcc, v68, v72
	s_and_b64 exec, exec, vcc
	s_cbranch_execz .LBB0_436
	v_cmp_lt_i32_e32 vcc, 0, v68
	v_mov_b32_e32 v83, 0
	v_mov_b32_e32 v82, 0
	s_and_saveexec_b64 s[4:5], vcc
	v_mov_b32_e32 v73, 0x11ffc
	v_lshl_add_u32 v73, v70, 2, v73
	ds_read_b32 v82, v73
	s_or_b64 exec, exec, s[4:5]
	v_add_u32_e32 v69, v71, v69
	v_cmp_lt_i32_e32 vcc, v69, v72
	v_lshl_add_u32 v69, v70, 2, v175
	ds_read_b32 v84, v69
	s_and_saveexec_b64 s[4:5], vcc
	ds_read_b32 v83, v69 offset:4
	s_or_b64 exec, exec, s[4:5]
	s_lshl_b32 s4, s20, 6
	s_ashr_i32 s5, s4, 31
	s_lshl_b64 s[4:5], s[4:5], 1
	v_ashrrev_i32_e32 v69, 31, v68
	s_add_u32 s4, s38, s4
	v_lshl_add_u64 v[66:67], v[66:67], 0, v[68:69]
	v_mul_lo_u32 v68, v70, s33
	s_addc_u32 s5, s39, s5
	v_add_u32_e32 v94, 0xfffffef0, v68
	v_mov_b64_e32 v[68:69], s[4:5]
	v_mad_u64_u32 v[86:87], s[4:5], v66, s3, v[68:69]
	v_mov_b32_e32 v66, v87
	v_mad_u64_u32 v[66:67], s[4:5], v67, s3, v[66:67]
	v_mov_b32_e32 v87, v66
	s_mov_b32 s4, 0

.Lbk64_530:
	s_waitcnt vmcnt(4)
	ds_read_b128 v[192:195], v227
	ds_read_b128 v[196:199], v228
	ds_read_b128 v[200:203], v227 offset:2048
	ds_read_b128 v[204:207], v228 offset:2048
	ds_read_b128 v[208:211], v227 offset:4096
	ds_read_b128 v[212:215], v228 offset:4096
	ds_read_b128 v[216:219], v227 offset:6144
	ds_read_b128 v[220:223], v228 offset:6144
	s_waitcnt vmcnt(0)
	s_barrier
	s_add_u32 s18, s18, 0x80
	s_addc_u32 s19, s19, 0
	s_waitcnt lgkmcnt(0)
	ds_read_b128 v[154:157], v229 offset:0
	ds_read_b128 v[158:161], v230 offset:0
	ds_read_b128 v[162:165], v229 offset:2048
	ds_read_b128 v[166:169], v230 offset:2048
	s_waitcnt lgkmcnt(2)
	v_mfma_f32_16x16x32_bf16 v[126:129], v[192:195], v[154:157], v[126:129]
	v_mfma_f32_16x16x32_bf16 v[114:117], v[200:203], v[154:157], v[114:117]
	v_mfma_f32_16x16x32_bf16 v[86:89], v[208:211], v[154:157], v[86:89]
	v_mfma_f32_16x16x32_bf16 v[54:57], v[216:219], v[154:157], v[54:57]
	v_readfirstlane_b32 s32, v145
	s_lshl_b32 m0, s32, 3
	v_mov_b32_e32 v226, v224
	global_load_lds_dwordx4 v226, s[18:19]
	v_mfma_f32_16x16x32_bf16 v[126:129], v[196:199], v[158:161], v[126:129]
	v_mfma_f32_16x16x32_bf16 v[114:117], v[204:207], v[158:161], v[114:117]
	v_mfma_f32_16x16x32_bf16 v[86:89], v[212:215], v[158:161], v[86:89]
	v_mfma_f32_16x16x32_bf16 v[54:57], v[220:223], v[158:161], v[54:57]
	s_add_u32 m0, m0, 0x400
	v_add_u32_e32 v226, 0x4000, v224
	global_load_lds_dwordx4 v226, s[18:19]
	ds_read_b128 v[154:157], v229 offset:4096
	ds_read_b128 v[158:161], v230 offset:4096
	s_waitcnt lgkmcnt(2)
	v_mfma_f32_16x16x32_bf16 v[122:125], v[192:195], v[162:165], v[122:125]
	v_mfma_f32_16x16x32_bf16 v[102:105], v[200:203], v[162:165], v[102:105]
	v_mfma_f32_16x16x32_bf16 v[70:73], v[208:211], v[162:165], v[70:73]
	v_mfma_f32_16x16x32_bf16 v[38:41], v[216:219], v[162:165], v[38:41]
	s_add_u32 m0, m0, 0x400
	v_add_u32_e32 v226, 0x8000, v224
	global_load_lds_dwordx4 v226, s[18:19]
	v_mfma_f32_16x16x32_bf16 v[122:125], v[196:199], v[166:169], v[122:125]
	v_mfma_f32_16x16x32_bf16 v[102:105], v[204:207], v[166:169], v[102:105]
	v_mfma_f32_16x16x32_bf16 v[70:73], v[212:215], v[166:169], v[70:73]
	v_mfma_f32_16x16x32_bf16 v[38:41], v[220:223], v[166:169], v[38:41]
	s_add_u32 m0, m0, 0x400
	v_add_u32_e32 v226, 0xc000, v224
	global_load_lds_dwordx4 v226, s[18:19]
	ds_read_b128 v[162:165], v229 offset:6144
	ds_read_b128 v[166:169], v230 offset:6144
	s_waitcnt lgkmcnt(2)
	v_mfma_f32_16x16x32_bf16 v[118:121], v[192:195], v[154:157], v[118:121]
	v_mfma_f32_16x16x32_bf16 v[90:93], v[200:203], v[154:157], v[90:93]
	v_mfma_f32_16x16x32_bf16 v[58:61], v[208:211], v[154:157], v[58:61]
	v_mfma_f32_16x16x32_bf16 v[26:29], v[216:219], v[154:157], v[26:29]
	s_add_u32 m0, m0, 0x400
	v_add_u32_e32 v226, 0x10000, v224
	global_load_lds_dwordx4 v226, s[18:19]
	v_mfma_f32_16x16x32_bf16 v[118:121], v[196:199], v[158:161], v[118:121]
	v_mfma_f32_16x16x32_bf16 v[90:93], v[204:207], v[158:161], v[90:93]
	v_mfma_f32_16x16x32_bf16 v[58:61], v[212:215], v[158:161], v[58:61]
	v_mfma_f32_16x16x32_bf16 v[26:29], v[220:223], v[158:161], v[26:29]
	s_add_u32 m0, m0, 0x400
	v_add_u32_e32 v226, 0x14000, v224
	global_load_lds_dwordx4 v226, s[18:19]
	ds_read_b128 v[154:157], v229 offset:8192
	ds_read_b128 v[158:161], v230 offset:8192
	s_waitcnt lgkmcnt(2)
	v_mfma_f32_16x16x32_bf16 v[110:113], v[192:195], v[162:165], v[110:113]
	v_mfma_f32_16x16x32_bf16 v[78:81], v[200:203], v[162:165], v[78:81]
	v_mfma_f32_16x16x32_bf16 v[46:49], v[208:211], v[162:165], v[46:49]
	v_mfma_f32_16x16x32_bf16 v[18:21], v[216:219], v[162:165], v[18:21]
	s_add_u32 m0, m0, 0x400
	v_add_u32_e32 v226, 0x18000, v224
	global_load_lds_dwordx4 v226, s[18:19]
	v_mfma_f32_16x16x32_bf16 v[110:113], v[196:199], v[166:169], v[110:113]
	v_mfma_f32_16x16x32_bf16 v[78:81], v[204:207], v[166:169], v[78:81]
	v_mfma_f32_16x16x32_bf16 v[46:49], v[212:215], v[166:169], v[46:49]
	v_mfma_f32_16x16x32_bf16 v[18:21], v[220:223], v[166:169], v[18:21]
	s_add_u32 m0, m0, 0x400
	v_add_u32_e32 v226, 0x1c000, v224
	global_load_lds_dwordx4 v226, s[18:19]
	ds_read_b128 v[162:165], v229 offset:10240
	ds_read_b128 v[166:169], v230 offset:10240
	s_waitcnt lgkmcnt(2)
	v_mfma_f32_16x16x32_bf16 v[106:109], v[192:195], v[154:157], v[106:109]
	v_mfma_f32_16x16x32_bf16 v[74:77], v[200:203], v[154:157], v[74:77]
	v_mfma_f32_16x16x32_bf16 v[42:45], v[208:211], v[154:157], v[42:45]
	v_mfma_f32_16x16x32_bf16 v[14:17], v[216:219], v[154:157], v[14:17]
	s_add_u32 m0, s25, 17
	s_and_b32 m0, m0, 1
	s_lshl_b32 m0, m0, 14
	s_add_u32 m0, m0, 0x8000
	v_readfirstlane_b32 s32, v145
	s_lshl_b32 s32, s32, 2
	s_add_u32 m0, m0, s32
	v_mov_b32_e32 v226, v225
	global_load_lds_dwordx4 v226, s[18:19]
	v_mfma_f32_16x16x32_bf16 v[106:109], v[196:199], v[158:161], v[106:109]
	v_mfma_f32_16x16x32_bf16 v[74:77], v[204:207], v[158:161], v[74:77]
	v_mfma_f32_16x16x32_bf16 v[42:45], v[212:215], v[158:161], v[42:45]
	v_mfma_f32_16x16x32_bf16 v[14:17], v[220:223], v[158:161], v[14:17]
	s_add_u32 m0, m0, 0x400
	v_add_u32_e32 v226, 0x4000, v225
	global_load_lds_dwordx4 v226, s[18:19]
	ds_read_b128 v[154:157], v229 offset:12288
	ds_read_b128 v[158:161], v230 offset:12288
	s_waitcnt lgkmcnt(2)
	v_mfma_f32_16x16x32_bf16 v[98:101], v[192:195], v[162:165], v[98:101]
	v_mfma_f32_16x16x32_bf16 v[66:69], v[200:203], v[162:165], v[66:69]
	v_mfma_f32_16x16x32_bf16 v[34:37], v[208:211], v[162:165], v[34:37]
	v_mfma_f32_16x16x32_bf16 v[10:13], v[216:219], v[162:165], v[10:13]
	s_add_u32 m0, m0, 0x400
	v_add_u32_e32 v226, 0x8000, v225
	global_load_lds_dwordx4 v226, s[18:19]
	v_mfma_f32_16x16x32_bf16 v[98:101], v[196:199], v[166:169], v[98:101]
	v_mfma_f32_16x16x32_bf16 v[66:69], v[204:207], v[166:169], v[66:69]
	v_mfma_f32_16x16x32_bf16 v[34:37], v[212:215], v[166:169], v[34:37]
	v_mfma_f32_16x16x32_bf16 v[10:13], v[220:223], v[166:169], v[10:13]
	s_add_u32 m0, m0, 0x400
	v_add_u32_e32 v226, 0xc000, v225
	global_load_lds_dwordx4 v226, s[18:19]
	ds_read_b128 v[162:165], v229 offset:14336
	ds_read_b128 v[166:169], v230 offset:14336
	s_waitcnt lgkmcnt(2)
	v_mfma_f32_16x16x32_bf16 v[94:97], v[192:195], v[154:157], v[94:97]
	v_mfma_f32_16x16x32_bf16 v[62:65], v[200:203], v[154:157], v[62:65]
	v_mfma_f32_16x16x32_bf16 v[30:33], v[208:211], v[154:157], v[30:33]
	v_mfma_f32_16x16x32_bf16 v[6:9], v[216:219], v[154:157], v[6:9]
	v_mfma_f32_16x16x32_bf16 v[94:97], v[196:199], v[158:161], v[94:97]
	v_mfma_f32_16x16x32_bf16 v[62:65], v[204:207], v[158:161], v[62:65]
	v_mfma_f32_16x16x32_bf16 v[30:33], v[212:215], v[158:161], v[30:33]
	v_mfma_f32_16x16x32_bf16 v[6:9], v[220:223], v[158:161], v[6:9]
	s_waitcnt lgkmcnt(0)
	v_mfma_f32_16x16x32_bf16 v[82:85], v[192:195], v[162:165], v[82:85]
	v_mfma_f32_16x16x32_bf16 v[50:53], v[200:203], v[162:165], v[50:53]
	v_mfma_f32_16x16x32_bf16 v[22:25], v[208:211], v[162:165], v[22:25]
	v_mfma_f32_16x16x32_bf16 v[2:5], v[216:219], v[162:165], v[2:5]
	v_mfma_f32_16x16x32_bf16 v[82:85], v[196:199], v[166:169], v[82:85]
	v_mfma_f32_16x16x32_bf16 v[50:53], v[204:207], v[166:169], v[50:53]
	v_mfma_f32_16x16x32_bf16 v[22:25], v[212:215], v[166:169], v[22:25]
	v_mfma_f32_16x16x32_bf16 v[2:5], v[220:223], v[166:169], v[2:5]
	v_xor_b32_e32 v229, 0x4000, v229
	v_xor_b32_e32 v230, 0x4000, v230
	s_add_i32 s25, s25, 1
	s_cmp_lg_u32 s25, 15
	s_cbranch_scc1 .Lbk64_530
	s_waitcnt vmcnt(4)
	ds_read_b128 v[192:195], v227
	ds_read_b128 v[196:199], v228
	ds_read_b128 v[200:203], v227 offset:2048
	ds_read_b128 v[204:207], v228 offset:2048
	ds_read_b128 v[208:211], v227 offset:4096
	ds_read_b128 v[212:215], v228 offset:4096
	ds_read_b128 v[216:219], v227 offset:6144
	ds_read_b128 v[220:223], v228 offset:6144
	s_waitcnt vmcnt(0)
	s_barrier
	s_waitcnt lgkmcnt(0)
	ds_read_b128 v[154:157], v229 offset:0
	ds_read_b128 v[158:161], v230 offset:0
	ds_read_b128 v[162:165], v229 offset:2048
	ds_read_b128 v[166:169], v230 offset:2048
	s_waitcnt lgkmcnt(2)
	v_mfma_f32_16x16x32_bf16 v[126:129], v[192:195], v[154:157], v[126:129]
	v_mfma_f32_16x16x32_bf16 v[114:117], v[200:203], v[154:157], v[114:117]
	v_mfma_f32_16x16x32_bf16 v[86:89], v[208:211], v[154:157], v[86:89]
	v_mfma_f32_16x16x32_bf16 v[54:57], v[216:219], v[154:157], v[54:57]
	v_mfma_f32_16x16x32_bf16 v[126:129], v[196:199], v[158:161], v[126:129]
	v_mfma_f32_16x16x32_bf16 v[114:117], v[204:207], v[158:161], v[114:117]
	v_mfma_f32_16x16x32_bf16 v[86:89], v[212:215], v[158:161], v[86:89]
	v_mfma_f32_16x16x32_bf16 v[54:57], v[220:223], v[158:161], v[54:57]
	ds_read_b128 v[154:157], v229 offset:4096
	ds_read_b128 v[158:161], v230 offset:4096
	s_waitcnt lgkmcnt(2)
	v_mfma_f32_16x16x32_bf16 v[122:125], v[192:195], v[162:165], v[122:125]
	v_mfma_f32_16x16x32_bf16 v[102:105], v[200:203], v[162:165], v[102:105]
	v_mfma_f32_16x16x32_bf16 v[70:73], v[208:211], v[162:165], v[70:73]
	v_mfma_f32_16x16x32_bf16 v[38:41], v[216:219], v[162:165], v[38:41]
	v_mfma_f32_16x16x32_bf16 v[122:125], v[196:199], v[166:169], v[122:125]
	v_mfma_f32_16x16x32_bf16 v[102:105], v[204:207], v[166:169], v[102:105]
	v_mfma_f32_16x16x32_bf16 v[70:73], v[212:215], v[166:169], v[70:73]
	v_mfma_f32_16x16x32_bf16 v[38:41], v[220:223], v[166:169], v[38:41]
	ds_read_b128 v[162:165], v229 offset:6144
	ds_read_b128 v[166:169], v230 offset:6144
	s_waitcnt lgkmcnt(2)
	v_mfma_f32_16x16x32_bf16 v[118:121], v[192:195], v[154:157], v[118:121]
	v_mfma_f32_16x16x32_bf16 v[90:93], v[200:203], v[154:157], v[90:93]
	v_mfma_f32_16x16x32_bf16 v[58:61], v[208:211], v[154:157], v[58:61]
	v_mfma_f32_16x16x32_bf16 v[26:29], v[216:219], v[154:157], v[26:29]
	v_mfma_f32_16x16x32_bf16 v[118:121], v[196:199], v[158:161], v[118:121]
	v_mfma_f32_16x16x32_bf16 v[90:93], v[204:207], v[158:161], v[90:93]
	v_mfma_f32_16x16x32_bf16 v[58:61], v[212:215], v[158:161], v[58:61]
	v_mfma_f32_16x16x32_bf16 v[26:29], v[220:223], v[158:161], v[26:29]
	ds_read_b128 v[154:157], v229 offset:8192
	ds_read_b128 v[158:161], v230 offset:8192
	s_waitcnt lgkmcnt(2)
	v_mfma_f32_16x16x32_bf16 v[110:113], v[192:195], v[162:165], v[110:113]
	v_mfma_f32_16x16x32_bf16 v[78:81], v[200:203], v[162:165], v[78:81]
	v_mfma_f32_16x16x32_bf16 v[46:49], v[208:211], v[162:165], v[46:49]
	v_mfma_f32_16x16x32_bf16 v[18:21], v[216:219], v[162:165], v[18:21]
	v_mfma_f32_16x16x32_bf16 v[110:113], v[196:199], v[166:169], v[110:113]
	v_mfma_f32_16x16x32_bf16 v[78:81], v[204:207], v[166:169], v[78:81]
	v_mfma_f32_16x16x32_bf16 v[46:49], v[212:215], v[166:169], v[46:49]
	v_mfma_f32_16x16x32_bf16 v[18:21], v[220:223], v[166:169], v[18:21]
	ds_read_b128 v[162:165], v229 offset:10240
	ds_read_b128 v[166:169], v230 offset:10240
	s_waitcnt lgkmcnt(2)
	v_mfma_f32_16x16x32_bf16 v[106:109], v[192:195], v[154:157], v[106:109]
	v_mfma_f32_16x16x32_bf16 v[74:77], v[200:203], v[154:157], v[74:77]
	v_mfma_f32_16x16x32_bf16 v[42:45], v[208:211], v[154:157], v[42:45]
	v_mfma_f32_16x16x32_bf16 v[14:17], v[216:219], v[154:157], v[14:17]
	v_mfma_f32_16x16x32_bf16 v[106:109], v[196:199], v[158:161], v[106:109]
	v_mfma_f32_16x16x32_bf16 v[74:77], v[204:207], v[158:161], v[74:77]
	v_mfma_f32_16x16x32_bf16 v[42:45], v[212:215], v[158:161], v[42:45]
	v_mfma_f32_16x16x32_bf16 v[14:17], v[220:223], v[158:161], v[14:17]
	ds_read_b128 v[154:157], v229 offset:12288
	ds_read_b128 v[158:161], v230 offset:12288
	s_waitcnt lgkmcnt(2)
	v_mfma_f32_16x16x32_bf16 v[98:101], v[192:195], v[162:165], v[98:101]
	v_mfma_f32_16x16x32_bf16 v[66:69], v[200:203], v[162:165], v[66:69]
	v_mfma_f32_16x16x32_bf16 v[34:37], v[208:211], v[162:165], v[34:37]
	v_mfma_f32_16x16x32_bf16 v[10:13], v[216:219], v[162:165], v[10:13]
	v_mfma_f32_16x16x32_bf16 v[98:101], v[196:199], v[166:169], v[98:101]
	v_mfma_f32_16x16x32_bf16 v[66:69], v[204:207], v[166:169], v[66:69]
	v_mfma_f32_16x16x32_bf16 v[34:37], v[212:215], v[166:169], v[34:37]
	v_mfma_f32_16x16x32_bf16 v[10:13], v[220:223], v[166:169], v[10:13]
	ds_read_b128 v[162:165], v229 offset:14336
	ds_read_b128 v[166:169], v230 offset:14336
	s_waitcnt lgkmcnt(2)
	v_mfma_f32_16x16x32_bf16 v[94:97], v[192:195], v[154:157], v[94:97]
	v_mfma_f32_16x16x32_bf16 v[62:65], v[200:203], v[154:157], v[62:65]
	v_mfma_f32_16x16x32_bf16 v[30:33], v[208:211], v[154:157], v[30:33]
	v_mfma_f32_16x16x32_bf16 v[6:9], v[216:219], v[154:157], v[6:9]
	v_mfma_f32_16x16x32_bf16 v[94:97], v[196:199], v[158:161], v[94:97]
	v_mfma_f32_16x16x32_bf16 v[62:65], v[204:207], v[158:161], v[62:65]
	v_mfma_f32_16x16x32_bf16 v[30:33], v[212:215], v[158:161], v[30:33]
	v_mfma_f32_16x16x32_bf16 v[6:9], v[220:223], v[158:161], v[6:9]
	s_waitcnt lgkmcnt(0)
	v_mfma_f32_16x16x32_bf16 v[82:85], v[192:195], v[162:165], v[82:85]
	v_mfma_f32_16x16x32_bf16 v[50:53], v[200:203], v[162:165], v[50:53]
	v_mfma_f32_16x16x32_bf16 v[22:25], v[208:211], v[162:165], v[22:25]
	v_mfma_f32_16x16x32_bf16 v[2:5], v[216:219], v[162:165], v[2:5]
	v_mfma_f32_16x16x32_bf16 v[82:85], v[196:199], v[166:169], v[82:85]
	v_mfma_f32_16x16x32_bf16 v[50:53], v[204:207], v[166:169], v[50:53]
	v_mfma_f32_16x16x32_bf16 v[22:25], v[212:215], v[166:169], v[22:25]
	v_mfma_f32_16x16x32_bf16 v[2:5], v[220:223], v[166:169], v[2:5]
	s_nop 7
	s_nop 7
	s_waitcnt vmcnt(6)
	v_add_u32_e32 v145, v149, v147
	s_waitcnt vmcnt(0)
	s_waitcnt lgkmcnt(0)
	s_lshl_b32 s18, s16, 7
	s_ashr_i32 s19, s18, 31
	s_lshl_b64 s[18:19], s[18:19], 1
	v_and_b32_e32 v1, 0xfffffc0, v1
	v_lshl_or_b32 v1, v143, 2, v1
	v_mul_lo_u32 v1, v1, s33
	v_lshl_or_b32 v1, v142, 2, v1
	s_lshl_b32 s16, s16, 1
	s_ashr_i32 s17, s16, 31
	s_lshl_b64 s[16:17], s[16:17], 2
	s_add_i32 s24, s24, 1
	v_mov_b64_e32 v[162:163], v[62:63]
	v_mov_b64_e32 v[164:165], v[64:65]
	v_mov_b64_e32 v[166:167], v[30:31]
	v_mov_b64_e32 v[168:169], v[32:33]
	v_mov_b64_e32 v[130:131], v[22:23]
	v_mov_b64_e32 v[132:133], v[24:25]
	s_waitcnt lgkmcnt(0)
	v_mov_b64_e32 v[232:233], v[38:39]
	v_mov_b64_e32 v[234:235], v[40:41]
	v_mov_b64_e32 v[38:39], v[34:35]
	v_mov_b64_e32 v[40:41], v[36:37]
	v_mov_b64_e32 v[34:35], v[2:3]
	v_mov_b64_e32 v[36:37], v[4:5]
	s_nop 2
	v_mov_b32_e32 v2, v170
	v_mov_b64_e32 v[216:217], v[114:115]
	v_mov_b64_e32 v[218:219], v[116:117]
	v_add_u32_e32 v2, s4, v2
	v_ashrrev_i32_e32 v3, 31, v2
	v_lshlrev_b64 v[2:3], 11, v[2:3]
	v_lshl_add_u64 v[2:3], s[8:9], 0, v[2:3]
	v_lshl_add_u64 v[2:3], v[2:3], 0, s[18:19]
	v_mov_b64_e32 v[220:221], v[54:55]
	v_mov_b64_e32 v[222:223], v[56:57]
	v_mov_b64_e32 v[224:225], v[122:123]
	v_mov_b64_e32 v[226:227], v[124:125]
	v_mov_b64_e32 v[228:229], v[102:103]
	v_mov_b64_e32 v[230:231], v[104:105]
	v_mov_b64_e32 v[236:237], v[118:119]
	v_mov_b64_e32 v[238:239], v[120:121]
	v_mov_b64_e32 v[240:241], v[58:59]
	v_mov_b64_e32 v[242:243], v[60:61]
	v_mov_b64_e32 v[244:245], v[26:27]
	v_mov_b64_e32 v[246:247], v[28:29]
	v_mov_b64_e32 v[248:249], v[110:111]
	v_mov_b64_e32 v[250:251], v[112:113]
	v_mov_b64_e32 v[180:181], v[78:79]
	v_mov_b64_e32 v[182:183], v[80:81]
	v_mov_b64_e32 v[154:155], v[46:47]
	v_mov_b64_e32 v[156:157], v[48:49]
	v_mov_b64_e32 v[62:63], v[106:107]
	v_mov_b64_e32 v[64:65], v[108:109]
	v_mov_b64_e32 v[46:47], v[74:75]
	v_mov_b64_e32 v[48:49], v[76:77]
	v_mov_b64_e32 v[74:75], v[98:99]
	v_mov_b64_e32 v[76:77], v[100:101]
	v_mov_b64_e32 v[54:55], v[66:67]
	v_mov_b64_e32 v[56:57], v[68:69]
	v_mov_b64_e32 v[58:59], v[162:163]
	v_mov_b64_e32 v[60:61], v[164:165]
	v_mov_b64_e32 v[66:67], v[50:51]
	v_mov_b64_e32 v[68:69], v[52:53]
	flat_load_dwordx4 v[138:141], v[2:3]
	flat_load_dwordx4 v[122:125], v[2:3] offset:16
	flat_load_dwordx4 v[118:121], v[2:3] offset:32
	flat_load_dwordx4 v[114:117], v[2:3] offset:48
	flat_load_dwordx4 v[110:113], v[2:3] offset:64
	flat_load_dwordx4 v[106:109], v[2:3] offset:80
	flat_load_dwordx4 v[102:105], v[2:3] offset:96
	flat_load_dwordx4 v[98:101], v[2:3] offset:112
	s_waitcnt vmcnt(0) lgkmcnt(0)
	s_barrier
	s_nop 7
	ds_write2_b32 v1, v126, v224 offset1:16
	ds_write2_b32 v1, v127, v225 offset0:68 offset1:84
	ds_write2_b32 v1, v128, v226 offset0:136 offset1:152
	ds_write2_b32 v1, v129, v227 offset0:204 offset1:220
	ds_write2_b32 v1, v236, v248 offset0:32 offset1:48
	ds_write2_b32 v1, v237, v249 offset0:100 offset1:116
	ds_write2_b32 v1, v238, v250 offset0:168 offset1:184
	ds_write2_b32 v1, v239, v251 offset0:236 offset1:252
	v_mov_b64_e32 v[196:197], v[18:19]
	v_mov_b64_e32 v[198:199], v[20:21]
	v_mov_b64_e32 v[78:79], v[94:95]
	v_mov_b64_e32 v[80:81], v[96:97]
	v_add_u32_e32 v135, 0x3000, v1
	v_add_u32_e32 v134, 0x3400, v1
	v_mov_b32_e32 v136, v170
	v_mov_b64_e32 v[50:51], v[130:131]
	v_mov_b64_e32 v[52:53], v[132:133]
	v_lshlrev_b32_e32 v137, 16, v138
	s_nop 1
	v_add_u32_e32 v130, 0x1000, v1
	v_add_u32_e32 v131, 0x1400, v1
	v_add_u32_e32 v132, 0x2000, v1
	v_add_u32_e32 v133, 0x2400, v1
	ds_write2_b32 v130, v216, v228 offset0:64 offset1:80
	ds_write2_b32 v130, v217, v229 offset0:132 offset1:148
	ds_write2_b32 v130, v218, v230 offset0:200 offset1:216
	ds_write2_b32 v131, v219, v231 offset0:12 offset1:28
	ds_write2_b32 v130, v90, v180 offset0:96 offset1:112
	ds_write2_b32 v130, v91, v181 offset0:164 offset1:180
	ds_write2_b32 v130, v92, v182 offset0:232 offset1:248
	ds_write2_b32 v131, v93, v183 offset0:44 offset1:60
	ds_write2_b32 v132, v86, v70 offset0:128 offset1:144
	ds_write2_b32 v132, v87, v71 offset0:196 offset1:212
	ds_write2_b32 v133, v88, v72 offset0:8 offset1:24
	ds_write2_b32 v133, v89, v73 offset0:76 offset1:92
	ds_write2_b32 v132, v240, v154 offset0:160 offset1:176
	ds_write2_b32 v132, v241, v155 offset0:228 offset1:244
	ds_write2_b32 v133, v242, v156 offset0:40 offset1:56
	ds_write2_b32 v133, v243, v157 offset0:108 offset1:124
	ds_write2_b32 v135, v220, v232 offset0:192 offset1:208
	ds_write2_b32 v134, v221, v233 offset0:4 offset1:20
	ds_write2_b32 v134, v222, v234 offset0:72 offset1:88
	ds_write2_b32 v134, v223, v235 offset0:140 offset1:156
	ds_write2_b32 v135, v244, v196 offset0:224 offset1:240
	ds_write2_b32 v134, v245, v197 offset0:36 offset1:52
	ds_write2_b32 v134, v246, v198 offset0:104 offset1:120
	ds_write2_b32 v134, v247, v199 offset0:172 offset1:188
	s_waitcnt lgkmcnt(0)
	s_barrier
	v_mov_b64_e32 v[18:19], v[14:15]
	v_mov_b64_e32 v[20:21], v[16:17]
	v_add_u32_e32 v126, s4, v136
	v_ashrrev_i32_e32 v127, 31, v126
	v_lshlrev_b64 v[2:3], 11, v[126:127]
	v_lshl_add_u64 v[2:3], s[8:9], 0, v[2:3]
	v_lshl_add_u64 v[128:129], v[2:3], 0, s[18:19]
	v_mul_lo_u32 v136, v136, s33
	v_mov_b64_e32 v[22:23], v[10:11]
	v_mov_b64_e32 v[24:25], v[12:13]
	v_and_b32_e32 v138, 0xffff0000, v138
	v_mov_b64_e32 v[26:27], v[6:7]
	v_mov_b64_e32 v[28:29], v[8:9]
	flat_load_dwordx4 v[94:97], v[128:129] offset:128
	flat_load_dwordx4 v[90:93], v[128:129] offset:144
	flat_load_dwordx4 v[86:89], v[128:129] offset:160
	flat_load_dwordx4 v[70:73], v[128:129] offset:176
	flat_load_dwordx4 v[14:17], v[128:129] offset:192
	flat_load_dwordx4 v[10:13], v[128:129] offset:208
	flat_load_dwordx4 v[6:9], v[128:129] offset:224
	flat_load_dwordx4 v[2:5], v[128:129] offset:240
	ds_read_b128 v[142:145], v136
	ds_read_b128 v[154:157], v136 offset:16
	s_waitcnt lgkmcnt(0)
	v_add_f32_e32 v137, v142, v137
	v_add_f32_e32 v138, v143, v138
	v_cvt_pk_bf16_f32 v138, v137, v138
	v_lshlrev_b32_e32 v137, 16, v139
	v_and_b32_e32 v139, 0xffff0000, v139
	v_add_f32_e32 v137, v144, v137
	v_add_f32_e32 v139, v145, v139
	v_cvt_pk_bf16_f32 v139, v137, v139
	v_lshlrev_b32_e32 v137, 16, v140
	v_and_b32_e32 v140, 0xffff0000, v140
	v_add_f32_e32 v137, v154, v137
	v_add_f32_e32 v140, v155, v140
	v_cvt_pk_bf16_f32 v140, v137, v140
	v_lshlrev_b32_e32 v137, 16, v141
	v_and_b32_e32 v141, 0xffff0000, v141
	v_add_f32_e32 v137, v156, v137
	v_add_f32_e32 v141, v157, v141
	v_and_b32_e32 v142, 0xffff0000, v138
	v_cvt_pk_bf16_f32 v141, v137, v141
	v_lshlrev_b32_e32 v137, 16, v138
	v_mul_f32_e32 v153, v142, v142
	v_lshlrev_b32_e32 v143, 16, v139
	v_fmac_f32_e32 v153, v137, v137
	v_and_b32_e32 v144, 0xffff0000, v139
	v_fmac_f32_e32 v153, v143, v143
	v_lshlrev_b32_e32 v145, 16, v140
	v_fmac_f32_e32 v153, v144, v144
	flat_store_dwordx4 v[128:129], v[138:141]
	v_and_b32_e32 v147, 0xffff0000, v140
	v_lshlrev_b32_e32 v149, 16, v141
	v_and_b32_e32 v151, 0xffff0000, v141
	v_fmac_f32_e32 v153, v145, v145
	ds_read_b128 v[138:141], v136 offset:32
	ds_read_b128 v[142:145], v136 offset:48
	v_lshlrev_b32_e32 v137, 16, v122
	v_and_b32_e32 v122, 0xffff0000, v122
	v_fmac_f32_e32 v153, v147, v147
	s_waitcnt lgkmcnt(0)
	v_add_f32_e32 v137, v138, v137
	v_add_f32_e32 v122, v139, v122
	v_cvt_pk_bf16_f32 v122, v137, v122
	v_lshlrev_b32_e32 v137, 16, v123
	v_and_b32_e32 v123, 0xffff0000, v123
	v_add_f32_e32 v137, v140, v137
	v_add_f32_e32 v123, v141, v123
	v_cvt_pk_bf16_f32 v123, v137, v123
	v_lshlrev_b32_e32 v137, 16, v124
	v_and_b32_e32 v124, 0xffff0000, v124
	v_add_f32_e32 v137, v142, v137
	v_add_f32_e32 v124, v143, v124
	v_cvt_pk_bf16_f32 v124, v137, v124
	v_lshlrev_b32_e32 v137, 16, v125
	v_and_b32_e32 v125, 0xffff0000, v125
	v_add_f32_e32 v137, v144, v137
	v_add_f32_e32 v125, v145, v125
	v_and_b32_e32 v138, 0xffff0000, v122
	v_cvt_pk_bf16_f32 v125, v137, v125
	v_lshlrev_b32_e32 v137, 16, v122
	v_mul_f32_e32 v138, v138, v138
	v_lshlrev_b32_e32 v139, 16, v123
	v_fmac_f32_e32 v138, v137, v137
	v_and_b32_e32 v140, 0xffff0000, v123
	v_fmac_f32_e32 v138, v139, v139
	v_lshlrev_b32_e32 v141, 16, v124
	v_fmac_f32_e32 v138, v140, v140
	v_and_b32_e32 v142, 0xffff0000, v124
	v_fmac_f32_e32 v138, v141, v141
	v_lshlrev_b32_e32 v143, 16, v125
	v_fmac_f32_e32 v138, v142, v142
	v_fmac_f32_e32 v153, v149, v149
	v_and_b32_e32 v144, 0xffff0000, v125
	v_fmac_f32_e32 v138, v143, v143
	v_fmac_f32_e32 v153, v151, v151
	v_fmac_f32_e32 v138, v144, v144
	flat_store_dwordx4 v[128:129], v[122:125] offset:16
	v_add_f32_e32 v137, v153, v138
	ds_read_b128 v[122:125], v136 offset:64
	ds_read_b128 v[138:141], v136 offset:80
	v_lshlrev_b32_e32 v142, 16, v118
	v_and_b32_e32 v118, 0xffff0000, v118
	v_mov_b64_e32 v[30:31], v[42:43]
	v_mov_b64_e32 v[32:33], v[44:45]
	s_waitcnt lgkmcnt(0)
	v_add_f32_e32 v122, v122, v142
	v_add_f32_e32 v118, v123, v118
	v_cvt_pk_bf16_f32 v118, v122, v118
	v_lshlrev_b32_e32 v122, 16, v119
	v_and_b32_e32 v119, 0xffff0000, v119
	v_add_f32_e32 v122, v124, v122
	v_add_f32_e32 v119, v125, v119
	v_cvt_pk_bf16_f32 v119, v122, v119
	v_lshlrev_b32_e32 v122, 16, v120
	v_and_b32_e32 v120, 0xffff0000, v120
	v_add_f32_e32 v122, v138, v122
	v_add_f32_e32 v120, v139, v120
	v_cvt_pk_bf16_f32 v120, v122, v120
	v_lshlrev_b32_e32 v122, 16, v121
	v_and_b32_e32 v121, 0xffff0000, v121
	v_add_f32_e32 v122, v140, v122
	v_add_f32_e32 v121, v141, v121
	v_and_b32_e32 v123, 0xffff0000, v118
	v_cvt_pk_bf16_f32 v121, v122, v121
	v_lshlrev_b32_e32 v122, 16, v118
	v_mul_f32_e32 v123, v123, v123
	v_lshlrev_b32_e32 v124, 16, v119
	v_fmac_f32_e32 v123, v122, v122
	v_and_b32_e32 v125, 0xffff0000, v119
	v_fmac_f32_e32 v123, v124, v124
	v_lshlrev_b32_e32 v138, 16, v120
	v_fmac_f32_e32 v123, v125, v125
	v_and_b32_e32 v139, 0xffff0000, v120
	v_fmac_f32_e32 v123, v138, v138
	v_lshlrev_b32_e32 v140, 16, v121
	v_fmac_f32_e32 v123, v139, v139
	v_and_b32_e32 v141, 0xffff0000, v121
	v_fmac_f32_e32 v123, v140, v140
	v_fmac_f32_e32 v123, v141, v141
	flat_store_dwordx4 v[128:129], v[118:121] offset:32
	v_add_f32_e32 v137, v137, v123
	ds_read_b128 v[118:121], v136 offset:96
	ds_read_b128 v[122:125], v136 offset:112
	v_lshlrev_b32_e32 v138, 16, v114
	v_and_b32_e32 v114, 0xffff0000, v114
	v_mov_b64_e32 v[42:43], v[166:167]
	v_mov_b64_e32 v[44:45], v[168:169]
	s_waitcnt lgkmcnt(0)
	v_add_f32_e32 v118, v118, v138
	v_add_f32_e32 v114, v119, v114
	v_cvt_pk_bf16_f32 v114, v118, v114
	v_lshlrev_b32_e32 v118, 16, v115
	v_and_b32_e32 v115, 0xffff0000, v115
	v_add_f32_e32 v118, v120, v118
	v_add_f32_e32 v115, v121, v115
	v_cvt_pk_bf16_f32 v115, v118, v115
	v_lshlrev_b32_e32 v118, 16, v116
	v_and_b32_e32 v116, 0xffff0000, v116
	v_add_f32_e32 v118, v122, v118
	v_add_f32_e32 v116, v123, v116
	v_cvt_pk_bf16_f32 v116, v118, v116
	v_lshlrev_b32_e32 v118, 16, v117
	v_and_b32_e32 v117, 0xffff0000, v117
	v_add_f32_e32 v118, v124, v118
	v_add_f32_e32 v117, v125, v117
	v_and_b32_e32 v119, 0xffff0000, v114
	v_cvt_pk_bf16_f32 v117, v118, v117
	v_lshlrev_b32_e32 v118, 16, v114
	v_mul_f32_e32 v119, v119, v119
	v_lshlrev_b32_e32 v120, 16, v115
	v_fmac_f32_e32 v119, v118, v118
	v_and_b32_e32 v121, 0xffff0000, v115
	v_fmac_f32_e32 v119, v120, v120
	v_lshlrev_b32_e32 v122, 16, v116
	v_fmac_f32_e32 v119, v121, v121
	v_and_b32_e32 v123, 0xffff0000, v116
	v_fmac_f32_e32 v119, v122, v122
	v_lshlrev_b32_e32 v124, 16, v117
	v_fmac_f32_e32 v119, v123, v123
	v_and_b32_e32 v125, 0xffff0000, v117
	v_fmac_f32_e32 v119, v124, v124
	v_fmac_f32_e32 v119, v125, v125
	flat_store_dwordx4 v[128:129], v[114:117] offset:48
	v_add_f32_e32 v122, v137, v119
	ds_read_b128 v[114:117], v136 offset:128
	ds_read_b128 v[118:121], v136 offset:144
	v_lshlrev_b32_e32 v123, 16, v110
	v_and_b32_e32 v110, 0xffff0000, v110
	s_waitcnt lgkmcnt(0)
	v_add_f32_e32 v114, v114, v123
	v_add_f32_e32 v110, v115, v110
	v_cvt_pk_bf16_f32 v110, v114, v110
	v_lshlrev_b32_e32 v114, 16, v111
	v_and_b32_e32 v111, 0xffff0000, v111
	v_add_f32_e32 v114, v116, v114
	v_add_f32_e32 v111, v117, v111
	v_cvt_pk_bf16_f32 v111, v114, v111
	v_lshlrev_b32_e32 v114, 16, v112
	v_and_b32_e32 v112, 0xffff0000, v112
	v_add_f32_e32 v114, v118, v114
	v_add_f32_e32 v112, v119, v112
	v_cvt_pk_bf16_f32 v112, v114, v112
	v_lshlrev_b32_e32 v114, 16, v113
	v_and_b32_e32 v113, 0xffff0000, v113
	v_add_f32_e32 v114, v120, v114
	v_add_f32_e32 v113, v121, v113
	v_and_b32_e32 v115, 0xffff0000, v110
	v_cvt_pk_bf16_f32 v113, v114, v113
	v_lshlrev_b32_e32 v114, 16, v110
	v_mul_f32_e32 v115, v115, v115
	v_lshlrev_b32_e32 v116, 16, v111
	v_fmac_f32_e32 v115, v114, v114
	v_and_b32_e32 v117, 0xffff0000, v111
	v_fmac_f32_e32 v115, v116, v116
	v_lshlrev_b32_e32 v118, 16, v112
	v_fmac_f32_e32 v115, v117, v117
	v_and_b32_e32 v119, 0xffff0000, v112
	v_fmac_f32_e32 v115, v118, v118
	v_lshlrev_b32_e32 v120, 16, v113
	v_fmac_f32_e32 v115, v119, v119
	v_and_b32_e32 v121, 0xffff0000, v113
	v_fmac_f32_e32 v115, v120, v120
	v_fmac_f32_e32 v115, v121, v121
	flat_store_dwordx4 v[128:129], v[110:113] offset:64
	v_add_f32_e32 v118, v122, v115
	ds_read_b128 v[110:113], v136 offset:160
	ds_read_b128 v[114:117], v136 offset:176
	v_lshlrev_b32_e32 v119, 16, v106
	v_and_b32_e32 v106, 0xffff0000, v106
	s_waitcnt lgkmcnt(0)
	v_add_f32_e32 v110, v110, v119
	v_add_f32_e32 v106, v111, v106
	v_cvt_pk_bf16_f32 v106, v110, v106
	v_lshlrev_b32_e32 v110, 16, v107
	v_and_b32_e32 v107, 0xffff0000, v107
	v_add_f32_e32 v110, v112, v110
	v_add_f32_e32 v107, v113, v107
	v_cvt_pk_bf16_f32 v107, v110, v107
	v_lshlrev_b32_e32 v110, 16, v108
	v_and_b32_e32 v108, 0xffff0000, v108
	v_add_f32_e32 v110, v114, v110
	v_add_f32_e32 v108, v115, v108
	v_cvt_pk_bf16_f32 v108, v110, v108
	v_lshlrev_b32_e32 v110, 16, v109
	v_and_b32_e32 v109, 0xffff0000, v109
	v_add_f32_e32 v110, v116, v110
	v_add_f32_e32 v109, v117, v109
	v_and_b32_e32 v111, 0xffff0000, v106
	v_cvt_pk_bf16_f32 v109, v110, v109
	v_lshlrev_b32_e32 v110, 16, v106
	v_mul_f32_e32 v111, v111, v111
	v_lshlrev_b32_e32 v112, 16, v107
	v_fmac_f32_e32 v111, v110, v110
	v_and_b32_e32 v113, 0xffff0000, v107
	v_fmac_f32_e32 v111, v112, v112
	v_lshlrev_b32_e32 v114, 16, v108
	v_fmac_f32_e32 v111, v113, v113
	v_and_b32_e32 v115, 0xffff0000, v108
	v_fmac_f32_e32 v111, v114, v114
	v_lshlrev_b32_e32 v116, 16, v109
	v_fmac_f32_e32 v111, v115, v115
	v_and_b32_e32 v117, 0xffff0000, v109
	v_fmac_f32_e32 v111, v116, v116
	v_fmac_f32_e32 v111, v117, v117
	flat_store_dwordx4 v[128:129], v[106:109] offset:80
	v_add_f32_e32 v114, v118, v111
	ds_read_b128 v[106:109], v136 offset:192
	ds_read_b128 v[110:113], v136 offset:208
	v_lshlrev_b32_e32 v115, 16, v102
	v_and_b32_e32 v102, 0xffff0000, v102
	s_waitcnt lgkmcnt(0)
	v_add_f32_e32 v106, v106, v115
	v_add_f32_e32 v102, v107, v102
	v_cvt_pk_bf16_f32 v102, v106, v102
	v_lshlrev_b32_e32 v106, 16, v103
	v_and_b32_e32 v103, 0xffff0000, v103
	v_add_f32_e32 v106, v108, v106
	v_add_f32_e32 v103, v109, v103
	v_cvt_pk_bf16_f32 v103, v106, v103
	v_lshlrev_b32_e32 v106, 16, v104
	v_and_b32_e32 v104, 0xffff0000, v104
	v_add_f32_e32 v106, v110, v106
	v_add_f32_e32 v104, v111, v104
	v_cvt_pk_bf16_f32 v104, v106, v104
	v_lshlrev_b32_e32 v106, 16, v105
	v_and_b32_e32 v105, 0xffff0000, v105
	v_add_f32_e32 v106, v112, v106
	v_add_f32_e32 v105, v113, v105
	v_and_b32_e32 v107, 0xffff0000, v102
	v_cvt_pk_bf16_f32 v105, v106, v105
	v_lshlrev_b32_e32 v106, 16, v102
	v_mul_f32_e32 v107, v107, v107
	v_lshlrev_b32_e32 v108, 16, v103
	v_fmac_f32_e32 v107, v106, v106
	v_and_b32_e32 v109, 0xffff0000, v103
	v_fmac_f32_e32 v107, v108, v108
	v_lshlrev_b32_e32 v110, 16, v104
	v_fmac_f32_e32 v107, v109, v109
	v_and_b32_e32 v111, 0xffff0000, v104
	v_fmac_f32_e32 v107, v110, v110
	v_lshlrev_b32_e32 v112, 16, v105
	v_fmac_f32_e32 v107, v111, v111
	v_and_b32_e32 v113, 0xffff0000, v105
	v_fmac_f32_e32 v107, v112, v112
	v_fmac_f32_e32 v107, v113, v113
	flat_store_dwordx4 v[128:129], v[102:105] offset:96
	v_add_f32_e32 v110, v114, v107
	ds_read_b128 v[102:105], v136 offset:224
	ds_read_b128 v[106:109], v136 offset:240
	v_lshlrev_b32_e32 v111, 16, v98
	v_and_b32_e32 v98, 0xffff0000, v98
	s_waitcnt lgkmcnt(0)
	v_add_f32_e32 v102, v102, v111
	v_add_f32_e32 v98, v103, v98
	v_cvt_pk_bf16_f32 v98, v102, v98
	v_lshlrev_b32_e32 v102, 16, v99
	v_and_b32_e32 v99, 0xffff0000, v99
	v_add_f32_e32 v102, v104, v102
	v_add_f32_e32 v99, v105, v99
	v_cvt_pk_bf16_f32 v99, v102, v99
	v_lshlrev_b32_e32 v102, 16, v100
	v_and_b32_e32 v100, 0xffff0000, v100
	v_add_f32_e32 v102, v106, v102
	v_add_f32_e32 v100, v107, v100
	v_cvt_pk_bf16_f32 v100, v102, v100
	v_lshlrev_b32_e32 v102, 16, v101
	v_and_b32_e32 v101, 0xffff0000, v101
	v_add_f32_e32 v102, v108, v102
	v_add_f32_e32 v101, v109, v101
	v_and_b32_e32 v103, 0xffff0000, v98
	v_cvt_pk_bf16_f32 v101, v102, v101
	v_lshlrev_b32_e32 v102, 16, v98
	v_mul_f32_e32 v103, v103, v103
	v_lshlrev_b32_e32 v104, 16, v99
	v_fmac_f32_e32 v103, v102, v102
	v_and_b32_e32 v105, 0xffff0000, v99
	v_fmac_f32_e32 v103, v104, v104
	v_lshlrev_b32_e32 v106, 16, v100
	v_fmac_f32_e32 v103, v105, v105
	v_and_b32_e32 v107, 0xffff0000, v100
	v_fmac_f32_e32 v103, v106, v106
	v_lshlrev_b32_e32 v108, 16, v101
	v_fmac_f32_e32 v103, v107, v107
	v_and_b32_e32 v109, 0xffff0000, v101
	v_fmac_f32_e32 v103, v108, v108
	flat_store_dwordx4 v[128:129], v[98:101] offset:112
	v_fmac_f32_e32 v103, v109, v109
	v_add_f32_e32 v102, v110, v103
	v_lshlrev_b64 v[98:99], 6, v[126:127]
	v_lshl_add_u64 v[98:99], s[6:7], 0, v[98:99]
	v_lshl_add_u64 v[98:99], v[98:99], 0, s[16:17]
	flat_store_dword v[98:99], v102
	s_waitcnt lgkmcnt(0)
	s_barrier
	ds_write2_b32 v1, v62, v74 offset1:16
	ds_write2_b32 v1, v63, v75 offset0:68 offset1:84
	ds_write2_b32 v1, v64, v76 offset0:136 offset1:152
	ds_write2_b32 v1, v65, v77 offset0:204 offset1:220
	ds_write2_b32 v1, v78, v82 offset0:32 offset1:48
	ds_write2_b32 v1, v79, v83 offset0:100 offset1:116
	ds_write2_b32 v1, v80, v84 offset0:168 offset1:184
	ds_write2_b32 v1, v81, v85 offset0:236 offset1:252
	ds_write2_b32 v130, v46, v54 offset0:64 offset1:80
	ds_write2_b32 v130, v47, v55 offset0:132 offset1:148
	ds_write2_b32 v130, v48, v56 offset0:200 offset1:216
	ds_write2_b32 v131, v49, v57 offset0:12 offset1:28
	ds_write2_b32 v130, v58, v66 offset0:96 offset1:112
	ds_write2_b32 v130, v59, v67 offset0:164 offset1:180
	ds_write2_b32 v130, v60, v68 offset0:232 offset1:248
	ds_write2_b32 v131, v61, v69 offset0:44 offset1:60
	ds_write2_b32 v132, v30, v38 offset0:128 offset1:144
	ds_write2_b32 v132, v31, v39 offset0:196 offset1:212
	ds_write2_b32 v133, v32, v40 offset0:8 offset1:24
	ds_write2_b32 v133, v33, v41 offset0:76 offset1:92
	ds_write2_b32 v132, v42, v50 offset0:160 offset1:176
	ds_write2_b32 v132, v43, v51 offset0:228 offset1:244
	ds_write2_b32 v133, v44, v52 offset0:40 offset1:56
	ds_write2_b32 v133, v45, v53 offset0:108 offset1:124
	ds_write2_b32 v135, v18, v22 offset0:192 offset1:208
	ds_write2_b32 v134, v19, v23 offset0:4 offset1:20
	ds_write2_b32 v134, v20, v24 offset0:72 offset1:88
	ds_write2_b32 v134, v21, v25 offset0:140 offset1:156
	ds_write2_b32 v135, v26, v34 offset0:224 offset1:240
	ds_write2_b32 v134, v27, v35 offset0:36 offset1:52
	ds_write2_b32 v134, v28, v36 offset0:104 offset1:120
	ds_write2_b32 v134, v29, v37 offset0:172 offset1:188
	v_mov_b32_e32 v1, v170
	s_waitcnt lgkmcnt(0)
	s_barrier
	s_waitcnt vmcnt(0)
	v_lshlrev_b32_e32 v28, 16, v94
	v_add_u32_e32 v18, s4, v1
	v_ashrrev_i32_e32 v19, 31, v18
	v_lshlrev_b64 v[20:21], 11, v[18:19]
	v_lshl_add_u64 v[20:21], s[38:39], 0, v[20:21]
	v_mul_lo_u32 v1, v1, s33
	v_lshl_add_u64 v[32:33], v[20:21], 0, s[18:19]
	ds_read_b128 v[20:23], v1
	ds_read_b128 v[24:27], v1 offset:16
	s_mov_b64 s[4:5], 0
	s_waitcnt lgkmcnt(1)
	v_add_f32_e32 v20, v20, v28
	v_and_b32_e32 v28, 0xffff0000, v94
	v_add_f32_e32 v21, v21, v28
	v_cvt_pk_bf16_f32 v28, v20, v21
	v_and_b32_e32 v21, 0xffff0000, v95
	v_lshlrev_b32_e32 v20, 16, v95
	v_add_f32_e32 v21, v23, v21
	v_add_f32_e32 v20, v22, v20
	v_cvt_pk_bf16_f32 v29, v20, v21
	v_and_b32_e32 v21, 0xffff0000, v96
	v_lshlrev_b32_e32 v20, 16, v96
	s_waitcnt lgkmcnt(0)
	v_add_f32_e32 v21, v25, v21
	v_add_f32_e32 v20, v24, v20
	v_cvt_pk_bf16_f32 v30, v20, v21
	v_and_b32_e32 v21, 0xffff0000, v97
	v_lshlrev_b32_e32 v20, 16, v97
	v_add_f32_e32 v21, v27, v21
	v_add_f32_e32 v20, v26, v20
	v_cvt_pk_bf16_f32 v31, v20, v21
	v_and_b32_e32 v21, 0xffff0000, v28
	v_lshlrev_b32_e32 v20, 16, v28
	v_mul_f32_e32 v34, v21, v21
	v_lshlrev_b32_e32 v22, 16, v29
	v_fmac_f32_e32 v34, v20, v20
	v_and_b32_e32 v23, 0xffff0000, v29
	v_fmac_f32_e32 v34, v22, v22
	v_lshlrev_b32_e32 v24, 16, v30
	v_fmac_f32_e32 v34, v23, v23
	v_and_b32_e32 v25, 0xffff0000, v30
	v_fmac_f32_e32 v34, v24, v24
	v_add_co_u32_e32 v20, vcc, s90, v32
	v_lshlrev_b32_e32 v26, 16, v31
	v_fmac_f32_e32 v34, v25, v25
	v_addc_co_u32_e32 v21, vcc, 0, v33, vcc
	v_and_b32_e32 v27, 0xffff0000, v31
	v_fmac_f32_e32 v34, v26, v26
	flat_store_dwordx4 v[20:21], v[28:31] offset:128
	v_fmac_f32_e32 v34, v27, v27
	ds_read_b128 v[22:25], v1 offset:32
	ds_read_b128 v[26:29], v1 offset:48
	v_lshlrev_b32_e32 v30, 16, v90
	s_waitcnt lgkmcnt(0)
	v_add_f32_e32 v22, v22, v30
	v_and_b32_e32 v30, 0xffff0000, v90
	v_add_f32_e32 v23, v23, v30
	v_cvt_pk_bf16_f32 v22, v22, v23
	v_lshlrev_b32_e32 v23, 16, v91
	v_add_f32_e32 v23, v24, v23
	v_and_b32_e32 v24, 0xffff0000, v91
	v_add_f32_e32 v24, v25, v24
	v_cvt_pk_bf16_f32 v23, v23, v24
	v_lshlrev_b32_e32 v24, 16, v92
	v_and_b32_e32 v25, 0xffff0000, v92
	v_add_f32_e32 v24, v26, v24
	v_add_f32_e32 v25, v27, v25
	v_cvt_pk_bf16_f32 v24, v24, v25
	v_lshlrev_b32_e32 v25, 16, v93
	v_and_b32_e32 v26, 0xffff0000, v93
	v_add_f32_e32 v25, v28, v25
	v_add_f32_e32 v26, v29, v26
	v_and_b32_e32 v27, 0xffff0000, v22
	v_cvt_pk_bf16_f32 v25, v25, v26
	v_lshlrev_b32_e32 v26, 16, v22
	v_mul_f32_e32 v27, v27, v27
	v_lshlrev_b32_e32 v28, 16, v23
	v_fmac_f32_e32 v27, v26, v26
	v_and_b32_e32 v29, 0xffff0000, v23
	v_fmac_f32_e32 v27, v28, v28
	v_lshlrev_b32_e32 v30, 16, v24
	v_fmac_f32_e32 v27, v29, v29
	v_and_b32_e32 v31, 0xffff0000, v24
	v_fmac_f32_e32 v27, v30, v30
	v_lshlrev_b32_e32 v32, 16, v25
	v_fmac_f32_e32 v27, v31, v31
	v_and_b32_e32 v33, 0xffff0000, v25
	v_fmac_f32_e32 v27, v32, v32
	v_fmac_f32_e32 v27, v33, v33
	flat_store_dwordx4 v[20:21], v[22:25] offset:144
	v_add_f32_e32 v30, v34, v27
	ds_read_b128 v[22:25], v1 offset:64
	ds_read_b128 v[26:29], v1 offset:80
	v_lshlrev_b32_e32 v31, 16, v86
	s_waitcnt lgkmcnt(0)
	v_add_f32_e32 v22, v22, v31
	v_and_b32_e32 v31, 0xffff0000, v86
	v_add_f32_e32 v23, v23, v31
	v_cvt_pk_bf16_f32 v22, v22, v23
	v_lshlrev_b32_e32 v23, 16, v87
	v_add_f32_e32 v23, v24, v23
	v_and_b32_e32 v24, 0xffff0000, v87
	v_add_f32_e32 v24, v25, v24
	v_cvt_pk_bf16_f32 v23, v23, v24
	v_lshlrev_b32_e32 v24, 16, v88
	v_and_b32_e32 v25, 0xffff0000, v88
	v_add_f32_e32 v24, v26, v24
	v_add_f32_e32 v25, v27, v25
	v_cvt_pk_bf16_f32 v24, v24, v25
	v_lshlrev_b32_e32 v25, 16, v89
	v_and_b32_e32 v26, 0xffff0000, v89
	v_add_f32_e32 v25, v28, v25
	v_add_f32_e32 v26, v29, v26
	v_and_b32_e32 v27, 0xffff0000, v22
	v_cvt_pk_bf16_f32 v25, v25, v26
	v_lshlrev_b32_e32 v26, 16, v22
	v_mul_f32_e32 v27, v27, v27
	v_lshlrev_b32_e32 v28, 16, v23
	v_fmac_f32_e32 v27, v26, v26
	v_and_b32_e32 v29, 0xffff0000, v23
	v_fmac_f32_e32 v27, v28, v28
	v_lshlrev_b32_e32 v31, 16, v24
	v_fmac_f32_e32 v27, v29, v29
	v_and_b32_e32 v32, 0xffff0000, v24
	v_fmac_f32_e32 v27, v31, v31
	v_lshlrev_b32_e32 v33, 16, v25
	v_fmac_f32_e32 v27, v32, v32
	v_and_b32_e32 v34, 0xffff0000, v25
	v_fmac_f32_e32 v27, v33, v33
	v_fmac_f32_e32 v27, v34, v34
	flat_store_dwordx4 v[20:21], v[22:25] offset:160
	v_add_f32_e32 v30, v30, v27
	ds_read_b128 v[22:25], v1 offset:96
	ds_read_b128 v[26:29], v1 offset:112
	v_lshlrev_b32_e32 v31, 16, v70
	s_waitcnt lgkmcnt(0)
	v_add_f32_e32 v22, v22, v31
	v_and_b32_e32 v31, 0xffff0000, v70
	v_add_f32_e32 v23, v23, v31
	v_cvt_pk_bf16_f32 v22, v22, v23
	v_lshlrev_b32_e32 v23, 16, v71
	v_add_f32_e32 v23, v24, v23
	v_and_b32_e32 v24, 0xffff0000, v71
	v_add_f32_e32 v24, v25, v24
	v_cvt_pk_bf16_f32 v23, v23, v24
	v_lshlrev_b32_e32 v24, 16, v72
	v_and_b32_e32 v25, 0xffff0000, v72
	v_add_f32_e32 v24, v26, v24
	v_add_f32_e32 v25, v27, v25
	v_cvt_pk_bf16_f32 v24, v24, v25
	v_lshlrev_b32_e32 v25, 16, v73
	v_and_b32_e32 v26, 0xffff0000, v73
	v_add_f32_e32 v25, v28, v25
	v_add_f32_e32 v26, v29, v26
	v_and_b32_e32 v27, 0xffff0000, v22
	v_cvt_pk_bf16_f32 v25, v25, v26
	v_lshlrev_b32_e32 v26, 16, v22
	v_mul_f32_e32 v27, v27, v27
	v_lshlrev_b32_e32 v28, 16, v23
	v_fmac_f32_e32 v27, v26, v26
	v_and_b32_e32 v29, 0xffff0000, v23
	v_fmac_f32_e32 v27, v28, v28
	v_lshlrev_b32_e32 v31, 16, v24
	v_fmac_f32_e32 v27, v29, v29
	v_and_b32_e32 v32, 0xffff0000, v24
	v_fmac_f32_e32 v27, v31, v31
	v_lshlrev_b32_e32 v33, 16, v25
	v_fmac_f32_e32 v27, v32, v32
	v_and_b32_e32 v34, 0xffff0000, v25
	v_fmac_f32_e32 v27, v33, v33
	v_fmac_f32_e32 v27, v34, v34
	flat_store_dwordx4 v[20:21], v[22:25] offset:176
	v_add_f32_e32 v30, v30, v27
	ds_read_b128 v[22:25], v1 offset:128
	ds_read_b128 v[26:29], v1 offset:144
	v_lshlrev_b32_e32 v31, 16, v14
	v_and_b32_e32 v14, 0xffff0000, v14
	s_waitcnt lgkmcnt(0)
	v_add_f32_e32 v22, v22, v31
	v_add_f32_e32 v14, v23, v14
	v_cvt_pk_bf16_f32 v14, v22, v14
	v_lshlrev_b32_e32 v22, 16, v15
	v_and_b32_e32 v15, 0xffff0000, v15
	v_add_f32_e32 v22, v24, v22
	v_add_f32_e32 v15, v25, v15
	v_cvt_pk_bf16_f32 v15, v22, v15
	v_lshlrev_b32_e32 v22, 16, v16
	v_and_b32_e32 v16, 0xffff0000, v16
	v_add_f32_e32 v22, v26, v22
	v_add_f32_e32 v16, v27, v16
	v_cvt_pk_bf16_f32 v16, v22, v16
	v_lshlrev_b32_e32 v22, 16, v17
	v_and_b32_e32 v17, 0xffff0000, v17
	v_add_f32_e32 v22, v28, v22
	v_add_f32_e32 v17, v29, v17
	v_and_b32_e32 v23, 0xffff0000, v14
	v_cvt_pk_bf16_f32 v17, v22, v17
	v_lshlrev_b32_e32 v22, 16, v14
	v_mul_f32_e32 v23, v23, v23
	v_lshlrev_b32_e32 v24, 16, v15
	v_fmac_f32_e32 v23, v22, v22
	v_and_b32_e32 v25, 0xffff0000, v15
	v_fmac_f32_e32 v23, v24, v24
	v_lshlrev_b32_e32 v26, 16, v16
	v_fmac_f32_e32 v23, v25, v25
	v_and_b32_e32 v27, 0xffff0000, v16
	v_fmac_f32_e32 v23, v26, v26
	v_lshlrev_b32_e32 v28, 16, v17
	v_fmac_f32_e32 v23, v27, v27
	v_and_b32_e32 v29, 0xffff0000, v17
	v_fmac_f32_e32 v23, v28, v28
	v_fmac_f32_e32 v23, v29, v29
	flat_store_dwordx4 v[20:21], v[14:17] offset:192
	v_add_f32_e32 v26, v30, v23
	ds_read_b128 v[14:17], v1 offset:160
	ds_read_b128 v[22:25], v1 offset:176
	v_lshlrev_b32_e32 v27, 16, v10
	v_and_b32_e32 v10, 0xffff0000, v10
	s_waitcnt lgkmcnt(0)
	v_add_f32_e32 v14, v14, v27
	v_add_f32_e32 v10, v15, v10
	v_cvt_pk_bf16_f32 v10, v14, v10
	v_lshlrev_b32_e32 v14, 16, v11
	v_and_b32_e32 v11, 0xffff0000, v11
	v_add_f32_e32 v14, v16, v14
	v_add_f32_e32 v11, v17, v11
	v_cvt_pk_bf16_f32 v11, v14, v11
	v_lshlrev_b32_e32 v14, 16, v12
	v_and_b32_e32 v12, 0xffff0000, v12
	v_add_f32_e32 v14, v22, v14
	v_add_f32_e32 v12, v23, v12
	v_cvt_pk_bf16_f32 v12, v14, v12
	v_lshlrev_b32_e32 v14, 16, v13
	v_and_b32_e32 v13, 0xffff0000, v13
	v_add_f32_e32 v14, v24, v14
	v_add_f32_e32 v13, v25, v13
	v_and_b32_e32 v15, 0xffff0000, v10
	v_cvt_pk_bf16_f32 v13, v14, v13
	v_lshlrev_b32_e32 v14, 16, v10
	v_mul_f32_e32 v15, v15, v15
	v_lshlrev_b32_e32 v16, 16, v11
	v_fmac_f32_e32 v15, v14, v14
	v_and_b32_e32 v17, 0xffff0000, v11
	v_fmac_f32_e32 v15, v16, v16
	v_lshlrev_b32_e32 v22, 16, v12
	v_fmac_f32_e32 v15, v17, v17
	v_and_b32_e32 v23, 0xffff0000, v12
	v_fmac_f32_e32 v15, v22, v22
	v_lshlrev_b32_e32 v24, 16, v13
	v_fmac_f32_e32 v15, v23, v23
	v_and_b32_e32 v25, 0xffff0000, v13
	v_fmac_f32_e32 v15, v24, v24
	v_fmac_f32_e32 v15, v25, v25
	flat_store_dwordx4 v[20:21], v[10:13] offset:208
	v_add_f32_e32 v22, v26, v15
	ds_read_b128 v[10:13], v1 offset:192
	ds_read_b128 v[14:17], v1 offset:208
	v_lshlrev_b32_e32 v23, 16, v6
	v_and_b32_e32 v6, 0xffff0000, v6
	s_waitcnt lgkmcnt(0)
	v_add_f32_e32 v10, v10, v23
	v_add_f32_e32 v6, v11, v6
	v_cvt_pk_bf16_f32 v6, v10, v6
	v_lshlrev_b32_e32 v10, 16, v7
	v_and_b32_e32 v7, 0xffff0000, v7
	v_add_f32_e32 v10, v12, v10
	v_add_f32_e32 v7, v13, v7
	v_cvt_pk_bf16_f32 v7, v10, v7
	v_lshlrev_b32_e32 v10, 16, v8
	v_and_b32_e32 v8, 0xffff0000, v8
	v_add_f32_e32 v10, v14, v10
	v_add_f32_e32 v8, v15, v8
	v_cvt_pk_bf16_f32 v8, v10, v8
	v_lshlrev_b32_e32 v10, 16, v9
	v_and_b32_e32 v9, 0xffff0000, v9
	v_add_f32_e32 v10, v16, v10
	v_add_f32_e32 v9, v17, v9
	v_and_b32_e32 v11, 0xffff0000, v6
	v_cvt_pk_bf16_f32 v9, v10, v9
	v_lshlrev_b32_e32 v10, 16, v6
	v_mul_f32_e32 v11, v11, v11
	v_lshlrev_b32_e32 v12, 16, v7
	v_fmac_f32_e32 v11, v10, v10
	v_and_b32_e32 v13, 0xffff0000, v7
	v_fmac_f32_e32 v11, v12, v12
	v_lshlrev_b32_e32 v14, 16, v8
	v_fmac_f32_e32 v11, v13, v13
	v_and_b32_e32 v15, 0xffff0000, v8
	v_fmac_f32_e32 v11, v14, v14
	v_lshlrev_b32_e32 v16, 16, v9
	v_fmac_f32_e32 v11, v15, v15
	v_and_b32_e32 v17, 0xffff0000, v9
	v_fmac_f32_e32 v11, v16, v16
	v_fmac_f32_e32 v11, v17, v17
	flat_store_dwordx4 v[20:21], v[6:9] offset:224
	v_add_f32_e32 v14, v22, v11
	ds_read_b128 v[6:9], v1 offset:224
	ds_read_b128 v[10:13], v1 offset:240
	v_lshlrev_b32_e32 v1, 16, v2
	v_and_b32_e32 v2, 0xffff0000, v2
	s_waitcnt lgkmcnt(0)
	v_add_f32_e32 v1, v6, v1
	v_add_f32_e32 v2, v7, v2
	v_cvt_pk_bf16_f32 v2, v1, v2
	v_lshlrev_b32_e32 v1, 16, v3
	v_and_b32_e32 v3, 0xffff0000, v3
	v_add_f32_e32 v1, v8, v1
	v_add_f32_e32 v3, v9, v3
	v_cvt_pk_bf16_f32 v3, v1, v3
	v_lshlrev_b32_e32 v1, 16, v4
	v_and_b32_e32 v4, 0xffff0000, v4
	v_add_f32_e32 v1, v10, v1
	v_add_f32_e32 v4, v11, v4
	v_cvt_pk_bf16_f32 v4, v1, v4
	v_lshlrev_b32_e32 v1, 16, v5
	v_and_b32_e32 v5, 0xffff0000, v5
	v_add_f32_e32 v1, v12, v1
	v_add_f32_e32 v5, v13, v5
	v_and_b32_e32 v6, 0xffff0000, v2
	v_cvt_pk_bf16_f32 v5, v1, v5
	v_lshlrev_b32_e32 v1, 16, v2
	v_mul_f32_e32 v6, v6, v6
	v_lshlrev_b32_e32 v7, 16, v3
	v_fmac_f32_e32 v6, v1, v1
	v_and_b32_e32 v8, 0xffff0000, v3
	v_fmac_f32_e32 v6, v7, v7
	v_lshlrev_b32_e32 v9, 16, v4
	v_fmac_f32_e32 v6, v8, v8
	v_and_b32_e32 v10, 0xffff0000, v4
	v_fmac_f32_e32 v6, v9, v9
	v_lshlrev_b32_e32 v11, 16, v5
	v_fmac_f32_e32 v6, v10, v10
	v_and_b32_e32 v12, 0xffff0000, v5
	v_fmac_f32_e32 v6, v11, v11
	flat_store_dwordx4 v[20:21], v[2:5] offset:240
	v_fmac_f32_e32 v6, v12, v12
	v_add_f32_e32 v1, v14, v6
	v_lshlrev_b64 v[2:3], 6, v[18:19]
	v_lshl_add_u64 v[2:3], s[6:7], 0, v[2:3]
	v_lshl_add_u64 v[2:3], v[2:3], 0, s[16:17]
	flat_store_dword v[2:3], v1 offset:4
	s_branch .LBB0_522

.Lbk64_557:
	s_waitcnt vmcnt(4)
	ds_read_b128 v[192:195], v243
	ds_read_b128 v[196:199], v244
	ds_read_b128 v[200:203], v243 offset:2048
	ds_read_b128 v[204:207], v244 offset:2048
	ds_read_b128 v[208:211], v243 offset:4096
	ds_read_b128 v[212:215], v244 offset:4096
	ds_read_b128 v[216:219], v243 offset:6144
	ds_read_b128 v[220:223], v244 offset:6144
	s_waitcnt vmcnt(0)
	s_barrier
	s_add_u32 s4, s4, 0x80
	s_addc_u32 s5, s5, 0
	s_add_u32 s6, s6, 0x80
	s_addc_u32 s7, s7, 0
	s_waitcnt lgkmcnt(0)
	ds_read_b128 v[224:227], v245 offset:0
	ds_read_b128 v[228:231], v246 offset:0
	ds_read_b128 v[232:235], v245 offset:2048
	ds_read_b128 v[236:239], v246 offset:2048
	s_waitcnt lgkmcnt(2)
	v_mfma_f32_16x16x32_bf16 v[142:145], v[192:195], v[224:227], v[142:145]
	v_mfma_f32_16x16x32_bf16 v[130:133], v[200:203], v[224:227], v[130:133]
	v_mfma_f32_16x16x32_bf16 v[110:113], v[208:211], v[224:227], v[110:113]
	v_mfma_f32_16x16x32_bf16 v[78:81], v[216:219], v[224:227], v[78:81]
	v_readfirstlane_b32 s32, v153
	s_lshl_b32 m0, s32, 3
	v_mov_b32_e32 v242, v240
	global_load_lds_dwordx4 v242, s[4:5]
	v_mfma_f32_16x16x32_bf16 v[142:145], v[196:199], v[228:231], v[142:145]
	v_mfma_f32_16x16x32_bf16 v[130:133], v[204:207], v[228:231], v[130:133]
	v_mfma_f32_16x16x32_bf16 v[110:113], v[212:215], v[228:231], v[110:113]
	v_mfma_f32_16x16x32_bf16 v[78:81], v[220:223], v[228:231], v[78:81]
	s_add_u32 m0, m0, 0x400
	v_add_u32_e32 v242, 0x4000, v240
	global_load_lds_dwordx4 v242, s[4:5]
	ds_read_b128 v[224:227], v245 offset:4096
	ds_read_b128 v[228:231], v246 offset:4096
	s_waitcnt lgkmcnt(2)
	v_mfma_f32_16x16x32_bf16 v[138:141], v[192:195], v[232:235], v[138:141]
	v_mfma_f32_16x16x32_bf16 v[122:125], v[200:203], v[232:235], v[122:125]
	v_mfma_f32_16x16x32_bf16 v[94:97], v[208:211], v[232:235], v[94:97]
	v_mfma_f32_16x16x32_bf16 v[62:65], v[216:219], v[232:235], v[62:65]
	s_add_u32 m0, m0, 0x400
	v_add_u32_e32 v242, 0x8000, v240
	global_load_lds_dwordx4 v242, s[4:5]
	v_mfma_f32_16x16x32_bf16 v[138:141], v[196:199], v[236:239], v[138:141]
	v_mfma_f32_16x16x32_bf16 v[122:125], v[204:207], v[236:239], v[122:125]
	v_mfma_f32_16x16x32_bf16 v[94:97], v[212:215], v[236:239], v[94:97]
	v_mfma_f32_16x16x32_bf16 v[62:65], v[220:223], v[236:239], v[62:65]
	s_add_u32 m0, m0, 0x400
	v_add_u32_e32 v242, 0xc000, v240
	global_load_lds_dwordx4 v242, s[4:5]
	ds_read_b128 v[232:235], v245 offset:6144
	ds_read_b128 v[236:239], v246 offset:6144
	s_waitcnt lgkmcnt(2)
	v_mfma_f32_16x16x32_bf16 v[134:137], v[192:195], v[224:227], v[134:137]
	v_mfma_f32_16x16x32_bf16 v[114:117], v[200:203], v[224:227], v[114:117]
	v_mfma_f32_16x16x32_bf16 v[86:89], v[208:211], v[224:227], v[86:89]
	v_mfma_f32_16x16x32_bf16 v[54:57], v[216:219], v[224:227], v[54:57]
	s_add_u32 m0, m0, 0x400
	v_add_u32_e32 v242, 0x10000, v240
	global_load_lds_dwordx4 v242, s[4:5]
	v_mfma_f32_16x16x32_bf16 v[134:137], v[196:199], v[228:231], v[134:137]
	v_mfma_f32_16x16x32_bf16 v[114:117], v[204:207], v[228:231], v[114:117]
	v_mfma_f32_16x16x32_bf16 v[86:89], v[212:215], v[228:231], v[86:89]
	v_mfma_f32_16x16x32_bf16 v[54:57], v[220:223], v[228:231], v[54:57]
	s_add_u32 m0, m0, 0x400
	v_add_u32_e32 v242, 0x14000, v240
	global_load_lds_dwordx4 v242, s[4:5]
	ds_read_b128 v[224:227], v245 offset:8192
	ds_read_b128 v[228:231], v246 offset:8192
	s_waitcnt lgkmcnt(2)
	v_mfma_f32_16x16x32_bf16 v[126:129], v[192:195], v[232:235], v[126:129]
	v_mfma_f32_16x16x32_bf16 v[102:105], v[200:203], v[232:235], v[102:105]
	v_mfma_f32_16x16x32_bf16 v[70:73], v[208:211], v[232:235], v[70:73]
	v_mfma_f32_16x16x32_bf16 v[42:45], v[216:219], v[232:235], v[42:45]
	s_add_u32 m0, m0, 0x400
	v_add_u32_e32 v242, 0x18000, v240
	global_load_lds_dwordx4 v242, s[4:5]
	v_mfma_f32_16x16x32_bf16 v[126:129], v[196:199], v[236:239], v[126:129]
	v_mfma_f32_16x16x32_bf16 v[102:105], v[204:207], v[236:239], v[102:105]
	v_mfma_f32_16x16x32_bf16 v[70:73], v[212:215], v[236:239], v[70:73]
	v_mfma_f32_16x16x32_bf16 v[42:45], v[220:223], v[236:239], v[42:45]
	s_add_u32 m0, m0, 0x400
	v_add_u32_e32 v242, 0x1c000, v240
	global_load_lds_dwordx4 v242, s[4:5]
	ds_read_b128 v[232:235], v245 offset:10240
	ds_read_b128 v[236:239], v246 offset:10240
	s_waitcnt lgkmcnt(2)
	v_mfma_f32_16x16x32_bf16 v[118:121], v[192:195], v[224:227], v[118:121]
	v_mfma_f32_16x16x32_bf16 v[90:93], v[200:203], v[224:227], v[90:93]
	v_mfma_f32_16x16x32_bf16 v[58:61], v[208:211], v[224:227], v[58:61]
	v_mfma_f32_16x16x32_bf16 v[34:37], v[216:219], v[224:227], v[34:37]
	s_add_u32 m0, s31, 17
	s_and_b32 m0, m0, 1
	s_lshl_b32 m0, m0, 14
	s_add_u32 m0, m0, 0x8000
	v_readfirstlane_b32 s32, v153
	s_lshl_b32 s32, s32, 2
	s_add_u32 m0, m0, s32
	v_mov_b32_e32 v242, v241
	global_load_lds_dwordx4 v242, s[6:7]
	v_mfma_f32_16x16x32_bf16 v[118:121], v[196:199], v[228:231], v[118:121]
	v_mfma_f32_16x16x32_bf16 v[90:93], v[204:207], v[228:231], v[90:93]
	v_mfma_f32_16x16x32_bf16 v[58:61], v[212:215], v[228:231], v[58:61]
	v_mfma_f32_16x16x32_bf16 v[34:37], v[220:223], v[228:231], v[34:37]
	s_add_u32 m0, m0, 0x400
	v_add_u32_e32 v242, 0x4000, v241
	global_load_lds_dwordx4 v242, s[6:7]
	ds_read_b128 v[224:227], v245 offset:12288
	ds_read_b128 v[228:231], v246 offset:12288
	s_waitcnt lgkmcnt(2)
	v_mfma_f32_16x16x32_bf16 v[106:109], v[192:195], v[232:235], v[106:109]
	v_mfma_f32_16x16x32_bf16 v[74:77], v[200:203], v[232:235], v[74:77]
	v_mfma_f32_16x16x32_bf16 v[46:49], v[208:211], v[232:235], v[46:49]
	v_mfma_f32_16x16x32_bf16 v[26:29], v[216:219], v[232:235], v[26:29]
	s_add_u32 m0, m0, 0x400
	v_add_u32_e32 v242, 0x8000, v241
	global_load_lds_dwordx4 v242, s[6:7]
	v_mfma_f32_16x16x32_bf16 v[106:109], v[196:199], v[236:239], v[106:109]
	v_mfma_f32_16x16x32_bf16 v[74:77], v[204:207], v[236:239], v[74:77]
	v_mfma_f32_16x16x32_bf16 v[46:49], v[212:215], v[236:239], v[46:49]
	v_mfma_f32_16x16x32_bf16 v[26:29], v[220:223], v[236:239], v[26:29]
	s_add_u32 m0, m0, 0x400
	v_add_u32_e32 v242, 0xc000, v241
	global_load_lds_dwordx4 v242, s[6:7]
	ds_read_b128 v[232:235], v245 offset:14336
	ds_read_b128 v[236:239], v246 offset:14336
	s_waitcnt lgkmcnt(2)
	v_mfma_f32_16x16x32_bf16 v[98:101], v[192:195], v[224:227], v[98:101]
	v_mfma_f32_16x16x32_bf16 v[66:69], v[200:203], v[224:227], v[66:69]
	v_mfma_f32_16x16x32_bf16 v[38:41], v[208:211], v[224:227], v[38:41]
	v_mfma_f32_16x16x32_bf16 v[22:25], v[216:219], v[224:227], v[22:25]
	v_mfma_f32_16x16x32_bf16 v[98:101], v[196:199], v[228:231], v[98:101]
	v_mfma_f32_16x16x32_bf16 v[66:69], v[204:207], v[228:231], v[66:69]
	v_mfma_f32_16x16x32_bf16 v[38:41], v[212:215], v[228:231], v[38:41]
	v_mfma_f32_16x16x32_bf16 v[22:25], v[220:223], v[228:231], v[22:25]
	s_waitcnt lgkmcnt(0)
	v_mfma_f32_16x16x32_bf16 v[82:85], v[192:195], v[232:235], v[82:85]
	v_mfma_f32_16x16x32_bf16 v[50:53], v[200:203], v[232:235], v[50:53]
	v_mfma_f32_16x16x32_bf16 v[30:33], v[208:211], v[232:235], v[30:33]
	v_mfma_f32_16x16x32_bf16 v[18:21], v[216:219], v[232:235], v[18:21]
	v_mfma_f32_16x16x32_bf16 v[82:85], v[196:199], v[236:239], v[82:85]
	v_mfma_f32_16x16x32_bf16 v[50:53], v[204:207], v[236:239], v[50:53]
	v_mfma_f32_16x16x32_bf16 v[30:33], v[212:215], v[236:239], v[30:33]
	v_mfma_f32_16x16x32_bf16 v[18:21], v[220:223], v[236:239], v[18:21]
	v_xor_b32_e32 v245, 0x4000, v245
	v_xor_b32_e32 v246, 0x4000, v246
	s_add_i32 s31, s31, 1
	s_cmp_lg_u32 s31, 15
	s_cbranch_scc1 .Lbk64_557
	s_waitcnt vmcnt(4)
	ds_read_b128 v[192:195], v243
	ds_read_b128 v[196:199], v244
	ds_read_b128 v[200:203], v243 offset:2048
	ds_read_b128 v[204:207], v244 offset:2048
	ds_read_b128 v[208:211], v243 offset:4096
	ds_read_b128 v[212:215], v244 offset:4096
	ds_read_b128 v[216:219], v243 offset:6144
	ds_read_b128 v[220:223], v244 offset:6144
	s_waitcnt vmcnt(0)
	s_barrier
	s_waitcnt lgkmcnt(0)
	ds_read_b128 v[224:227], v245 offset:0
	ds_read_b128 v[228:231], v246 offset:0
	ds_read_b128 v[232:235], v245 offset:2048
	ds_read_b128 v[236:239], v246 offset:2048
	s_waitcnt lgkmcnt(2)
	v_mfma_f32_16x16x32_bf16 v[142:145], v[192:195], v[224:227], v[142:145]
	v_mfma_f32_16x16x32_bf16 v[130:133], v[200:203], v[224:227], v[130:133]
	v_mfma_f32_16x16x32_bf16 v[110:113], v[208:211], v[224:227], v[110:113]
	v_mfma_f32_16x16x32_bf16 v[78:81], v[216:219], v[224:227], v[78:81]
	v_mfma_f32_16x16x32_bf16 v[142:145], v[196:199], v[228:231], v[142:145]
	v_mfma_f32_16x16x32_bf16 v[130:133], v[204:207], v[228:231], v[130:133]
	v_mfma_f32_16x16x32_bf16 v[110:113], v[212:215], v[228:231], v[110:113]
	v_mfma_f32_16x16x32_bf16 v[78:81], v[220:223], v[228:231], v[78:81]
	ds_read_b128 v[224:227], v245 offset:4096
	ds_read_b128 v[228:231], v246 offset:4096
	s_waitcnt lgkmcnt(2)
	v_mfma_f32_16x16x32_bf16 v[138:141], v[192:195], v[232:235], v[138:141]
	v_mfma_f32_16x16x32_bf16 v[122:125], v[200:203], v[232:235], v[122:125]
	v_mfma_f32_16x16x32_bf16 v[94:97], v[208:211], v[232:235], v[94:97]
	v_mfma_f32_16x16x32_bf16 v[62:65], v[216:219], v[232:235], v[62:65]
	v_mfma_f32_16x16x32_bf16 v[138:141], v[196:199], v[236:239], v[138:141]
	v_mfma_f32_16x16x32_bf16 v[122:125], v[204:207], v[236:239], v[122:125]
	v_mfma_f32_16x16x32_bf16 v[94:97], v[212:215], v[236:239], v[94:97]
	v_mfma_f32_16x16x32_bf16 v[62:65], v[220:223], v[236:239], v[62:65]
	ds_read_b128 v[232:235], v245 offset:6144
	ds_read_b128 v[236:239], v246 offset:6144
	s_waitcnt lgkmcnt(2)
	v_mfma_f32_16x16x32_bf16 v[134:137], v[192:195], v[224:227], v[134:137]
	v_mfma_f32_16x16x32_bf16 v[114:117], v[200:203], v[224:227], v[114:117]
	v_mfma_f32_16x16x32_bf16 v[86:89], v[208:211], v[224:227], v[86:89]
	v_mfma_f32_16x16x32_bf16 v[54:57], v[216:219], v[224:227], v[54:57]
	v_mfma_f32_16x16x32_bf16 v[134:137], v[196:199], v[228:231], v[134:137]
	v_mfma_f32_16x16x32_bf16 v[114:117], v[204:207], v[228:231], v[114:117]
	v_mfma_f32_16x16x32_bf16 v[86:89], v[212:215], v[228:231], v[86:89]
	v_mfma_f32_16x16x32_bf16 v[54:57], v[220:223], v[228:231], v[54:57]
	ds_read_b128 v[224:227], v245 offset:8192
	ds_read_b128 v[228:231], v246 offset:8192
	s_waitcnt lgkmcnt(2)
	v_mfma_f32_16x16x32_bf16 v[126:129], v[192:195], v[232:235], v[126:129]
	v_mfma_f32_16x16x32_bf16 v[102:105], v[200:203], v[232:235], v[102:105]
	v_mfma_f32_16x16x32_bf16 v[70:73], v[208:211], v[232:235], v[70:73]
	v_mfma_f32_16x16x32_bf16 v[42:45], v[216:219], v[232:235], v[42:45]
	v_mfma_f32_16x16x32_bf16 v[126:129], v[196:199], v[236:239], v[126:129]
	v_mfma_f32_16x16x32_bf16 v[102:105], v[204:207], v[236:239], v[102:105]
	v_mfma_f32_16x16x32_bf16 v[70:73], v[212:215], v[236:239], v[70:73]
	v_mfma_f32_16x16x32_bf16 v[42:45], v[220:223], v[236:239], v[42:45]
	ds_read_b128 v[232:235], v245 offset:10240
	ds_read_b128 v[236:239], v246 offset:10240
	s_waitcnt lgkmcnt(2)
	v_mfma_f32_16x16x32_bf16 v[118:121], v[192:195], v[224:227], v[118:121]
	v_mfma_f32_16x16x32_bf16 v[90:93], v[200:203], v[224:227], v[90:93]
	v_mfma_f32_16x16x32_bf16 v[58:61], v[208:211], v[224:227], v[58:61]
	v_mfma_f32_16x16x32_bf16 v[34:37], v[216:219], v[224:227], v[34:37]
	v_mfma_f32_16x16x32_bf16 v[118:121], v[196:199], v[228:231], v[118:121]
	v_mfma_f32_16x16x32_bf16 v[90:93], v[204:207], v[228:231], v[90:93]
	v_mfma_f32_16x16x32_bf16 v[58:61], v[212:215], v[228:231], v[58:61]
	v_mfma_f32_16x16x32_bf16 v[34:37], v[220:223], v[228:231], v[34:37]
	ds_read_b128 v[224:227], v245 offset:12288
	ds_read_b128 v[228:231], v246 offset:12288
	s_waitcnt lgkmcnt(2)
	v_mfma_f32_16x16x32_bf16 v[106:109], v[192:195], v[232:235], v[106:109]
	v_mfma_f32_16x16x32_bf16 v[74:77], v[200:203], v[232:235], v[74:77]
	v_mfma_f32_16x16x32_bf16 v[46:49], v[208:211], v[232:235], v[46:49]
	v_mfma_f32_16x16x32_bf16 v[26:29], v[216:219], v[232:235], v[26:29]
	v_mfma_f32_16x16x32_bf16 v[106:109], v[196:199], v[236:239], v[106:109]
	v_mfma_f32_16x16x32_bf16 v[74:77], v[204:207], v[236:239], v[74:77]
	v_mfma_f32_16x16x32_bf16 v[46:49], v[212:215], v[236:239], v[46:49]
	v_mfma_f32_16x16x32_bf16 v[26:29], v[220:223], v[236:239], v[26:29]
	ds_read_b128 v[232:235], v245 offset:14336
	ds_read_b128 v[236:239], v246 offset:14336
	s_waitcnt lgkmcnt(2)
	v_mfma_f32_16x16x32_bf16 v[98:101], v[192:195], v[224:227], v[98:101]
	v_mfma_f32_16x16x32_bf16 v[66:69], v[200:203], v[224:227], v[66:69]
	v_mfma_f32_16x16x32_bf16 v[38:41], v[208:211], v[224:227], v[38:41]
	v_mfma_f32_16x16x32_bf16 v[22:25], v[216:219], v[224:227], v[22:25]
	v_mfma_f32_16x16x32_bf16 v[98:101], v[196:199], v[228:231], v[98:101]
	v_mfma_f32_16x16x32_bf16 v[66:69], v[204:207], v[228:231], v[66:69]
	v_mfma_f32_16x16x32_bf16 v[38:41], v[212:215], v[228:231], v[38:41]
	v_mfma_f32_16x16x32_bf16 v[22:25], v[220:223], v[228:231], v[22:25]
	s_waitcnt lgkmcnt(0)
	v_mfma_f32_16x16x32_bf16 v[82:85], v[192:195], v[232:235], v[82:85]
	v_mfma_f32_16x16x32_bf16 v[50:53], v[200:203], v[232:235], v[50:53]
	v_mfma_f32_16x16x32_bf16 v[30:33], v[208:211], v[232:235], v[30:33]
	v_mfma_f32_16x16x32_bf16 v[18:21], v[216:219], v[232:235], v[18:21]
	v_mfma_f32_16x16x32_bf16 v[82:85], v[196:199], v[236:239], v[82:85]
	v_mfma_f32_16x16x32_bf16 v[50:53], v[204:207], v[236:239], v[50:53]
	v_mfma_f32_16x16x32_bf16 v[30:33], v[212:215], v[236:239], v[30:33]
	v_mfma_f32_16x16x32_bf16 v[18:21], v[220:223], v[236:239], v[18:21]
	s_nop 7
	s_nop 7
	s_waitcnt vmcnt(6)
	v_add_u32_e32 v153, v157, v155
	s_waitcnt lgkmcnt(0)
	v_and_b32_e32 v1, 0xfffffc0, v1
	v_lshl_or_b32 v1, v149, 2, v1
	v_mul_lo_u32 v1, v1, s33
	v_lshl_or_b32 v1, v147, 2, v1
	s_lshl_b32 s31, s30, 1
	s_mov_b64 s[4:5], -1
	s_cmp_lg_u32 s30, 20
	s_waitcnt lgkmcnt(0)
	s_waitcnt lgkmcnt(0)
	s_waitcnt lgkmcnt(0)
	s_waitcnt lgkmcnt(0)
	s_waitcnt lgkmcnt(0)
	v_mov_b64_e32 v[162:163], v[26:27]
	v_mov_b64_e32 v[164:165], v[28:29]
	s_nop 2
	s_waitcnt lgkmcnt(0)
	v_mov_b64_e32 v[204:205], v[22:23]
	v_mov_b64_e32 v[206:207], v[24:25]
	s_nop 2
	s_waitcnt vmcnt(0)
	v_mov_b64_e32 v[200:201], v[66:67]
	v_mov_b64_e32 v[202:203], v[68:69]
	s_waitcnt vmcnt(0)
	s_nop 0
	v_mov_b32_e32 v66, v15
	v_mov_b32_e32 v67, v16
	v_mov_b32_e32 v68, v11
	s_waitcnt lgkmcnt(0)
	v_mov_b32_e32 v69, v12
	v_mov_b32_e32 v15, v17
	v_mov_b32_e32 v11, v13
	v_pk_add_f32 v[14:15], v[66:67], v[14:15]
	v_pk_add_f32 v[10:11], v[68:69], v[10:11]
	v_mov_b64_e32 v[158:159], v[30:31]
	v_mov_b64_e32 v[160:161], v[32:33]
	v_pk_add_f32 v[14:15], v[14:15], v[14:15] op_sel:[0,1] op_sel_hi:[1,0]
	v_pk_add_f32 v[16:17], v[10:11], v[10:11] op_sel:[0,1] op_sel_hi:[1,0]
	v_mov_b32_e32 v15, v2
	v_mov_b64_e32 v[192:193], v[18:19]
	v_mov_b64_e32 v[194:195], v[20:21]
	s_nop 1
	v_mov_b32_e32 v17, v3
	s_waitcnt lgkmcnt(3)
	v_mov_b64_e32 v[22:23], v[142:143]
	v_mov_b64_e32 v[24:25], v[144:145]
	v_add_f32_e64 v14, v14, v16
	v_add_f32_e64 v15, v15, v17
	s_nop 0
	s_waitcnt lgkmcnt(3)
	v_mov_b64_e32 v[30:31], v[130:131]
	v_mov_b64_e32 v[32:33], v[132:133]
	s_waitcnt lgkmcnt(0)
	v_mov_b32_e32 v26, v7
	v_pk_add_f32 v[66:67], v[6:7], v[26:27]
	v_mov_b32_e32 v6, v9
	v_pk_add_f32 v[68:69], v[8:9], v[6:7]
	v_mov_b32_e32 v67, v4
	v_mov_b32_e32 v69, v5
	v_pk_add_f32 v[16:17], v[66:67], v[68:69]
	v_pk_add_f32 v[14:15], v[14:15], v[16:17]
	v_mov_b64_e32 v[26:27], v[122:123]
	v_mov_b64_e32 v[28:29], v[124:125]
	v_add_f32_e32 v14, v14, v15
	v_fmamk_f32 v14, v14, 0x3a800000, v172
	v_mul_f32_e32 v15, 0x4b800000, v14
	v_cmp_gt_f32_e32 vcc, s58, v14
	v_mov_b64_e32 v[122:123], v[94:95]
	v_mov_b64_e32 v[124:125], v[96:97]
	s_nop 2
	v_cndmask_b32_e32 v14, v14, v15, vcc
	v_rsq_f32_e32 v14, v14
	v_mov_b64_e32 v[10:11], v[138:139]
	v_mov_b64_e32 v[12:13], v[140:141]
	v_add_u32_e32 v67, 0x1000, v1
	v_mul_f32_e32 v15, 0x45800000, v14
	v_cndmask_b32_e32 v66, v14, v15, vcc
	s_waitcnt lgkmcnt(3)
	v_mov_b64_e32 v[18:19], v[134:135]
	v_mov_b64_e32 v[20:21], v[136:137]
	s_waitcnt lgkmcnt(2)
	v_mov_b64_e32 v[6:7], v[126:127]
	v_mov_b64_e32 v[8:9], v[128:129]
	s_nop 2
	s_waitcnt lgkmcnt(0)
	s_barrier
	ds_write2_b32 v1, v22, v10 offset1:16
	ds_write2_b32 v1, v23, v11 offset0:68 offset1:84
	ds_write2_b32 v1, v24, v12 offset0:136 offset1:152
	ds_write2_b32 v1, v25, v13 offset0:204 offset1:220
	ds_write2_b32 v1, v18, v6 offset0:32 offset1:48
	ds_write2_b32 v1, v19, v7 offset0:100 offset1:116
	v_mov_b32_e32 v68, v70
	v_mov_b32_e32 v69, v71
	v_mov_b32_e32 v70, v72
	v_mov_b32_e32 v71, v73
	ds_write2_b32 v1, v20, v8 offset0:168 offset1:184
	ds_write2_b32 v1, v21, v9 offset0:236 offset1:252
	ds_write2_b32 v67, v30, v26 offset0:64 offset1:80
	ds_write2_b32 v67, v31, v27 offset0:132 offset1:148
	ds_write2_b32 v67, v32, v28 offset0:200 offset1:216
	v_mov_b64_e32 v[138:139], v[42:43]
	v_mov_b64_e32 v[140:141], v[44:45]
	v_mov_b64_e32 v[14:15], v[118:119]
	v_mov_b64_e32 v[16:17], v[120:121]
	v_mov_b64_e32 v[10:11], v[90:91]
	v_mov_b64_e32 v[12:13], v[92:93]
	v_mov_b64_e32 v[6:7], v[58:59]
	v_mov_b64_e32 v[8:9], v[60:61]
	v_mov_b64_e32 v[2:3], v[34:35]
	v_mov_b64_e32 v[4:5], v[36:37]
	v_add_u32_e32 v94, 0x1400, v1
	v_add_u32_e32 v95, 0x2000, v1
	v_add_u32_e32 v96, 0x2400, v1
	v_mov_b64_e32 v[22:23], v[46:47]
	v_mov_b64_e32 v[24:25], v[48:49]
	v_add_u32_e32 v97, 0x3000, v1
	ds_write2_b32 v94, v33, v29 offset0:12 offset1:28
	ds_write2_b32 v67, v114, v102 offset0:96 offset1:112
	ds_write2_b32 v67, v115, v103 offset0:164 offset1:180
	ds_write2_b32 v67, v116, v104 offset0:232 offset1:248
	ds_write2_b32 v94, v117, v105 offset0:44 offset1:60
	v_mov_b64_e32 v[46:47], v[98:99]
	v_mov_b64_e32 v[48:49], v[100:101]
	ds_write2_b32 v95, v110, v122 offset0:128 offset1:144
	ds_write2_b32 v95, v111, v123 offset0:196 offset1:212
	ds_write2_b32 v96, v112, v124 offset0:8 offset1:24
	ds_write2_b32 v96, v113, v125 offset0:76 offset1:92
	v_add_u32_e32 v98, 0x3400, v1
	v_mov_b64_e32 v[30:31], v[106:107]
	v_mov_b64_e32 v[32:33], v[108:109]
	ds_write2_b32 v95, v86, v68 offset0:160 offset1:176
	ds_write2_b32 v95, v87, v69 offset0:228 offset1:244
	ds_write2_b32 v96, v88, v70 offset0:40 offset1:56
	ds_write2_b32 v96, v89, v71 offset0:108 offset1:124
	ds_write2_b32 v97, v78, v62 offset0:192 offset1:208
	v_mov_b64_e32 v[26:27], v[74:75]
	v_mov_b64_e32 v[28:29], v[76:77]
	ds_write2_b32 v98, v79, v63 offset0:4 offset1:20
	ds_write2_b32 v98, v80, v64 offset0:72 offset1:88
	ds_write2_b32 v98, v81, v65 offset0:140 offset1:156
	ds_write2_b32 v97, v54, v138 offset0:224 offset1:240
	ds_write2_b32 v98, v55, v139 offset0:36 offset1:52
	ds_write2_b32 v98, v56, v140 offset0:104 offset1:120
	ds_write2_b32 v98, v57, v141 offset0:172 offset1:188
	v_mov_b64_e32 v[18:19], v[162:163]
	v_mov_b64_e32 v[20:21], v[164:165]
	v_mov_b32_e32 v100, v170
	s_waitcnt lgkmcnt(0)
	s_barrier
	v_mov_b64_e32 v[42:43], v[200:201]
	v_mov_b64_e32 v[44:45], v[202:203]
	v_add_u32_e32 v68, s71, v100
	v_ashrrev_i32_e32 v69, 31, v68
	v_mul_lo_u32 v99, v100, s33
	v_mov_b64_e32 v[34:35], v[204:205]
	v_mov_b64_e32 v[36:37], v[206:207]
	v_mov_b64_e32 v[62:63], v[82:83]
	v_mov_b64_e32 v[64:65], v[84:85]
	v_mov_b64_e32 v[58:59], v[50:51]
	v_mov_b64_e32 v[60:61], v[52:53]
	v_mov_b64_e32 v[54:55], v[158:159]
	v_mov_b64_e32 v[56:57], v[160:161]
	v_mov_b64_e32 v[50:51], v[192:193]
	v_mov_b64_e32 v[52:53], v[194:195]
	s_cbranch_scc0 .LBB0_570
	v_cmp_gt_i32_e32 vcc, s78, v68
	s_nop 1
	v_cndmask_b32_e32 v70, v179, v173, vcc
	v_and_b32_e32 v101, v70, v68
	v_mov_b64_e32 v[70:71], s[38:39]
	v_mad_i64_i32 v[70:71], s[4:5], v68, s59, v[70:71]
	s_lshl_b32 s4, s30, 7
	s_ashr_i32 s5, s4, 31
	v_lshl_add_u64 v[70:71], s[4:5], 1, v[70:71]
	s_sub_i32 s4, s31, 28
	s_cmp_gt_u32 s4, 9
	s_mov_b64 s[4:5], -1
	s_cbranch_scc0 .LBB0_566
	s_cmp_lt_i32 s30, 2
	v_mul_f32_e32 v72, 0x3e38aa3b, v66
	s_cselect_b64 vcc, -1, 0
	s_cmp_lt_i32 s30, 4
	v_cndmask_b32_e32 v72, v66, v72, vcc
	s_cselect_b64 s[6:7], -1, 0
	v_lshlrev_b32_e32 v74, 6, v101
	v_mov_b32_e32 v75, v0
	v_lshl_add_u64 v[74:75], s[16:17], 0, v[74:75]
	v_mov_b32_e32 v73, v72
	s_mov_b32 s4, 0
	s_xor_b64 s[6:7], s[6:7], -1
	v_mov_b64_e32 v[76:77], v[70:71]
	s_branch .LBB0_562
